# plus: removed redundant s_setprio 0/1 pairs and duplicate post-barrier lgkmcnt(0) in the 8 SP2 GEMM loops
# speedup vs baseline: 1.0011x; 1.0011x over previous
; #define PG8_STAGE(bufoff, gbase, voff) do { _Pragma("unroll") for (int _i = 0; _i < 2; ++_i) \
;         __builtin_amdgcn_global_load_lds((const unsigned*)((const char*)(gbase) + (voff)[_i]), (LAS unsigned*)(lds + (bufoff) + ldsw + _i * 8192), 16, 0, 0); } while (0)
; #define PG8_LDA(dst, b, h) do { _Pragma("unroll") for (int m = 0; m < 4; ++m) _Pragma("unroll") for (int k = 0; k < 2; ++k) dst[m][k] = *(const LAS bf16x8*)(lds + PG8_SA(b, h) + aoff + m * 2048 + k * 1024); } while (0)
; #define PG8_LDB(dst, b, h) do { _Pragma("unroll") for (int n = 0; n < 2; ++n) _Pragma("unroll") for (int k = 0; k < 2; ++k) dst[n][k] = *(const LAS bf16x8*)(lds + PG8_SB(b, h) + boff + n * 2048 + k * 1024); } while (0)
; #define PG8_WAIT_V(n) asm volatile("s_waitcnt vmcnt(" #n ")" ::: "memory")
; #define PG8_WAIT_L(n) asm volatile("s_waitcnt lgkmcnt(" #n ")" ::: "memory")
; #define PG8_BAR __builtin_amdgcn_s_barrier()
; #define PG8_SCHED __builtin_amdgcn_sched_barrier(0)
;     ...
;         for (int t = 0; t < nt; t += 2) {
;             const bool last = (t == nt - 2);
;             const char* a1 = cA + (size_t)(t + 1) * kstep;
;             const char* a2 = last ? nA : cA + (size_t)(t + 2) * kstep; const char* b2 = last ? nB : cB + (size_t)(t + 2) * kstep;
;             const char* a3 = a2 + kstep; const char* b3 = b2 + kstep;
;             if constexpr (SP2) {
;             PG8_LDB(B0, 0, 0); PG8_LDB(B1, 0, 1); PG8_SCHED; PG8_LDA(At, 0, 0); PG8_STAGE(PG8_SA(1, 1), a1 + hstepA, voffA);
;             PG8_WAIT_V(8); PG8_WAIT_L(0); PG8_BAR; PG8_MMA(0, 0, At, B0); PG8_MMA(0, 1, At, B1); PG8_BAR; PG8_SCHED;
;             PG8_LDA(At, 0, 1); PG8_STAGE(PG8_SB(0, 0), b2, voffB); PG8_STAGE(PG8_SB(0, 1), b2 + hstepB, voffB); PG8_STAGE(PG8_SA(0, 0), a2, voffA);
;             PG8_WAIT_V(8); PG8_WAIT_L(0); PG8_BAR; PG8_MMA(1, 0, At, B0); PG8_MMA(1, 1, At, B1); PG8_BAR; PG8_SCHED;
.LBB0_165:
	s_add_i32 s62, 0, 0x10000
	v_lshl_add_u64 v[162:163], v[148:149], 0, s[38:39]
	s_cmpk_eq_i32 s38, 0xf00
	v_lshl_add_u64 v[162:163], v[162:163], 0, s[4:5]
	s_cselect_b64 vcc, -1, 0
	v_add_u32_e32 v161, s62, v158
	s_add_i32 s63, 0, 0x14000
	v_lshl_add_u64 v[178:179], v[154:155], 0, s[38:39]
	v_cndmask_b32_e32 v231, v163, v145, vcc
	v_cndmask_b32_e32 v230, v162, v144, vcc
	ds_read_b128 v[162:165], v161
	ds_read_b128 v[166:169], v161 offset:1024
	ds_read_b128 v[170:173], v161 offset:2048
	ds_read_b128 v[174:177], v161 offset:3072
	v_add_u32_e32 v161, s63, v158
	v_cndmask_b32_e32 v233, v179, v147, vcc
	v_cndmask_b32_e32 v232, v178, v146, vcc
	ds_read_b128 v[178:181], v161
	ds_read_b128 v[182:185], v161 offset:1024
	ds_read_b128 v[186:189], v161 offset:2048
	ds_read_b128 v[190:193], v161 offset:3072
	v_lshl_add_u64 v[234:235], v[152:153], 0, s[38:39]
	s_add_i32 m0, s3, 0xc000
	ds_read_b128 v[194:197], v160
	ds_read_b128 v[198:201], v160 offset:1024
	ds_read_b128 v[202:205], v160 offset:2048
	ds_read_b128 v[206:209], v160 offset:3072
	ds_read_b128 v[210:213], v160 offset:4096
	ds_read_b128 v[214:217], v160 offset:5120
	ds_read_b128 v[218:221], v160 offset:6144
	ds_read_b128 v[226:229], v160 offset:7168
	global_load_lds_dwordx4 v[234:235], off
	v_lshl_add_u64 v[234:235], v[150:151], 0, s[38:39]
	s_add_i32 m0, s3, 0xe000
	s_nop 0
	global_load_lds_dwordx4 v[234:235], off
	s_waitcnt vmcnt(8)
	s_waitcnt lgkmcnt(0)
	s_barrier
	s_setprio 1
	v_mfma_i32_16x16x64_i8 v[128:131], v[162:165], v[194:197], v[128:131]
	v_mfma_i32_16x16x64_i8 v[124:127], v[170:173], v[194:197], v[124:127]
	v_mfma_i32_16x16x64_i8 v[112:115], v[162:165], v[202:205], v[112:115]
	v_mfma_i32_16x16x64_i8 v[108:111], v[170:173], v[202:205], v[108:111]
	v_mfma_i32_16x16x64_i8 v[96:99], v[162:165], v[210:213], v[96:99]
	v_mfma_i32_16x16x64_i8 v[92:95], v[170:173], v[210:213], v[92:95]
	v_mfma_i32_16x16x64_i8 v[80:83], v[162:165], v[218:221], v[80:83]
	v_mfma_i32_16x16x64_i8 v[76:79], v[170:173], v[218:221], v[76:79]
	v_mfma_i32_16x16x64_i8 v[128:131], v[166:169], v[198:201], v[128:131]
	v_mfma_i32_16x16x64_i8 v[124:127], v[174:177], v[198:201], v[124:127]
	v_mfma_i32_16x16x64_i8 v[112:115], v[166:169], v[206:209], v[112:115]
	v_mfma_i32_16x16x64_i8 v[108:111], v[174:177], v[206:209], v[108:111]
	v_mfma_i32_16x16x64_i8 v[96:99], v[166:169], v[214:217], v[96:99]
	v_mfma_i32_16x16x64_i8 v[92:95], v[174:177], v[214:217], v[92:95]
	v_mfma_i32_16x16x64_i8 v[80:83], v[166:169], v[226:229], v[80:83]
	v_mfma_i32_16x16x64_i8 v[76:79], v[174:177], v[226:229], v[76:79]
	v_mfma_i32_16x16x64_i8 v[120:123], v[178:181], v[194:197], v[120:123]
	v_mfma_i32_16x16x64_i8 v[116:119], v[186:189], v[194:197], v[116:119]
	v_mfma_i32_16x16x64_i8 v[104:107], v[178:181], v[202:205], v[104:107]
	v_mfma_i32_16x16x64_i8 v[100:103], v[186:189], v[202:205], v[100:103]
	v_mfma_i32_16x16x64_i8 v[88:91], v[178:181], v[210:213], v[88:91]
	v_mfma_i32_16x16x64_i8 v[84:87], v[186:189], v[210:213], v[84:87]
	v_mfma_i32_16x16x64_i8 v[72:75], v[178:181], v[218:221], v[72:75]
	v_mfma_i32_16x16x64_i8 v[68:71], v[186:189], v[218:221], v[68:71]
	v_mfma_i32_16x16x64_i8 v[120:123], v[182:185], v[198:201], v[120:123]
	v_mfma_i32_16x16x64_i8 v[116:119], v[190:193], v[198:201], v[116:119]
	v_mfma_i32_16x16x64_i8 v[104:107], v[182:185], v[206:209], v[104:107]
	v_mfma_i32_16x16x64_i8 v[100:103], v[190:193], v[206:209], v[100:103]
	v_mfma_i32_16x16x64_i8 v[88:91], v[182:185], v[214:217], v[88:91]
	v_mfma_i32_16x16x64_i8 v[84:87], v[190:193], v[214:217], v[84:87]
	v_mfma_i32_16x16x64_i8 v[72:75], v[182:185], v[226:229], v[72:75]
	v_mfma_i32_16x16x64_i8 v[68:71], v[190:193], v[226:229], v[68:71]
	s_setprio 0
	s_barrier
	s_add_i32 s62, s62, s2
	v_lshl_add_u64 v[234:235], v[232:233], 0, v[2:3]
	s_mov_b32 m0, s62
	ds_read_b128 v[194:197], v160 offset:16384
	ds_read_b128 v[198:201], v160 offset:17408
	ds_read_b128 v[202:205], v160 offset:18432
	ds_read_b128 v[206:209], v160 offset:19456
	ds_read_b128 v[210:213], v160 offset:20480
	ds_read_b128 v[214:217], v160 offset:21504
	ds_read_b128 v[218:221], v160 offset:22528
	ds_read_b128 v[226:229], v160 offset:23552
	global_load_lds_dwordx4 v[234:235], off
	v_lshl_add_u64 v[236:237], v[232:233], 0, v[134:135]
	s_add_i32 m0, s62, 0x2000
	v_lshl_add_u64 v[232:233], v[232:233], 0, v[138:139]
	s_add_i32 s62, s63, s2
	global_load_lds_dwordx4 v[236:237], off
	v_lshl_add_u64 v[238:239], v[232:233], 0, v[2:3]
	s_mov_b32 m0, s62
	v_lshl_add_u64 v[232:233], v[232:233], 0, v[134:135]
	global_load_lds_dwordx4 v[238:239], off
	s_add_i32 m0, s62, 0x2000
	v_lshl_add_u64 v[240:241], v[230:231], 0, v[0:1]
	global_load_lds_dwordx4 v[232:233], off
	s_mov_b32 m0, s3
	v_lshl_add_u64 v[242:243], v[230:231], 0, v[132:133]
	global_load_lds_dwordx4 v[240:241], off
	s_mov_b32 m0, s8
	s_nop 0
	global_load_lds_dwordx4 v[242:243], off
	s_waitcnt vmcnt(8)
	s_waitcnt lgkmcnt(0)
	s_barrier
; #define PG8_STAGE(bufoff, gbase, voff) do { _Pragma("unroll") for (int _i = 0; _i < 2; ++_i) \
;         __builtin_amdgcn_global_load_lds((const unsigned*)((const char*)(gbase) + (voff)[_i]), (LAS unsigned*)(lds + (bufoff) + ldsw + _i * 8192), 16, 0, 0); } while (0)
; #define PG8_LDA(dst, b, h) do { _Pragma("unroll") for (int m = 0; m < 4; ++m) _Pragma("unroll") for (int k = 0; k < 2; ++k) dst[m][k] = *(const LAS bf16x8*)(lds + PG8_SA(b, h) + aoff + m * 2048 + k * 1024); } while (0)
; #define PG8_LDB(dst, b, h) do { _Pragma("unroll") for (int n = 0; n < 2; ++n) _Pragma("unroll") for (int k = 0; k < 2; ++k) dst[n][k] = *(const LAS bf16x8*)(lds + PG8_SB(b, h) + boff + n * 2048 + k * 1024); } while (0)
; #define PG8_WAIT_V(n) asm volatile("s_waitcnt vmcnt(" #n ")" ::: "memory")
; #define PG8_WAIT_L(n) asm volatile("s_waitcnt lgkmcnt(" #n ")" ::: "memory")
; #define PG8_BAR __builtin_amdgcn_s_barrier()
; #define PG8_SCHED __builtin_amdgcn_sched_barrier(0)
;     ...
;             PG8_WAIT_V(8); PG8_WAIT_L(0); PG8_BAR; PG8_MMA(1, 0, At, B0); PG8_MMA(1, 1, At, B1); PG8_BAR; PG8_SCHED;
;             PG8_LDB(B0, 1, 0); PG8_LDB(B1, 1, 1); PG8_SCHED; PG8_LDA(At, 1, 0); PG8_STAGE(PG8_SA(0, 1), a2 + hstepA, voffA);
;             PG8_WAIT_V(8); PG8_WAIT_L(0); PG8_BAR; PG8_MMA(0, 0, At, B0); PG8_MMA(0, 1, At, B1); PG8_BAR; PG8_SCHED;
	s_setprio 1
	v_mfma_i32_16x16x64_i8 v[64:67], v[162:165], v[194:197], v[64:67]
	v_mfma_i32_16x16x64_i8 v[60:63], v[170:173], v[194:197], v[60:63]
	v_mfma_i32_16x16x64_i8 v[48:51], v[162:165], v[202:205], v[48:51]
	v_mfma_i32_16x16x64_i8 v[44:47], v[170:173], v[202:205], v[44:47]
	v_mfma_i32_16x16x64_i8 v[32:35], v[162:165], v[210:213], v[32:35]
	v_mfma_i32_16x16x64_i8 v[28:31], v[170:173], v[210:213], v[28:31]
	v_mfma_i32_16x16x64_i8 v[16:19], v[162:165], v[218:221], v[16:19]
	v_mfma_i32_16x16x64_i8 v[12:15], v[170:173], v[218:221], v[12:15]
	v_mfma_i32_16x16x64_i8 v[64:67], v[166:169], v[198:201], v[64:67]
	v_mfma_i32_16x16x64_i8 v[60:63], v[174:177], v[198:201], v[60:63]
	v_mfma_i32_16x16x64_i8 v[48:51], v[166:169], v[206:209], v[48:51]
	v_mfma_i32_16x16x64_i8 v[44:47], v[174:177], v[206:209], v[44:47]
	v_mfma_i32_16x16x64_i8 v[32:35], v[166:169], v[214:217], v[32:35]
	v_mfma_i32_16x16x64_i8 v[28:31], v[174:177], v[214:217], v[28:31]
	v_mfma_i32_16x16x64_i8 v[16:19], v[166:169], v[226:229], v[16:19]
	v_mfma_i32_16x16x64_i8 v[12:15], v[174:177], v[226:229], v[12:15]
	v_mfma_i32_16x16x64_i8 v[56:59], v[178:181], v[194:197], v[56:59]
	v_mfma_i32_16x16x64_i8 v[52:55], v[186:189], v[194:197], v[52:55]
	v_mfma_i32_16x16x64_i8 v[40:43], v[178:181], v[202:205], v[40:43]
	v_mfma_i32_16x16x64_i8 v[36:39], v[186:189], v[202:205], v[36:39]
	v_mfma_i32_16x16x64_i8 v[24:27], v[178:181], v[210:213], v[24:27]
	v_mfma_i32_16x16x64_i8 v[20:23], v[186:189], v[210:213], v[20:23]
	v_mfma_i32_16x16x64_i8 v[8:11], v[178:181], v[218:221], v[8:11]
	v_mfma_i32_16x16x64_i8 v[4:7], v[186:189], v[218:221], v[4:7]
	v_mfma_i32_16x16x64_i8 v[56:59], v[182:185], v[198:201], v[56:59]
	v_mfma_i32_16x16x64_i8 v[52:55], v[190:193], v[198:201], v[52:55]
	v_mfma_i32_16x16x64_i8 v[40:43], v[182:185], v[206:209], v[40:43]
	v_mfma_i32_16x16x64_i8 v[36:39], v[190:193], v[206:209], v[36:39]
	v_mfma_i32_16x16x64_i8 v[24:27], v[182:185], v[214:217], v[24:27]
	v_mfma_i32_16x16x64_i8 v[20:23], v[190:193], v[214:217], v[20:23]
	v_mfma_i32_16x16x64_i8 v[8:11], v[182:185], v[226:229], v[8:11]
	v_mfma_i32_16x16x64_i8 v[4:7], v[190:193], v[226:229], v[4:7]
	s_setprio 0
	s_barrier
	s_add_i32 s62, 0, 0x18000
	v_add_u32_e32 v161, s62, v158
	s_add_i32 s63, 0, 0x1c000
	ds_read_b128 v[162:165], v161
	ds_read_b128 v[166:169], v161 offset:1024
	ds_read_b128 v[170:173], v161 offset:2048
	ds_read_b128 v[174:177], v161 offset:3072
	v_add_u32_e32 v161, s63, v158
	ds_read_b128 v[178:181], v161
	ds_read_b128 v[182:185], v161 offset:1024
	ds_read_b128 v[186:189], v161 offset:2048
	ds_read_b128 v[190:193], v161 offset:3072
	v_lshl_add_u64 v[230:231], v[230:231], 0, v[136:137]
	s_mov_b32 m0, s9
	v_lshl_add_u64 v[244:245], v[230:231], 0, v[0:1]
	ds_read_b128 v[194:197], v160 offset:32768
	ds_read_b128 v[198:201], v160 offset:33792
	ds_read_b128 v[202:205], v160 offset:34816
	ds_read_b128 v[206:209], v160 offset:35840
	ds_read_b128 v[210:213], v160 offset:36864
	ds_read_b128 v[214:217], v160 offset:37888
	ds_read_b128 v[218:221], v160 offset:38912
	ds_read_b128 v[226:229], v160 offset:39936
	global_load_lds_dwordx4 v[244:245], off
	v_lshl_add_u64 v[230:231], v[230:231], 0, v[132:133]
	s_mov_b32 m0, s15
	s_nop 0
	global_load_lds_dwordx4 v[230:231], off
	s_waitcnt vmcnt(8)
	s_waitcnt lgkmcnt(0)
	s_barrier
	s_setprio 1
	v_mfma_i32_16x16x64_i8 v[128:131], v[162:165], v[194:197], v[128:131]
	v_mfma_i32_16x16x64_i8 v[124:127], v[170:173], v[194:197], v[124:127]
	v_mfma_i32_16x16x64_i8 v[112:115], v[162:165], v[202:205], v[112:115]
	v_mfma_i32_16x16x64_i8 v[108:111], v[170:173], v[202:205], v[108:111]
	v_mfma_i32_16x16x64_i8 v[96:99], v[162:165], v[210:213], v[96:99]
	v_mfma_i32_16x16x64_i8 v[92:95], v[170:173], v[210:213], v[92:95]
	v_mfma_i32_16x16x64_i8 v[80:83], v[162:165], v[218:221], v[80:83]
	v_mfma_i32_16x16x64_i8 v[76:79], v[170:173], v[218:221], v[76:79]
	v_mfma_i32_16x16x64_i8 v[128:131], v[166:169], v[198:201], v[128:131]
	v_mfma_i32_16x16x64_i8 v[124:127], v[174:177], v[198:201], v[124:127]
	v_mfma_i32_16x16x64_i8 v[112:115], v[166:169], v[206:209], v[112:115]
	v_mfma_i32_16x16x64_i8 v[108:111], v[174:177], v[206:209], v[108:111]
	v_mfma_i32_16x16x64_i8 v[96:99], v[166:169], v[214:217], v[96:99]
	v_mfma_i32_16x16x64_i8 v[92:95], v[174:177], v[214:217], v[92:95]
	v_mfma_i32_16x16x64_i8 v[80:83], v[166:169], v[226:229], v[80:83]
	v_mfma_i32_16x16x64_i8 v[76:79], v[174:177], v[226:229], v[76:79]
	v_mfma_i32_16x16x64_i8 v[120:123], v[178:181], v[194:197], v[120:123]
	v_mfma_i32_16x16x64_i8 v[116:119], v[186:189], v[194:197], v[116:119]
	v_mfma_i32_16x16x64_i8 v[104:107], v[178:181], v[202:205], v[104:107]
	v_mfma_i32_16x16x64_i8 v[100:103], v[186:189], v[202:205], v[100:103]
	v_mfma_i32_16x16x64_i8 v[88:91], v[178:181], v[210:213], v[88:91]
	v_mfma_i32_16x16x64_i8 v[84:87], v[186:189], v[210:213], v[84:87]
	v_mfma_i32_16x16x64_i8 v[72:75], v[178:181], v[218:221], v[72:75]
	v_mfma_i32_16x16x64_i8 v[68:71], v[186:189], v[218:221], v[68:71]
	v_mfma_i32_16x16x64_i8 v[120:123], v[182:185], v[198:201], v[120:123]
	v_mfma_i32_16x16x64_i8 v[116:119], v[190:193], v[198:201], v[116:119]
	v_mfma_i32_16x16x64_i8 v[104:107], v[182:185], v[206:209], v[104:107]
	v_mfma_i32_16x16x64_i8 v[100:103], v[190:193], v[206:209], v[100:103]
	v_mfma_i32_16x16x64_i8 v[88:91], v[182:185], v[214:217], v[88:91]
	v_mfma_i32_16x16x64_i8 v[84:87], v[190:193], v[214:217], v[84:87]
	v_mfma_i32_16x16x64_i8 v[72:75], v[182:185], v[226:229], v[72:75]
	v_mfma_i32_16x16x64_i8 v[68:71], v[190:193], v[226:229], v[68:71]
	s_setprio 0
	s_barrier
; #define PG8_STAGE(bufoff, gbase, voff) do { _Pragma("unroll") for (int _i = 0; _i < 2; ++_i) \
;         __builtin_amdgcn_global_load_lds((const unsigned*)((const char*)(gbase) + (voff)[_i]), (LAS unsigned*)(lds + (bufoff) + ldsw + _i * 8192), 16, 0, 0); } while (0)
; #define PG8_LDA(dst, b, h) do { _Pragma("unroll") for (int m = 0; m < 4; ++m) _Pragma("unroll") for (int k = 0; k < 2; ++k) dst[m][k] = *(const LAS bf16x8*)(lds + PG8_SA(b, h) + aoff + m * 2048 + k * 1024); } while (0)
; #define PG8_WAIT_V(n) asm volatile("s_waitcnt vmcnt(" #n ")" ::: "memory")
; #define PG8_WAIT_L(n) asm volatile("s_waitcnt lgkmcnt(" #n ")" ::: "memory")
; #define PG8_BAR __builtin_amdgcn_s_barrier()
; #define PG8_SCHED __builtin_amdgcn_sched_barrier(0)
;     ...
;             PG8_LDA(At, 1, 1); PG8_STAGE(PG8_SB(1, 0), b3, voffB); PG8_STAGE(PG8_SB(1, 1), b3 + hstepB, voffB); PG8_STAGE(PG8_SA(1, 0), a3, voffA);
;             PG8_WAIT_V(8); PG8_WAIT_L(0); PG8_BAR; PG8_MMA(1, 0, At, B0); PG8_MMA(1, 1, At, B1); PG8_BAR; PG8_SCHED;
	s_add_i32 s62, s62, s2
	v_lshl_add_u64 v[230:231], v[234:235], 0, s[52:53]
	s_mov_b32 m0, s62
	ds_read_b128 v[194:197], v160 offset:49152
	ds_read_b128 v[198:201], v160 offset:50176
	ds_read_b128 v[202:205], v160 offset:51200
	ds_read_b128 v[206:209], v160 offset:52224
	ds_read_b128 v[210:213], v160 offset:53248
	ds_read_b128 v[214:217], v160 offset:54272
	ds_read_b128 v[218:221], v160 offset:55296
	ds_read_b128 v[226:229], v160 offset:56320
	global_load_lds_dwordx4 v[230:231], off
	v_lshl_add_u64 v[230:231], v[236:237], 0, s[52:53]
	s_add_i32 m0, s62, 0x2000
	s_add_i32 s62, s63, s2
	global_load_lds_dwordx4 v[230:231], off
	v_lshl_add_u64 v[230:231], v[238:239], 0, s[52:53]
	s_mov_b32 m0, s62
	s_nop 0
	global_load_lds_dwordx4 v[230:231], off
	v_lshl_add_u64 v[230:231], v[232:233], 0, s[52:53]
	s_add_i32 m0, s62, 0x2000
	s_nop 0
	global_load_lds_dwordx4 v[230:231], off
	v_lshl_add_u64 v[230:231], v[240:241], 0, s[52:53]
	s_mov_b32 m0, s47
	s_nop 0
	global_load_lds_dwordx4 v[230:231], off
	v_lshl_add_u64 v[230:231], v[242:243], 0, s[52:53]
	s_mov_b32 m0, s48
	s_nop 0
	global_load_lds_dwordx4 v[230:231], off
	s_waitcnt vmcnt(8)
	s_waitcnt lgkmcnt(0)
	s_barrier
	s_setprio 1
	v_mfma_i32_16x16x64_i8 v[64:67], v[162:165], v[194:197], v[64:67]
	v_mfma_i32_16x16x64_i8 v[60:63], v[170:173], v[194:197], v[60:63]
	v_mfma_i32_16x16x64_i8 v[48:51], v[162:165], v[202:205], v[48:51]
	v_mfma_i32_16x16x64_i8 v[44:47], v[170:173], v[202:205], v[44:47]
	v_mfma_i32_16x16x64_i8 v[32:35], v[162:165], v[210:213], v[32:35]
	v_mfma_i32_16x16x64_i8 v[28:31], v[170:173], v[210:213], v[28:31]
	v_mfma_i32_16x16x64_i8 v[16:19], v[162:165], v[218:221], v[16:19]
	v_mfma_i32_16x16x64_i8 v[12:15], v[170:173], v[218:221], v[12:15]
	v_mfma_i32_16x16x64_i8 v[64:67], v[166:169], v[198:201], v[64:67]
	v_mfma_i32_16x16x64_i8 v[60:63], v[174:177], v[198:201], v[60:63]
	v_mfma_i32_16x16x64_i8 v[48:51], v[166:169], v[206:209], v[48:51]
	v_mfma_i32_16x16x64_i8 v[44:47], v[174:177], v[206:209], v[44:47]
	v_mfma_i32_16x16x64_i8 v[32:35], v[166:169], v[214:217], v[32:35]
	v_mfma_i32_16x16x64_i8 v[28:31], v[174:177], v[214:217], v[28:31]
	v_mfma_i32_16x16x64_i8 v[16:19], v[166:169], v[226:229], v[16:19]
	v_mfma_i32_16x16x64_i8 v[12:15], v[174:177], v[226:229], v[12:15]
	v_mfma_i32_16x16x64_i8 v[56:59], v[178:181], v[194:197], v[56:59]
	v_mfma_i32_16x16x64_i8 v[52:55], v[186:189], v[194:197], v[52:55]
	v_mfma_i32_16x16x64_i8 v[40:43], v[178:181], v[202:205], v[40:43]
	v_mfma_i32_16x16x64_i8 v[36:39], v[186:189], v[202:205], v[36:39]
	v_mfma_i32_16x16x64_i8 v[24:27], v[178:181], v[210:213], v[24:27]
	v_mfma_i32_16x16x64_i8 v[20:23], v[186:189], v[210:213], v[20:23]
	v_mfma_i32_16x16x64_i8 v[8:11], v[178:181], v[218:221], v[8:11]
	v_mfma_i32_16x16x64_i8 v[4:7], v[186:189], v[218:221], v[4:7]
	v_mfma_i32_16x16x64_i8 v[56:59], v[182:185], v[198:201], v[56:59]
	v_mfma_i32_16x16x64_i8 v[52:55], v[190:193], v[198:201], v[52:55]
	v_mfma_i32_16x16x64_i8 v[40:43], v[182:185], v[206:209], v[40:43]
	v_mfma_i32_16x16x64_i8 v[36:39], v[190:193], v[206:209], v[36:39]
	v_mfma_i32_16x16x64_i8 v[24:27], v[182:185], v[214:217], v[24:27]
	v_mfma_i32_16x16x64_i8 v[20:23], v[190:193], v[214:217], v[20:23]
	v_mfma_i32_16x16x64_i8 v[8:11], v[182:185], v[226:229], v[8:11]
	v_mfma_i32_16x16x64_i8 v[4:7], v[190:193], v[226:229], v[4:7]
	s_setprio 0
	s_barrier
	s_add_i32 s60, s60, 2
	s_add_u32 s38, s38, 0x100
	s_addc_u32 s39, s39, 0
	s_cmp_gt_u32 s60, 29
	s_cbranch_scc0 .LBB0_165
	s_and_b64 vcc, exec, s[42:43]
	s_cbranch_vccz .LBB0_168
	s_barrier

; #define PG8_STAGE(bufoff, gbase, voff) do { _Pragma("unroll") for (int _i = 0; _i < 2; ++_i) \
;         __builtin_amdgcn_global_load_lds((const unsigned*)((const char*)(gbase) + (voff)[_i]), (LAS unsigned*)(lds + (bufoff) + ldsw + _i * 8192), 16, 0, 0); } while (0)
; #define PG8_LDA(dst, b, h) do { _Pragma("unroll") for (int m = 0; m < 4; ++m) _Pragma("unroll") for (int k = 0; k < 2; ++k) dst[m][k] = *(const LAS bf16x8*)(lds + PG8_SA(b, h) + aoff + m * 2048 + k * 1024); } while (0)
; #define PG8_LDB(dst, b, h) do { _Pragma("unroll") for (int n = 0; n < 2; ++n) _Pragma("unroll") for (int k = 0; k < 2; ++k) dst[n][k] = *(const LAS bf16x8*)(lds + PG8_SB(b, h) + boff + n * 2048 + k * 1024); } while (0)
; #define PG8_WAIT_V(n) asm volatile("s_waitcnt vmcnt(" #n ")" ::: "memory")
; #define PG8_WAIT_L(n) asm volatile("s_waitcnt lgkmcnt(" #n ")" ::: "memory")
; #define PG8_BAR __builtin_amdgcn_s_barrier()
; #define PG8_SCHED __builtin_amdgcn_sched_barrier(0)
;     ...
;         for (int t = 0; t < nt; t += 2) {
;             const bool last = (t == nt - 2);
;             const char* a1 = cA + (size_t)(t + 1) * kstep;
;             const char* a2 = last ? nA : cA + (size_t)(t + 2) * kstep; const char* b2 = last ? nB : cB + (size_t)(t + 2) * kstep;
;             const char* a3 = a2 + kstep; const char* b3 = b2 + kstep;
;             if constexpr (SP2) {
;             PG8_LDB(B0, 0, 0); PG8_LDB(B1, 0, 1); PG8_SCHED; PG8_LDA(At, 0, 0); PG8_STAGE(PG8_SA(1, 1), a1 + hstepA, voffA);
;             PG8_WAIT_V(8); PG8_WAIT_L(0); PG8_BAR; PG8_MMA(0, 0, At, B0); PG8_MMA(0, 1, At, B1); PG8_BAR; PG8_SCHED;
;             PG8_LDA(At, 0, 1); PG8_STAGE(PG8_SB(0, 0), b2, voffB); PG8_STAGE(PG8_SB(0, 1), b2 + hstepB, voffB); PG8_STAGE(PG8_SA(0, 0), a2, voffA);
;             PG8_WAIT_V(8); PG8_WAIT_L(0); PG8_BAR; PG8_MMA(1, 0, At, B0); PG8_MMA(1, 1, At, B1); PG8_BAR; PG8_SCHED;
.LBB0_440:
	s_add_i32 s63, 0, 0x10000
	v_lshl_add_u64 v[4:5], v[180:181], 0, s[38:39]
	s_cmpk_eq_i32 s38, 0x300
	v_lshl_add_u64 v[4:5], v[4:5], 0, s[4:5]
	s_cselect_b64 vcc, -1, 0
	s_add_i32 s64, 0, 0x14000
	v_lshl_add_u64 v[6:7], v[186:187], 0, s[38:39]
	v_cndmask_b32_e32 v188, v4, v176, vcc
	v_add_u32_e32 v4, s63, v210
	v_add_u32_e32 v8, s64, v210
	v_cndmask_b32_e32 v189, v5, v177, vcc
	ds_read_b128 v[28:31], v4
	ds_read_b128 v[32:35], v4 offset:1024
	ds_read_b128 v[20:23], v4 offset:2048
	ds_read_b128 v[24:27], v4 offset:3072
	v_cndmask_b32_e32 v199, v7, v179, vcc
	v_cndmask_b32_e32 v198, v6, v178, vcc
	ds_read_b128 v[12:15], v8
	ds_read_b128 v[16:19], v8 offset:1024
	ds_read_b128 v[4:7], v8 offset:2048
	ds_read_b128 v[8:11], v8 offset:3072
	v_lshl_add_u64 v[200:201], v[184:185], 0, s[38:39]
	s_add_i32 m0, s15, 0xc000
	ds_read_b128 v[190:193], v212
	ds_read_b128 v[194:197], v212 offset:1024
	ds_read_b128 v[226:229], v212 offset:2048
	ds_read_b128 v[230:233], v212 offset:3072
	ds_read_b128 v[234:237], v212 offset:4096
	ds_read_b128 v[238:241], v212 offset:5120
	ds_read_b128 v[242:245], v212 offset:6144
	ds_read_b128 v[246:249], v212 offset:7168
	global_load_lds_dwordx4 v[200:201], off
	v_lshl_add_u64 v[200:201], v[182:183], 0, s[38:39]
	s_add_i32 m0, s15, 0xe000
	s_nop 0
	global_load_lds_dwordx4 v[200:201], off
	s_waitcnt vmcnt(8)
	s_waitcnt lgkmcnt(0)
	s_barrier
	s_setprio 1
	v_mfma_f32_16x16x128_f8f6f4 v[160:163], v[28:35], v[190:197], v[160:163]
	v_mfma_f32_16x16x128_f8f6f4 v[156:159], v[20:27], v[190:197], v[156:159]
	v_mfma_f32_16x16x128_f8f6f4 v[148:151], v[28:35], v[226:233], v[148:151]
	v_mfma_f32_16x16x128_f8f6f4 v[140:143], v[20:27], v[226:233], v[140:143]
	v_mfma_f32_16x16x128_f8f6f4 v[132:135], v[28:35], v[234:241], v[132:135]
	v_mfma_f32_16x16x128_f8f6f4 v[124:127], v[20:27], v[234:241], v[124:127]
	v_mfma_f32_16x16x128_f8f6f4 v[116:119], v[28:35], v[242:249], v[116:119]
	v_mfma_f32_16x16x128_f8f6f4 v[108:111], v[20:27], v[242:249], v[108:111]
	v_mfma_f32_16x16x128_f8f6f4 v[152:155], v[12:19], v[190:197], v[152:155]
	v_mfma_f32_16x16x128_f8f6f4 v[144:147], v[4:11], v[190:197], v[144:147]
	v_mfma_f32_16x16x128_f8f6f4 v[136:139], v[12:19], v[226:233], v[136:139]
	v_mfma_f32_16x16x128_f8f6f4 v[128:131], v[4:11], v[226:233], v[128:131]
	v_mfma_f32_16x16x128_f8f6f4 v[120:123], v[12:19], v[234:241], v[120:123]
	v_mfma_f32_16x16x128_f8f6f4 v[112:115], v[4:11], v[234:241], v[112:115]
	v_mfma_f32_16x16x128_f8f6f4 v[104:107], v[12:19], v[242:249], v[104:107]
	v_mfma_f32_16x16x128_f8f6f4 v[100:103], v[4:11], v[242:249], v[100:103]
	s_setprio 0
	s_barrier
	s_add_i32 s63, s63, s8
	v_lshl_add_u64 v[190:191], v[198:199], 0, v[2:3]
	s_mov_b32 m0, s63
	ds_read_b128 v[226:229], v212 offset:16384
	ds_read_b128 v[230:233], v212 offset:17408
	ds_read_b128 v[234:237], v212 offset:18432
	ds_read_b128 v[238:241], v212 offset:19456
	ds_read_b128 v[242:245], v212 offset:20480
	ds_read_b128 v[246:249], v212 offset:21504
	ds_read_b128 v[214:217], v212 offset:22528
	ds_read_b128 v[218:221], v212 offset:23552
	global_load_lds_dwordx4 v[190:191], off
	v_lshl_add_u64 v[192:193], v[198:199], 0, v[166:167]
	s_add_i32 m0, s63, 0x2000
	v_lshl_add_u64 v[196:197], v[198:199], 0, v[164:165]
	s_add_i32 s63, s64, s8
	global_load_lds_dwordx4 v[192:193], off
	v_lshl_add_u64 v[194:195], v[196:197], 0, v[2:3]
	s_mov_b32 m0, s63
	v_lshl_add_u64 v[196:197], v[196:197], 0, v[166:167]
	global_load_lds_dwordx4 v[194:195], off
	s_add_i32 m0, s63, 0x2000
	v_lshl_add_u64 v[198:199], v[188:189], 0, v[170:171]
	global_load_lds_dwordx4 v[196:197], off
	s_mov_b32 m0, s15
	v_lshl_add_u64 v[200:201], v[188:189], 0, v[168:169]
	global_load_lds_dwordx4 v[198:199], off
	s_mov_b32 m0, s33
	s_nop 0
	global_load_lds_dwordx4 v[200:201], off
	s_waitcnt vmcnt(8)
	s_waitcnt lgkmcnt(0)
	s_barrier
	s_setprio 1
	v_mfma_f32_16x16x128_f8f6f4 v[96:99], v[28:35], v[226:233], v[96:99]
	v_mfma_f32_16x16x128_f8f6f4 v[92:95], v[20:27], v[226:233], v[92:95]
	v_mfma_f32_16x16x128_f8f6f4 v[84:87], v[28:35], v[234:241], v[84:87]
	v_mfma_f32_16x16x128_f8f6f4 v[76:79], v[20:27], v[234:241], v[76:79]
	v_mfma_f32_16x16x128_f8f6f4 v[68:71], v[28:35], v[242:249], v[68:71]
	v_mfma_f32_16x16x128_f8f6f4 v[60:63], v[20:27], v[242:249], v[60:63]
	v_mfma_f32_16x16x128_f8f6f4 v[52:55], v[28:35], v[214:221], v[52:55]
	v_mfma_f32_16x16x128_f8f6f4 v[44:47], v[20:27], v[214:221], v[44:47]
	v_mfma_f32_16x16x128_f8f6f4 v[88:91], v[12:19], v[226:233], v[88:91]
	v_mfma_f32_16x16x128_f8f6f4 v[80:83], v[4:11], v[226:233], v[80:83]
	v_mfma_f32_16x16x128_f8f6f4 v[72:75], v[12:19], v[234:241], v[72:75]
	v_mfma_f32_16x16x128_f8f6f4 v[64:67], v[4:11], v[234:241], v[64:67]
	v_mfma_f32_16x16x128_f8f6f4 v[56:59], v[12:19], v[242:249], v[56:59]
	v_mfma_f32_16x16x128_f8f6f4 v[48:51], v[4:11], v[242:249], v[48:51]
	v_mfma_f32_16x16x128_f8f6f4 v[40:43], v[12:19], v[214:221], v[40:43]
	v_mfma_f32_16x16x128_f8f6f4 v[36:39], v[4:11], v[214:221], v[36:39]
	s_setprio 0
	s_barrier
; #define PG8_STAGE(bufoff, gbase, voff) do { _Pragma("unroll") for (int _i = 0; _i < 2; ++_i) \
;         __builtin_amdgcn_global_load_lds((const unsigned*)((const char*)(gbase) + (voff)[_i]), (LAS unsigned*)(lds + (bufoff) + ldsw + _i * 8192), 16, 0, 0); } while (0)
; #define PG8_LDA(dst, b, h) do { _Pragma("unroll") for (int m = 0; m < 4; ++m) _Pragma("unroll") for (int k = 0; k < 2; ++k) dst[m][k] = *(const LAS bf16x8*)(lds + PG8_SA(b, h) + aoff + m * 2048 + k * 1024); } while (0)
; #define PG8_LDB(dst, b, h) do { _Pragma("unroll") for (int n = 0; n < 2; ++n) _Pragma("unroll") for (int k = 0; k < 2; ++k) dst[n][k] = *(const LAS bf16x8*)(lds + PG8_SB(b, h) + boff + n * 2048 + k * 1024); } while (0)
; #define PG8_WAIT_V(n) asm volatile("s_waitcnt vmcnt(" #n ")" ::: "memory")
; #define PG8_WAIT_L(n) asm volatile("s_waitcnt lgkmcnt(" #n ")" ::: "memory")
; #define PG8_BAR __builtin_amdgcn_s_barrier()
; #define PG8_SCHED __builtin_amdgcn_sched_barrier(0)
;     ...
;             PG8_LDB(B0, 1, 0); PG8_LDB(B1, 1, 1); PG8_SCHED; PG8_LDA(At, 1, 0); PG8_STAGE(PG8_SA(0, 1), a2 + hstepA, voffA);
;             PG8_WAIT_V(8); PG8_WAIT_L(0); PG8_BAR; PG8_MMA(0, 0, At, B0); PG8_MMA(0, 1, At, B1); PG8_BAR; PG8_SCHED;
;             PG8_LDA(At, 1, 1); PG8_STAGE(PG8_SB(1, 0), b3, voffB); PG8_STAGE(PG8_SB(1, 1), b3 + hstepB, voffB); PG8_STAGE(PG8_SA(1, 0), a3, voffA);
;             PG8_WAIT_V(8); PG8_WAIT_L(0); PG8_BAR; PG8_MMA(1, 0, At, B0); PG8_MMA(1, 1, At, B1); PG8_BAR; PG8_SCHED;
	s_add_i32 s63, 0, 0x18000
	s_add_i32 s64, 0, 0x1c000
	v_add_u32_e32 v16, s63, v210
	v_add_u32_e32 v32, s64, v210
	ds_read_b128 v[4:7], v16
	ds_read_b128 v[8:11], v16 offset:1024
	ds_read_b128 v[12:15], v16 offset:2048
	ds_read_b128 v[16:19], v16 offset:3072
	ds_read_b128 v[20:23], v32
	ds_read_b128 v[24:27], v32 offset:1024
	ds_read_b128 v[28:31], v32 offset:2048
	ds_read_b128 v[32:35], v32 offset:3072
	v_lshl_add_u64 v[188:189], v[188:189], 0, v[0:1]
	s_mov_b32 m0, s44
	v_lshl_add_u64 v[202:203], v[188:189], 0, v[170:171]
	ds_read_b128 v[214:217], v212 offset:32768
	ds_read_b128 v[218:221], v212 offset:33792
	ds_read_b128 v[226:229], v212 offset:34816
	ds_read_b128 v[230:233], v212 offset:35840
	ds_read_b128 v[234:237], v212 offset:36864
	ds_read_b128 v[238:241], v212 offset:37888
	ds_read_b128 v[242:245], v212 offset:38912
	ds_read_b128 v[246:249], v212 offset:39936
	global_load_lds_dwordx4 v[202:203], off
	v_lshl_add_u64 v[188:189], v[188:189], 0, v[168:169]
	s_mov_b32 m0, s45
	s_nop 0
	global_load_lds_dwordx4 v[188:189], off
	s_waitcnt vmcnt(8)
	s_waitcnt lgkmcnt(0)
	s_barrier
	s_setprio 1
	v_mfma_f32_16x16x128_f8f6f4 v[160:163], v[4:11], v[214:221], v[160:163]
	v_mfma_f32_16x16x128_f8f6f4 v[156:159], v[12:19], v[214:221], v[156:159]
	v_mfma_f32_16x16x128_f8f6f4 v[148:151], v[4:11], v[226:233], v[148:151]
	v_mfma_f32_16x16x128_f8f6f4 v[140:143], v[12:19], v[226:233], v[140:143]
	v_mfma_f32_16x16x128_f8f6f4 v[132:135], v[4:11], v[234:241], v[132:135]
	v_mfma_f32_16x16x128_f8f6f4 v[124:127], v[12:19], v[234:241], v[124:127]
	v_mfma_f32_16x16x128_f8f6f4 v[116:119], v[4:11], v[242:249], v[116:119]
	v_mfma_f32_16x16x128_f8f6f4 v[108:111], v[12:19], v[242:249], v[108:111]
	v_mfma_f32_16x16x128_f8f6f4 v[152:155], v[20:27], v[214:221], v[152:155]
	v_mfma_f32_16x16x128_f8f6f4 v[144:147], v[28:35], v[214:221], v[144:147]
	v_mfma_f32_16x16x128_f8f6f4 v[136:139], v[20:27], v[226:233], v[136:139]
	v_mfma_f32_16x16x128_f8f6f4 v[128:131], v[28:35], v[226:233], v[128:131]
	v_mfma_f32_16x16x128_f8f6f4 v[120:123], v[20:27], v[234:241], v[120:123]
	v_mfma_f32_16x16x128_f8f6f4 v[112:115], v[28:35], v[234:241], v[112:115]
	v_mfma_f32_16x16x128_f8f6f4 v[104:107], v[20:27], v[242:249], v[104:107]
	v_mfma_f32_16x16x128_f8f6f4 v[100:103], v[28:35], v[242:249], v[100:103]
	s_setprio 0
	s_barrier
	s_add_i32 s63, s63, s8
	v_lshl_add_u64 v[188:189], v[190:191], 0, s[52:53]
	s_mov_b32 m0, s63
	ds_read_b128 v[214:217], v212 offset:49152
	ds_read_b128 v[218:221], v212 offset:50176
	ds_read_b128 v[226:229], v212 offset:51200
	ds_read_b128 v[230:233], v212 offset:52224
	ds_read_b128 v[234:237], v212 offset:53248
	ds_read_b128 v[238:241], v212 offset:54272
	ds_read_b128 v[242:245], v212 offset:55296
	ds_read_b128 v[246:249], v212 offset:56320
	global_load_lds_dwordx4 v[188:189], off
	v_lshl_add_u64 v[188:189], v[192:193], 0, s[52:53]
	s_add_i32 m0, s63, 0x2000
	s_add_i32 s63, s64, s8
	global_load_lds_dwordx4 v[188:189], off
	v_lshl_add_u64 v[188:189], v[194:195], 0, s[52:53]
	s_mov_b32 m0, s63
	s_nop 0
	global_load_lds_dwordx4 v[188:189], off
	v_lshl_add_u64 v[188:189], v[196:197], 0, s[52:53]
	s_add_i32 m0, s63, 0x2000
	s_nop 0
	global_load_lds_dwordx4 v[188:189], off
	v_lshl_add_u64 v[188:189], v[198:199], 0, s[52:53]
	s_mov_b32 m0, s46
	s_nop 0
	global_load_lds_dwordx4 v[188:189], off
	v_lshl_add_u64 v[188:189], v[200:201], 0, s[52:53]
	s_mov_b32 m0, s47
	s_nop 0
	global_load_lds_dwordx4 v[188:189], off
	s_waitcnt vmcnt(8)
	s_waitcnt lgkmcnt(0)
	s_barrier
	s_setprio 1
	v_mfma_f32_16x16x128_f8f6f4 v[96:99], v[4:11], v[214:221], v[96:99]
	v_mfma_f32_16x16x128_f8f6f4 v[92:95], v[12:19], v[214:221], v[92:95]
	v_mfma_f32_16x16x128_f8f6f4 v[84:87], v[4:11], v[226:233], v[84:87]
	v_mfma_f32_16x16x128_f8f6f4 v[76:79], v[12:19], v[226:233], v[76:79]
	v_mfma_f32_16x16x128_f8f6f4 v[68:71], v[4:11], v[234:241], v[68:71]
	v_mfma_f32_16x16x128_f8f6f4 v[60:63], v[12:19], v[234:241], v[60:63]
	v_mfma_f32_16x16x128_f8f6f4 v[52:55], v[4:11], v[242:249], v[52:55]
	v_mfma_f32_16x16x128_f8f6f4 v[44:47], v[12:19], v[242:249], v[44:47]
	v_mfma_f32_16x16x128_f8f6f4 v[88:91], v[20:27], v[214:221], v[88:91]
	v_mfma_f32_16x16x128_f8f6f4 v[80:83], v[28:35], v[214:221], v[80:83]
	v_mfma_f32_16x16x128_f8f6f4 v[72:75], v[20:27], v[226:233], v[72:75]
	v_mfma_f32_16x16x128_f8f6f4 v[64:67], v[28:35], v[226:233], v[64:67]
	v_mfma_f32_16x16x128_f8f6f4 v[56:59], v[20:27], v[234:241], v[56:59]
	v_mfma_f32_16x16x128_f8f6f4 v[48:51], v[28:35], v[234:241], v[48:51]
	v_mfma_f32_16x16x128_f8f6f4 v[40:43], v[20:27], v[242:249], v[40:43]
	v_mfma_f32_16x16x128_f8f6f4 v[36:39], v[28:35], v[242:249], v[36:39]
	s_setprio 0
	s_barrier
	s_add_i32 s62, s62, 2
	s_add_u32 s38, s38, 0x100
	s_addc_u32 s39, s39, 0
	s_cmp_gt_u32 s62, 5
	s_cbranch_scc0 .LBB0_440
	s_and_b64 vcc, exec, s[42:43]
	s_cbranch_vccz .LBB0_443
	s_barrier

; #define PG8_STAGE(bufoff, gbase, voff) do { _Pragma("unroll") for (int _i = 0; _i < 2; ++_i) \
;         __builtin_amdgcn_global_load_lds((const unsigned*)((const char*)(gbase) + (voff)[_i]), (LAS unsigned*)(lds + (bufoff) + ldsw + _i * 8192), 16, 0, 0); } while (0)
; #define PG8_LDA(dst, b, h) do { _Pragma("unroll") for (int m = 0; m < 4; ++m) _Pragma("unroll") for (int k = 0; k < 2; ++k) dst[m][k] = *(const LAS bf16x8*)(lds + PG8_SA(b, h) + aoff + m * 2048 + k * 1024); } while (0)
; #define PG8_LDB(dst, b, h) do { _Pragma("unroll") for (int n = 0; n < 2; ++n) _Pragma("unroll") for (int k = 0; k < 2; ++k) dst[n][k] = *(const LAS bf16x8*)(lds + PG8_SB(b, h) + boff + n * 2048 + k * 1024); } while (0)
; #define PG8_WAIT_V(n) asm volatile("s_waitcnt vmcnt(" #n ")" ::: "memory")
; #define PG8_WAIT_L(n) asm volatile("s_waitcnt lgkmcnt(" #n ")" ::: "memory")
; #define PG8_BAR __builtin_amdgcn_s_barrier()
; #define PG8_SCHED __builtin_amdgcn_sched_barrier(0)
;     ...
;         for (int t = 0; t < nt; t += 2) {
;             const bool last = (t == nt - 2);
;             const char* a1 = cA + (size_t)(t + 1) * kstep;
;             const char* a2 = last ? nA : cA + (size_t)(t + 2) * kstep; const char* b2 = last ? nB : cB + (size_t)(t + 2) * kstep;
;             const char* a3 = a2 + kstep; const char* b3 = b2 + kstep;
;             if constexpr (SP2) {
;             PG8_LDB(B0, 0, 0); PG8_LDB(B1, 0, 1); PG8_SCHED; PG8_LDA(At, 0, 0); PG8_STAGE(PG8_SA(1, 1), a1 + hstepA, voffA);
;             PG8_WAIT_V(8); PG8_WAIT_L(0); PG8_BAR; PG8_MMA(0, 0, At, B0); PG8_MMA(0, 1, At, B1); PG8_BAR; PG8_SCHED;
;             PG8_LDA(At, 0, 1); PG8_STAGE(PG8_SB(0, 0), b2, voffB); PG8_STAGE(PG8_SB(0, 1), b2 + hstepB, voffB); PG8_STAGE(PG8_SA(0, 0), a2, voffA);
;             PG8_WAIT_V(8); PG8_WAIT_L(0); PG8_BAR; PG8_MMA(1, 0, At, B0); PG8_MMA(1, 1, At, B1); PG8_BAR; PG8_SCHED;
.LBB0_783:
	s_add_i32 s39, 0, 0x10000
	s_cmpk_eq_i32 s28, 0xf00
	v_lshl_add_u64 v[160:161], v[148:149], 0, s[28:29]
	s_cselect_b64 vcc, -1, 0
	s_add_i32 s75, 0, 0x14000
	v_lshl_add_u64 v[160:161], v[160:161], 0, s[4:5]
	v_lshl_add_u64 v[176:177], v[154:155], 0, s[28:29]
	v_add_u32_e32 v172, s39, v157
	v_add_u32_e32 v188, s75, v157
	v_cndmask_b32_e32 v231, v161, v145, vcc
	v_cndmask_b32_e32 v230, v160, v144, vcc
	ds_read_b128 v[160:163], v172
	ds_read_b128 v[164:167], v172 offset:1024
	ds_read_b128 v[168:171], v172 offset:2048
	ds_read_b128 v[172:175], v172 offset:3072
	v_cndmask_b32_e32 v233, v177, v147, vcc
	v_cndmask_b32_e32 v232, v176, v146, vcc
	ds_read_b128 v[176:179], v188
	ds_read_b128 v[180:183], v188 offset:1024
	ds_read_b128 v[184:187], v188 offset:2048
	ds_read_b128 v[188:191], v188 offset:3072
	v_lshl_add_u64 v[234:235], v[152:153], 0, s[28:29]
	s_add_i32 m0, s33, 0xc000
	ds_read_b128 v[192:195], v159
	ds_read_b128 v[196:199], v159 offset:1024
	ds_read_b128 v[200:203], v159 offset:2048
	ds_read_b128 v[204:207], v159 offset:3072
	ds_read_b128 v[210:213], v159 offset:4096
	ds_read_b128 v[214:217], v159 offset:5120
	ds_read_b128 v[218:221], v159 offset:6144
	ds_read_b128 v[226:229], v159 offset:7168
	global_load_lds_dwordx4 v[234:235], off
	v_lshl_add_u64 v[234:235], v[150:151], 0, s[28:29]
	s_add_i32 m0, s33, 0xe000
	s_nop 0
	global_load_lds_dwordx4 v[234:235], off
	s_waitcnt vmcnt(8)
	s_waitcnt lgkmcnt(0)
	s_barrier
	s_setprio 1
	v_mfma_i32_16x16x64_i8 v[128:131], v[160:163], v[192:195], v[128:131]
	v_mfma_i32_16x16x64_i8 v[124:127], v[168:171], v[192:195], v[124:127]
	v_mfma_i32_16x16x64_i8 v[112:115], v[160:163], v[200:203], v[112:115]
	v_mfma_i32_16x16x64_i8 v[108:111], v[168:171], v[200:203], v[108:111]
	v_mfma_i32_16x16x64_i8 v[96:99], v[160:163], v[210:213], v[96:99]
	v_mfma_i32_16x16x64_i8 v[92:95], v[168:171], v[210:213], v[92:95]
	v_mfma_i32_16x16x64_i8 v[80:83], v[160:163], v[218:221], v[80:83]
	v_mfma_i32_16x16x64_i8 v[76:79], v[168:171], v[218:221], v[76:79]
	v_mfma_i32_16x16x64_i8 v[128:131], v[164:167], v[196:199], v[128:131]
	v_mfma_i32_16x16x64_i8 v[124:127], v[172:175], v[196:199], v[124:127]
	v_mfma_i32_16x16x64_i8 v[112:115], v[164:167], v[204:207], v[112:115]
	v_mfma_i32_16x16x64_i8 v[108:111], v[172:175], v[204:207], v[108:111]
	v_mfma_i32_16x16x64_i8 v[96:99], v[164:167], v[214:217], v[96:99]
	v_mfma_i32_16x16x64_i8 v[92:95], v[172:175], v[214:217], v[92:95]
	v_mfma_i32_16x16x64_i8 v[80:83], v[164:167], v[226:229], v[80:83]
	v_mfma_i32_16x16x64_i8 v[76:79], v[172:175], v[226:229], v[76:79]
	v_mfma_i32_16x16x64_i8 v[120:123], v[176:179], v[192:195], v[120:123]
	v_mfma_i32_16x16x64_i8 v[116:119], v[184:187], v[192:195], v[116:119]
	v_mfma_i32_16x16x64_i8 v[104:107], v[176:179], v[200:203], v[104:107]
	v_mfma_i32_16x16x64_i8 v[100:103], v[184:187], v[200:203], v[100:103]
	v_mfma_i32_16x16x64_i8 v[88:91], v[176:179], v[210:213], v[88:91]
	v_mfma_i32_16x16x64_i8 v[84:87], v[184:187], v[210:213], v[84:87]
	v_mfma_i32_16x16x64_i8 v[72:75], v[176:179], v[218:221], v[72:75]
	v_mfma_i32_16x16x64_i8 v[68:71], v[184:187], v[218:221], v[68:71]
	v_mfma_i32_16x16x64_i8 v[120:123], v[180:183], v[196:199], v[120:123]
	v_mfma_i32_16x16x64_i8 v[116:119], v[188:191], v[196:199], v[116:119]
	v_mfma_i32_16x16x64_i8 v[104:107], v[180:183], v[204:207], v[104:107]
	v_mfma_i32_16x16x64_i8 v[100:103], v[188:191], v[204:207], v[100:103]
	v_mfma_i32_16x16x64_i8 v[88:91], v[180:183], v[214:217], v[88:91]
	v_mfma_i32_16x16x64_i8 v[84:87], v[188:191], v[214:217], v[84:87]
	v_mfma_i32_16x16x64_i8 v[72:75], v[180:183], v[226:229], v[72:75]
	v_mfma_i32_16x16x64_i8 v[68:71], v[188:191], v[226:229], v[68:71]
	s_setprio 0
	s_barrier
	s_add_i32 s39, s39, s15
	v_lshl_add_u64 v[234:235], v[232:233], 0, v[2:3]
	s_mov_b32 m0, s39
	ds_read_b128 v[192:195], v159 offset:16384
	ds_read_b128 v[196:199], v159 offset:17408
	ds_read_b128 v[200:203], v159 offset:18432
	ds_read_b128 v[204:207], v159 offset:19456
	ds_read_b128 v[210:213], v159 offset:20480
	ds_read_b128 v[214:217], v159 offset:21504
	ds_read_b128 v[218:221], v159 offset:22528
	ds_read_b128 v[226:229], v159 offset:23552
	global_load_lds_dwordx4 v[234:235], off
	v_lshl_add_u64 v[236:237], v[232:233], 0, v[134:135]
	s_add_i32 m0, s39, 0x2000
	v_lshl_add_u64 v[232:233], v[232:233], 0, v[138:139]
	s_add_i32 s39, s75, s15
	global_load_lds_dwordx4 v[236:237], off
	v_lshl_add_u64 v[238:239], v[232:233], 0, v[2:3]
	s_mov_b32 m0, s39
	v_lshl_add_u64 v[232:233], v[232:233], 0, v[134:135]
	global_load_lds_dwordx4 v[238:239], off
	s_add_i32 m0, s39, 0x2000
	v_lshl_add_u64 v[240:241], v[230:231], 0, v[0:1]
	global_load_lds_dwordx4 v[232:233], off
	s_mov_b32 m0, s33
	v_lshl_add_u64 v[242:243], v[230:231], 0, v[132:133]
	global_load_lds_dwordx4 v[240:241], off
	s_mov_b32 m0, s57
	s_nop 0
	global_load_lds_dwordx4 v[242:243], off
	s_waitcnt vmcnt(8)
	s_waitcnt lgkmcnt(0)
	s_barrier
; #define PG8_STAGE(bufoff, gbase, voff) do { _Pragma("unroll") for (int _i = 0; _i < 2; ++_i) \
;         __builtin_amdgcn_global_load_lds((const unsigned*)((const char*)(gbase) + (voff)[_i]), (LAS unsigned*)(lds + (bufoff) + ldsw + _i * 8192), 16, 0, 0); } while (0)
; #define PG8_LDA(dst, b, h) do { _Pragma("unroll") for (int m = 0; m < 4; ++m) _Pragma("unroll") for (int k = 0; k < 2; ++k) dst[m][k] = *(const LAS bf16x8*)(lds + PG8_SA(b, h) + aoff + m * 2048 + k * 1024); } while (0)
; #define PG8_LDB(dst, b, h) do { _Pragma("unroll") for (int n = 0; n < 2; ++n) _Pragma("unroll") for (int k = 0; k < 2; ++k) dst[n][k] = *(const LAS bf16x8*)(lds + PG8_SB(b, h) + boff + n * 2048 + k * 1024); } while (0)
; #define PG8_WAIT_V(n) asm volatile("s_waitcnt vmcnt(" #n ")" ::: "memory")
; #define PG8_WAIT_L(n) asm volatile("s_waitcnt lgkmcnt(" #n ")" ::: "memory")
; #define PG8_BAR __builtin_amdgcn_s_barrier()
; #define PG8_SCHED __builtin_amdgcn_sched_barrier(0)
;     ...
;             PG8_WAIT_V(8); PG8_WAIT_L(0); PG8_BAR; PG8_MMA(1, 0, At, B0); PG8_MMA(1, 1, At, B1); PG8_BAR; PG8_SCHED;
;             PG8_LDB(B0, 1, 0); PG8_LDB(B1, 1, 1); PG8_SCHED; PG8_LDA(At, 1, 0); PG8_STAGE(PG8_SA(0, 1), a2 + hstepA, voffA);
;             PG8_WAIT_V(8); PG8_WAIT_L(0); PG8_BAR; PG8_MMA(0, 0, At, B0); PG8_MMA(0, 1, At, B1); PG8_BAR; PG8_SCHED;
	s_setprio 1
	v_mfma_i32_16x16x64_i8 v[64:67], v[160:163], v[192:195], v[64:67]
	v_mfma_i32_16x16x64_i8 v[60:63], v[168:171], v[192:195], v[60:63]
	v_mfma_i32_16x16x64_i8 v[48:51], v[160:163], v[200:203], v[48:51]
	v_mfma_i32_16x16x64_i8 v[44:47], v[168:171], v[200:203], v[44:47]
	v_mfma_i32_16x16x64_i8 v[32:35], v[160:163], v[210:213], v[32:35]
	v_mfma_i32_16x16x64_i8 v[28:31], v[168:171], v[210:213], v[28:31]
	v_mfma_i32_16x16x64_i8 v[16:19], v[160:163], v[218:221], v[16:19]
	v_mfma_i32_16x16x64_i8 v[12:15], v[168:171], v[218:221], v[12:15]
	v_mfma_i32_16x16x64_i8 v[64:67], v[164:167], v[196:199], v[64:67]
	v_mfma_i32_16x16x64_i8 v[60:63], v[172:175], v[196:199], v[60:63]
	v_mfma_i32_16x16x64_i8 v[48:51], v[164:167], v[204:207], v[48:51]
	v_mfma_i32_16x16x64_i8 v[44:47], v[172:175], v[204:207], v[44:47]
	v_mfma_i32_16x16x64_i8 v[32:35], v[164:167], v[214:217], v[32:35]
	v_mfma_i32_16x16x64_i8 v[28:31], v[172:175], v[214:217], v[28:31]
	v_mfma_i32_16x16x64_i8 v[16:19], v[164:167], v[226:229], v[16:19]
	v_mfma_i32_16x16x64_i8 v[12:15], v[172:175], v[226:229], v[12:15]
	v_mfma_i32_16x16x64_i8 v[56:59], v[176:179], v[192:195], v[56:59]
	v_mfma_i32_16x16x64_i8 v[52:55], v[184:187], v[192:195], v[52:55]
	v_mfma_i32_16x16x64_i8 v[40:43], v[176:179], v[200:203], v[40:43]
	v_mfma_i32_16x16x64_i8 v[36:39], v[184:187], v[200:203], v[36:39]
	v_mfma_i32_16x16x64_i8 v[24:27], v[176:179], v[210:213], v[24:27]
	v_mfma_i32_16x16x64_i8 v[20:23], v[184:187], v[210:213], v[20:23]
	v_mfma_i32_16x16x64_i8 v[8:11], v[176:179], v[218:221], v[8:11]
	v_mfma_i32_16x16x64_i8 v[4:7], v[184:187], v[218:221], v[4:7]
	v_mfma_i32_16x16x64_i8 v[56:59], v[180:183], v[196:199], v[56:59]
	v_mfma_i32_16x16x64_i8 v[52:55], v[188:191], v[196:199], v[52:55]
	v_mfma_i32_16x16x64_i8 v[40:43], v[180:183], v[204:207], v[40:43]
	v_mfma_i32_16x16x64_i8 v[36:39], v[188:191], v[204:207], v[36:39]
	v_mfma_i32_16x16x64_i8 v[24:27], v[180:183], v[214:217], v[24:27]
	v_mfma_i32_16x16x64_i8 v[20:23], v[188:191], v[214:217], v[20:23]
	v_mfma_i32_16x16x64_i8 v[8:11], v[180:183], v[226:229], v[8:11]
	v_mfma_i32_16x16x64_i8 v[4:7], v[188:191], v[226:229], v[4:7]
	s_setprio 0
	s_barrier
	s_add_i32 s39, 0, 0x18000
	s_add_i32 s75, 0, 0x1c000
	v_add_u32_e32 v172, s39, v157
	v_add_u32_e32 v188, s75, v157
	ds_read_b128 v[160:163], v172
	ds_read_b128 v[164:167], v172 offset:1024
	ds_read_b128 v[168:171], v172 offset:2048
	ds_read_b128 v[172:175], v172 offset:3072
	ds_read_b128 v[176:179], v188
	ds_read_b128 v[180:183], v188 offset:1024
	ds_read_b128 v[184:187], v188 offset:2048
	ds_read_b128 v[188:191], v188 offset:3072
	v_lshl_add_u64 v[230:231], v[230:231], 0, v[136:137]
	s_mov_b32 m0, s62
	v_lshl_add_u64 v[244:245], v[230:231], 0, v[0:1]
	ds_read_b128 v[192:195], v159 offset:32768
	ds_read_b128 v[196:199], v159 offset:33792
	ds_read_b128 v[200:203], v159 offset:34816
	ds_read_b128 v[204:207], v159 offset:35840
	ds_read_b128 v[210:213], v159 offset:36864
	ds_read_b128 v[214:217], v159 offset:37888
	ds_read_b128 v[218:221], v159 offset:38912
	ds_read_b128 v[226:229], v159 offset:39936
	global_load_lds_dwordx4 v[244:245], off
	v_lshl_add_u64 v[230:231], v[230:231], 0, v[132:133]
	s_mov_b32 m0, s63
	s_nop 0
	global_load_lds_dwordx4 v[230:231], off
	s_waitcnt vmcnt(8)
	s_waitcnt lgkmcnt(0)
	s_barrier
	s_setprio 1
	v_mfma_i32_16x16x64_i8 v[128:131], v[160:163], v[192:195], v[128:131]
	v_mfma_i32_16x16x64_i8 v[124:127], v[168:171], v[192:195], v[124:127]
	v_mfma_i32_16x16x64_i8 v[112:115], v[160:163], v[200:203], v[112:115]
	v_mfma_i32_16x16x64_i8 v[108:111], v[168:171], v[200:203], v[108:111]
	v_mfma_i32_16x16x64_i8 v[96:99], v[160:163], v[210:213], v[96:99]
	v_mfma_i32_16x16x64_i8 v[92:95], v[168:171], v[210:213], v[92:95]
	v_mfma_i32_16x16x64_i8 v[80:83], v[160:163], v[218:221], v[80:83]
	v_mfma_i32_16x16x64_i8 v[76:79], v[168:171], v[218:221], v[76:79]
	v_mfma_i32_16x16x64_i8 v[128:131], v[164:167], v[196:199], v[128:131]
	v_mfma_i32_16x16x64_i8 v[124:127], v[172:175], v[196:199], v[124:127]
	v_mfma_i32_16x16x64_i8 v[112:115], v[164:167], v[204:207], v[112:115]
	v_mfma_i32_16x16x64_i8 v[108:111], v[172:175], v[204:207], v[108:111]
	v_mfma_i32_16x16x64_i8 v[96:99], v[164:167], v[214:217], v[96:99]
	v_mfma_i32_16x16x64_i8 v[92:95], v[172:175], v[214:217], v[92:95]
	v_mfma_i32_16x16x64_i8 v[80:83], v[164:167], v[226:229], v[80:83]
	v_mfma_i32_16x16x64_i8 v[76:79], v[172:175], v[226:229], v[76:79]
	v_mfma_i32_16x16x64_i8 v[120:123], v[176:179], v[192:195], v[120:123]
	v_mfma_i32_16x16x64_i8 v[116:119], v[184:187], v[192:195], v[116:119]
	v_mfma_i32_16x16x64_i8 v[104:107], v[176:179], v[200:203], v[104:107]
	v_mfma_i32_16x16x64_i8 v[100:103], v[184:187], v[200:203], v[100:103]
	v_mfma_i32_16x16x64_i8 v[88:91], v[176:179], v[210:213], v[88:91]
	v_mfma_i32_16x16x64_i8 v[84:87], v[184:187], v[210:213], v[84:87]
	v_mfma_i32_16x16x64_i8 v[72:75], v[176:179], v[218:221], v[72:75]
	v_mfma_i32_16x16x64_i8 v[68:71], v[184:187], v[218:221], v[68:71]
	v_mfma_i32_16x16x64_i8 v[120:123], v[180:183], v[196:199], v[120:123]
	v_mfma_i32_16x16x64_i8 v[116:119], v[188:191], v[196:199], v[116:119]
	v_mfma_i32_16x16x64_i8 v[104:107], v[180:183], v[204:207], v[104:107]
	v_mfma_i32_16x16x64_i8 v[100:103], v[188:191], v[204:207], v[100:103]
	v_mfma_i32_16x16x64_i8 v[88:91], v[180:183], v[214:217], v[88:91]
	v_mfma_i32_16x16x64_i8 v[84:87], v[188:191], v[214:217], v[84:87]
	v_mfma_i32_16x16x64_i8 v[72:75], v[180:183], v[226:229], v[72:75]
	v_mfma_i32_16x16x64_i8 v[68:71], v[188:191], v[226:229], v[68:71]
	s_setprio 0
	s_barrier
; #define PG8_STAGE(bufoff, gbase, voff) do { _Pragma("unroll") for (int _i = 0; _i < 2; ++_i) \
;         __builtin_amdgcn_global_load_lds((const unsigned*)((const char*)(gbase) + (voff)[_i]), (LAS unsigned*)(lds + (bufoff) + ldsw + _i * 8192), 16, 0, 0); } while (0)
; #define PG8_LDA(dst, b, h) do { _Pragma("unroll") for (int m = 0; m < 4; ++m) _Pragma("unroll") for (int k = 0; k < 2; ++k) dst[m][k] = *(const LAS bf16x8*)(lds + PG8_SA(b, h) + aoff + m * 2048 + k * 1024); } while (0)
; #define PG8_WAIT_V(n) asm volatile("s_waitcnt vmcnt(" #n ")" ::: "memory")
; #define PG8_WAIT_L(n) asm volatile("s_waitcnt lgkmcnt(" #n ")" ::: "memory")
; #define PG8_BAR __builtin_amdgcn_s_barrier()
; #define PG8_SCHED __builtin_amdgcn_sched_barrier(0)
;     ...
;             PG8_LDA(At, 1, 1); PG8_STAGE(PG8_SB(1, 0), b3, voffB); PG8_STAGE(PG8_SB(1, 1), b3 + hstepB, voffB); PG8_STAGE(PG8_SA(1, 0), a3, voffA);
;             PG8_WAIT_V(8); PG8_WAIT_L(0); PG8_BAR; PG8_MMA(1, 0, At, B0); PG8_MMA(1, 1, At, B1); PG8_BAR; PG8_SCHED;
	s_add_i32 s39, s39, s15
	v_lshl_add_u64 v[230:231], v[234:235], 0, s[52:53]
	s_mov_b32 m0, s39
	ds_read_b128 v[192:195], v159 offset:49152
	ds_read_b128 v[196:199], v159 offset:50176
	ds_read_b128 v[200:203], v159 offset:51200
	ds_read_b128 v[204:207], v159 offset:52224
	ds_read_b128 v[210:213], v159 offset:53248
	ds_read_b128 v[214:217], v159 offset:54272
	ds_read_b128 v[218:221], v159 offset:55296
	ds_read_b128 v[226:229], v159 offset:56320
	global_load_lds_dwordx4 v[230:231], off
	v_lshl_add_u64 v[230:231], v[236:237], 0, s[52:53]
	s_add_i32 m0, s39, 0x2000
	s_add_i32 s39, s75, s15
	global_load_lds_dwordx4 v[230:231], off
	v_lshl_add_u64 v[230:231], v[238:239], 0, s[52:53]
	s_mov_b32 m0, s39
	s_nop 0
	global_load_lds_dwordx4 v[230:231], off
	v_lshl_add_u64 v[230:231], v[232:233], 0, s[52:53]
	s_add_i32 m0, s39, 0x2000
	s_nop 0
	global_load_lds_dwordx4 v[230:231], off
	v_lshl_add_u64 v[230:231], v[240:241], 0, s[52:53]
	s_mov_b32 m0, s64
	s_nop 0
	global_load_lds_dwordx4 v[230:231], off
	v_lshl_add_u64 v[230:231], v[242:243], 0, s[52:53]
	s_mov_b32 m0, s65
	s_nop 0
	global_load_lds_dwordx4 v[230:231], off
	s_waitcnt vmcnt(8)
	s_waitcnt lgkmcnt(0)
	s_barrier
	s_setprio 1
	v_mfma_i32_16x16x64_i8 v[64:67], v[160:163], v[192:195], v[64:67]
	v_mfma_i32_16x16x64_i8 v[60:63], v[168:171], v[192:195], v[60:63]
	v_mfma_i32_16x16x64_i8 v[48:51], v[160:163], v[200:203], v[48:51]
	v_mfma_i32_16x16x64_i8 v[44:47], v[168:171], v[200:203], v[44:47]
	v_mfma_i32_16x16x64_i8 v[32:35], v[160:163], v[210:213], v[32:35]
	v_mfma_i32_16x16x64_i8 v[28:31], v[168:171], v[210:213], v[28:31]
	v_mfma_i32_16x16x64_i8 v[16:19], v[160:163], v[218:221], v[16:19]
	v_mfma_i32_16x16x64_i8 v[12:15], v[168:171], v[218:221], v[12:15]
	v_mfma_i32_16x16x64_i8 v[64:67], v[164:167], v[196:199], v[64:67]
	v_mfma_i32_16x16x64_i8 v[60:63], v[172:175], v[196:199], v[60:63]
	v_mfma_i32_16x16x64_i8 v[48:51], v[164:167], v[204:207], v[48:51]
	v_mfma_i32_16x16x64_i8 v[44:47], v[172:175], v[204:207], v[44:47]
	v_mfma_i32_16x16x64_i8 v[32:35], v[164:167], v[214:217], v[32:35]
	v_mfma_i32_16x16x64_i8 v[28:31], v[172:175], v[214:217], v[28:31]
	v_mfma_i32_16x16x64_i8 v[16:19], v[164:167], v[226:229], v[16:19]
	v_mfma_i32_16x16x64_i8 v[12:15], v[172:175], v[226:229], v[12:15]
	v_mfma_i32_16x16x64_i8 v[56:59], v[176:179], v[192:195], v[56:59]
	v_mfma_i32_16x16x64_i8 v[52:55], v[184:187], v[192:195], v[52:55]
	v_mfma_i32_16x16x64_i8 v[40:43], v[176:179], v[200:203], v[40:43]
	v_mfma_i32_16x16x64_i8 v[36:39], v[184:187], v[200:203], v[36:39]
	v_mfma_i32_16x16x64_i8 v[24:27], v[176:179], v[210:213], v[24:27]
	v_mfma_i32_16x16x64_i8 v[20:23], v[184:187], v[210:213], v[20:23]
	v_mfma_i32_16x16x64_i8 v[8:11], v[176:179], v[218:221], v[8:11]
	v_mfma_i32_16x16x64_i8 v[4:7], v[184:187], v[218:221], v[4:7]
	v_mfma_i32_16x16x64_i8 v[56:59], v[180:183], v[196:199], v[56:59]
	v_mfma_i32_16x16x64_i8 v[52:55], v[188:191], v[196:199], v[52:55]
	v_mfma_i32_16x16x64_i8 v[40:43], v[180:183], v[204:207], v[40:43]
	v_mfma_i32_16x16x64_i8 v[36:39], v[188:191], v[204:207], v[36:39]
	v_mfma_i32_16x16x64_i8 v[24:27], v[180:183], v[214:217], v[24:27]
	v_mfma_i32_16x16x64_i8 v[20:23], v[188:191], v[214:217], v[20:23]
	v_mfma_i32_16x16x64_i8 v[8:11], v[180:183], v[226:229], v[8:11]
	v_mfma_i32_16x16x64_i8 v[4:7], v[188:191], v[226:229], v[4:7]
	s_setprio 0
	s_barrier
	s_add_i32 s38, s38, 2
	s_add_u32 s28, s28, 0x100
	s_addc_u32 s29, s29, 0
	s_cmp_gt_u32 s38, 29
	s_cbranch_scc0 .LBB0_783
	s_and_b64 vcc, exec, s[60:61]
	s_cbranch_vccz .LBB0_786
	s_barrier

; #define PG8_STAGE(bufoff, gbase, voff) do { _Pragma("unroll") for (int _i = 0; _i < 2; ++_i) \
;         __builtin_amdgcn_global_load_lds((const unsigned*)((const char*)(gbase) + (voff)[_i]), (LAS unsigned*)(lds + (bufoff) + ldsw + _i * 8192), 16, 0, 0); } while (0)
; #define PG8_LDA(dst, b, h) do { _Pragma("unroll") for (int m = 0; m < 4; ++m) _Pragma("unroll") for (int k = 0; k < 2; ++k) dst[m][k] = *(const LAS bf16x8*)(lds + PG8_SA(b, h) + aoff + m * 2048 + k * 1024); } while (0)
; #define PG8_LDB(dst, b, h) do { _Pragma("unroll") for (int n = 0; n < 2; ++n) _Pragma("unroll") for (int k = 0; k < 2; ++k) dst[n][k] = *(const LAS bf16x8*)(lds + PG8_SB(b, h) + boff + n * 2048 + k * 1024); } while (0)
; #define PG8_WAIT_V(n) asm volatile("s_waitcnt vmcnt(" #n ")" ::: "memory")
; #define PG8_WAIT_L(n) asm volatile("s_waitcnt lgkmcnt(" #n ")" ::: "memory")
; #define PG8_BAR __builtin_amdgcn_s_barrier()
; #define PG8_SCHED __builtin_amdgcn_sched_barrier(0)
;     ...
;         for (int t = 0; t < nt; t += 2) {
;             const bool last = (t == nt - 2);
;             const char* a1 = cA + (size_t)(t + 1) * kstep;
;             const char* a2 = last ? nA : cA + (size_t)(t + 2) * kstep; const char* b2 = last ? nB : cB + (size_t)(t + 2) * kstep;
;             const char* a3 = a2 + kstep; const char* b3 = b2 + kstep;
;             if constexpr (SP2) {
;             PG8_LDB(B0, 0, 0); PG8_LDB(B1, 0, 1); PG8_SCHED; PG8_LDA(At, 0, 0); PG8_STAGE(PG8_SA(1, 1), a1 + hstepA, voffA);
;             PG8_WAIT_V(8); PG8_WAIT_L(0); PG8_BAR; PG8_MMA(0, 0, At, B0); PG8_MMA(0, 1, At, B1); PG8_BAR; PG8_SCHED;
;             PG8_LDA(At, 0, 1); PG8_STAGE(PG8_SB(0, 0), b2, voffB); PG8_STAGE(PG8_SB(0, 1), b2 + hstepB, voffB); PG8_STAGE(PG8_SA(0, 0), a2, voffA);
;             PG8_WAIT_V(8); PG8_WAIT_L(0); PG8_BAR; PG8_MMA(1, 0, At, B0); PG8_MMA(1, 1, At, B1); PG8_BAR; PG8_SCHED;
.LBB0_818:
	s_add_i32 s43, 0, 0x10000
	v_lshl_add_u64 v[4:5], v[180:181], 0, s[28:29]
	s_cmpk_eq_i32 s28, 0xf00
	v_lshl_add_u64 v[4:5], v[4:5], 0, s[4:5]
	s_cselect_b64 vcc, -1, 0
	s_add_i32 s75, 0, 0x14000
	v_lshl_add_u64 v[6:7], v[186:187], 0, s[28:29]
	v_cndmask_b32_e32 v188, v4, v176, vcc
	v_add_u32_e32 v4, s43, v210
	v_add_u32_e32 v8, s75, v210
	v_cndmask_b32_e32 v189, v5, v177, vcc
	ds_read_b128 v[28:31], v4
	ds_read_b128 v[32:35], v4 offset:1024
	ds_read_b128 v[20:23], v4 offset:2048
	ds_read_b128 v[24:27], v4 offset:3072
	v_cndmask_b32_e32 v207, v7, v179, vcc
	v_cndmask_b32_e32 v206, v6, v178, vcc
	ds_read_b128 v[12:15], v8
	ds_read_b128 v[16:19], v8 offset:1024
	ds_read_b128 v[4:7], v8 offset:2048
	ds_read_b128 v[8:11], v8 offset:3072
	v_lshl_add_u64 v[234:235], v[184:185], 0, s[28:29]
	s_add_i32 m0, s57, 0xc000
	ds_read_b128 v[190:193], v212
	ds_read_b128 v[194:197], v212 offset:1024
	ds_read_b128 v[198:201], v212 offset:2048
	ds_read_b128 v[202:205], v212 offset:3072
	ds_read_b128 v[214:217], v212 offset:4096
	ds_read_b128 v[218:221], v212 offset:5120
	ds_read_b128 v[226:229], v212 offset:6144
	ds_read_b128 v[230:233], v212 offset:7168
	global_load_lds_dwordx4 v[234:235], off
	v_lshl_add_u64 v[234:235], v[182:183], 0, s[28:29]
	s_add_i32 m0, s57, 0xe000
	s_nop 0
	global_load_lds_dwordx4 v[234:235], off
	s_waitcnt vmcnt(8)
	s_waitcnt lgkmcnt(0)
	s_barrier
	s_setprio 1
	v_mfma_f32_16x16x128_f8f6f4 v[160:163], v[28:35], v[190:197], v[160:163]
	v_mfma_f32_16x16x128_f8f6f4 v[156:159], v[20:27], v[190:197], v[156:159]
	v_mfma_f32_16x16x128_f8f6f4 v[144:147], v[28:35], v[198:205], v[144:147]
	v_mfma_f32_16x16x128_f8f6f4 v[140:143], v[20:27], v[198:205], v[140:143]
	v_mfma_f32_16x16x128_f8f6f4 v[128:131], v[28:35], v[214:221], v[128:131]
	v_mfma_f32_16x16x128_f8f6f4 v[124:127], v[20:27], v[214:221], v[124:127]
	v_mfma_f32_16x16x128_f8f6f4 v[112:115], v[28:35], v[226:233], v[112:115]
	v_mfma_f32_16x16x128_f8f6f4 v[108:111], v[20:27], v[226:233], v[108:111]
	v_mfma_f32_16x16x128_f8f6f4 v[152:155], v[12:19], v[190:197], v[152:155]
	v_mfma_f32_16x16x128_f8f6f4 v[148:151], v[4:11], v[190:197], v[148:151]
	v_mfma_f32_16x16x128_f8f6f4 v[136:139], v[12:19], v[198:205], v[136:139]
	v_mfma_f32_16x16x128_f8f6f4 v[132:135], v[4:11], v[198:205], v[132:135]
	v_mfma_f32_16x16x128_f8f6f4 v[120:123], v[12:19], v[214:221], v[120:123]
	v_mfma_f32_16x16x128_f8f6f4 v[116:119], v[4:11], v[214:221], v[116:119]
	v_mfma_f32_16x16x128_f8f6f4 v[104:107], v[12:19], v[226:233], v[104:107]
	v_mfma_f32_16x16x128_f8f6f4 v[100:103], v[4:11], v[226:233], v[100:103]
	s_setprio 0
	s_barrier
	s_add_i32 s43, s43, s33
	v_lshl_add_u64 v[190:191], v[206:207], 0, v[2:3]
	s_mov_b32 m0, s43
	ds_read_b128 v[214:217], v212 offset:16384
	ds_read_b128 v[218:221], v212 offset:17408
	ds_read_b128 v[226:229], v212 offset:18432
	ds_read_b128 v[230:233], v212 offset:19456
	ds_read_b128 v[234:237], v212 offset:20480
	ds_read_b128 v[238:241], v212 offset:21504
	ds_read_b128 v[242:245], v212 offset:22528
	ds_read_b128 v[246:249], v212 offset:23552
	global_load_lds_dwordx4 v[190:191], off
	v_lshl_add_u64 v[192:193], v[206:207], 0, v[166:167]
	s_add_i32 m0, s43, 0x2000
	v_lshl_add_u64 v[196:197], v[206:207], 0, v[170:171]
	s_add_i32 s43, s75, s33
	global_load_lds_dwordx4 v[192:193], off
	v_lshl_add_u64 v[194:195], v[196:197], 0, v[2:3]
	s_mov_b32 m0, s43
	v_lshl_add_u64 v[196:197], v[196:197], 0, v[166:167]
	global_load_lds_dwordx4 v[194:195], off
	s_add_i32 m0, s43, 0x2000
	v_lshl_add_u64 v[198:199], v[188:189], 0, v[0:1]
	global_load_lds_dwordx4 v[196:197], off
	s_mov_b32 m0, s57
	v_lshl_add_u64 v[200:201], v[188:189], 0, v[164:165]
	global_load_lds_dwordx4 v[198:199], off
	s_mov_b32 m0, s62
	s_nop 0
	global_load_lds_dwordx4 v[200:201], off
	s_waitcnt vmcnt(8)
	s_waitcnt lgkmcnt(0)
	s_barrier
	s_setprio 1
	v_mfma_f32_16x16x128_f8f6f4 v[96:99], v[28:35], v[214:221], v[96:99]
	v_mfma_f32_16x16x128_f8f6f4 v[92:95], v[20:27], v[214:221], v[92:95]
	v_mfma_f32_16x16x128_f8f6f4 v[80:83], v[28:35], v[226:233], v[80:83]
	v_mfma_f32_16x16x128_f8f6f4 v[76:79], v[20:27], v[226:233], v[76:79]
	v_mfma_f32_16x16x128_f8f6f4 v[64:67], v[28:35], v[234:241], v[64:67]
	v_mfma_f32_16x16x128_f8f6f4 v[60:63], v[20:27], v[234:241], v[60:63]
	v_mfma_f32_16x16x128_f8f6f4 v[48:51], v[28:35], v[242:249], v[48:51]
	v_mfma_f32_16x16x128_f8f6f4 v[44:47], v[20:27], v[242:249], v[44:47]
	v_mfma_f32_16x16x128_f8f6f4 v[88:91], v[12:19], v[214:221], v[88:91]
	v_mfma_f32_16x16x128_f8f6f4 v[84:87], v[4:11], v[214:221], v[84:87]
	v_mfma_f32_16x16x128_f8f6f4 v[72:75], v[12:19], v[226:233], v[72:75]
	v_mfma_f32_16x16x128_f8f6f4 v[68:71], v[4:11], v[226:233], v[68:71]
	v_mfma_f32_16x16x128_f8f6f4 v[56:59], v[12:19], v[234:241], v[56:59]
	v_mfma_f32_16x16x128_f8f6f4 v[52:55], v[4:11], v[234:241], v[52:55]
	v_mfma_f32_16x16x128_f8f6f4 v[40:43], v[12:19], v[242:249], v[40:43]
	v_mfma_f32_16x16x128_f8f6f4 v[36:39], v[4:11], v[242:249], v[36:39]
	s_setprio 0
	s_barrier
; #define PG8_STAGE(bufoff, gbase, voff) do { _Pragma("unroll") for (int _i = 0; _i < 2; ++_i) \
;         __builtin_amdgcn_global_load_lds((const unsigned*)((const char*)(gbase) + (voff)[_i]), (LAS unsigned*)(lds + (bufoff) + ldsw + _i * 8192), 16, 0, 0); } while (0)
; #define PG8_LDA(dst, b, h) do { _Pragma("unroll") for (int m = 0; m < 4; ++m) _Pragma("unroll") for (int k = 0; k < 2; ++k) dst[m][k] = *(const LAS bf16x8*)(lds + PG8_SA(b, h) + aoff + m * 2048 + k * 1024); } while (0)
; #define PG8_LDB(dst, b, h) do { _Pragma("unroll") for (int n = 0; n < 2; ++n) _Pragma("unroll") for (int k = 0; k < 2; ++k) dst[n][k] = *(const LAS bf16x8*)(lds + PG8_SB(b, h) + boff + n * 2048 + k * 1024); } while (0)
; #define PG8_WAIT_V(n) asm volatile("s_waitcnt vmcnt(" #n ")" ::: "memory")
; #define PG8_WAIT_L(n) asm volatile("s_waitcnt lgkmcnt(" #n ")" ::: "memory")
; #define PG8_BAR __builtin_amdgcn_s_barrier()
; #define PG8_SCHED __builtin_amdgcn_sched_barrier(0)
;     ...
;             PG8_LDB(B0, 1, 0); PG8_LDB(B1, 1, 1); PG8_SCHED; PG8_LDA(At, 1, 0); PG8_STAGE(PG8_SA(0, 1), a2 + hstepA, voffA);
;             PG8_WAIT_V(8); PG8_WAIT_L(0); PG8_BAR; PG8_MMA(0, 0, At, B0); PG8_MMA(0, 1, At, B1); PG8_BAR; PG8_SCHED;
;             PG8_LDA(At, 1, 1); PG8_STAGE(PG8_SB(1, 0), b3, voffB); PG8_STAGE(PG8_SB(1, 1), b3 + hstepB, voffB); PG8_STAGE(PG8_SA(1, 0), a3, voffA);
;             PG8_WAIT_V(8); PG8_WAIT_L(0); PG8_BAR; PG8_MMA(1, 0, At, B0); PG8_MMA(1, 1, At, B1); PG8_BAR; PG8_SCHED;
	s_add_i32 s43, 0, 0x18000
	s_add_i32 s75, 0, 0x1c000
	v_add_u32_e32 v16, s43, v210
	v_add_u32_e32 v32, s75, v210
	ds_read_b128 v[4:7], v16
	ds_read_b128 v[8:11], v16 offset:1024
	ds_read_b128 v[12:15], v16 offset:2048
	ds_read_b128 v[16:19], v16 offset:3072
	ds_read_b128 v[20:23], v32
	ds_read_b128 v[24:27], v32 offset:1024
	ds_read_b128 v[28:31], v32 offset:2048
	ds_read_b128 v[32:35], v32 offset:3072
	v_lshl_add_u64 v[188:189], v[188:189], 0, v[168:169]
	s_mov_b32 m0, s63
	v_lshl_add_u64 v[202:203], v[188:189], 0, v[0:1]
	ds_read_b128 v[214:217], v212 offset:32768
	ds_read_b128 v[218:221], v212 offset:33792
	ds_read_b128 v[226:229], v212 offset:34816
	ds_read_b128 v[230:233], v212 offset:35840
	ds_read_b128 v[234:237], v212 offset:36864
	ds_read_b128 v[238:241], v212 offset:37888
	ds_read_b128 v[242:245], v212 offset:38912
	ds_read_b128 v[246:249], v212 offset:39936
	global_load_lds_dwordx4 v[202:203], off
	v_lshl_add_u64 v[188:189], v[188:189], 0, v[164:165]
	s_mov_b32 m0, s64
	s_nop 0
	global_load_lds_dwordx4 v[188:189], off
	s_waitcnt vmcnt(8)
	s_waitcnt lgkmcnt(0)
	s_barrier
	s_setprio 1
	v_mfma_f32_16x16x128_f8f6f4 v[160:163], v[4:11], v[214:221], v[160:163]
	v_mfma_f32_16x16x128_f8f6f4 v[156:159], v[12:19], v[214:221], v[156:159]
	v_mfma_f32_16x16x128_f8f6f4 v[144:147], v[4:11], v[226:233], v[144:147]
	v_mfma_f32_16x16x128_f8f6f4 v[140:143], v[12:19], v[226:233], v[140:143]
	v_mfma_f32_16x16x128_f8f6f4 v[128:131], v[4:11], v[234:241], v[128:131]
	v_mfma_f32_16x16x128_f8f6f4 v[124:127], v[12:19], v[234:241], v[124:127]
	v_mfma_f32_16x16x128_f8f6f4 v[112:115], v[4:11], v[242:249], v[112:115]
	v_mfma_f32_16x16x128_f8f6f4 v[108:111], v[12:19], v[242:249], v[108:111]
	v_mfma_f32_16x16x128_f8f6f4 v[152:155], v[20:27], v[214:221], v[152:155]
	v_mfma_f32_16x16x128_f8f6f4 v[148:151], v[28:35], v[214:221], v[148:151]
	v_mfma_f32_16x16x128_f8f6f4 v[136:139], v[20:27], v[226:233], v[136:139]
	v_mfma_f32_16x16x128_f8f6f4 v[132:135], v[28:35], v[226:233], v[132:135]
	v_mfma_f32_16x16x128_f8f6f4 v[120:123], v[20:27], v[234:241], v[120:123]
	v_mfma_f32_16x16x128_f8f6f4 v[116:119], v[28:35], v[234:241], v[116:119]
	v_mfma_f32_16x16x128_f8f6f4 v[104:107], v[20:27], v[242:249], v[104:107]
	v_mfma_f32_16x16x128_f8f6f4 v[100:103], v[28:35], v[242:249], v[100:103]
	s_setprio 0
	s_barrier
	s_add_i32 s43, s43, s33
	v_lshl_add_u64 v[188:189], v[190:191], 0, s[52:53]
	s_mov_b32 m0, s43
	ds_read_b128 v[214:217], v212 offset:49152
	ds_read_b128 v[218:221], v212 offset:50176
	ds_read_b128 v[226:229], v212 offset:51200
	ds_read_b128 v[230:233], v212 offset:52224
	ds_read_b128 v[234:237], v212 offset:53248
	ds_read_b128 v[238:241], v212 offset:54272
	ds_read_b128 v[242:245], v212 offset:55296
	ds_read_b128 v[246:249], v212 offset:56320
	global_load_lds_dwordx4 v[188:189], off
	v_lshl_add_u64 v[188:189], v[192:193], 0, s[52:53]
	s_add_i32 m0, s43, 0x2000
	s_add_i32 s43, s75, s33
	global_load_lds_dwordx4 v[188:189], off
	v_lshl_add_u64 v[188:189], v[194:195], 0, s[52:53]
	s_mov_b32 m0, s43
	s_nop 0
	global_load_lds_dwordx4 v[188:189], off
	v_lshl_add_u64 v[188:189], v[196:197], 0, s[52:53]
	s_add_i32 m0, s43, 0x2000
	s_nop 0
	global_load_lds_dwordx4 v[188:189], off
	v_lshl_add_u64 v[188:189], v[198:199], 0, s[52:53]
	s_mov_b32 m0, s65
	s_nop 0
	global_load_lds_dwordx4 v[188:189], off
	v_lshl_add_u64 v[188:189], v[200:201], 0, s[52:53]
	s_mov_b32 m0, s66
	s_nop 0
	global_load_lds_dwordx4 v[188:189], off
	s_waitcnt vmcnt(8)
	s_waitcnt lgkmcnt(0)
	s_barrier
	s_setprio 1
	v_mfma_f32_16x16x128_f8f6f4 v[96:99], v[4:11], v[214:221], v[96:99]
	v_mfma_f32_16x16x128_f8f6f4 v[92:95], v[12:19], v[214:221], v[92:95]
	v_mfma_f32_16x16x128_f8f6f4 v[80:83], v[4:11], v[226:233], v[80:83]
	v_mfma_f32_16x16x128_f8f6f4 v[76:79], v[12:19], v[226:233], v[76:79]
	v_mfma_f32_16x16x128_f8f6f4 v[64:67], v[4:11], v[234:241], v[64:67]
	v_mfma_f32_16x16x128_f8f6f4 v[60:63], v[12:19], v[234:241], v[60:63]
	v_mfma_f32_16x16x128_f8f6f4 v[48:51], v[4:11], v[242:249], v[48:51]
	v_mfma_f32_16x16x128_f8f6f4 v[44:47], v[12:19], v[242:249], v[44:47]
	v_mfma_f32_16x16x128_f8f6f4 v[88:91], v[20:27], v[214:221], v[88:91]
	v_mfma_f32_16x16x128_f8f6f4 v[84:87], v[28:35], v[214:221], v[84:87]
	v_mfma_f32_16x16x128_f8f6f4 v[72:75], v[20:27], v[226:233], v[72:75]
	v_mfma_f32_16x16x128_f8f6f4 v[68:71], v[28:35], v[226:233], v[68:71]
	v_mfma_f32_16x16x128_f8f6f4 v[56:59], v[20:27], v[234:241], v[56:59]
	v_mfma_f32_16x16x128_f8f6f4 v[52:55], v[28:35], v[234:241], v[52:55]
	v_mfma_f32_16x16x128_f8f6f4 v[40:43], v[20:27], v[242:249], v[40:43]
	v_mfma_f32_16x16x128_f8f6f4 v[36:39], v[28:35], v[242:249], v[36:39]
	s_setprio 0
	s_barrier
	s_add_i32 s42, s42, 2
	s_add_u32 s28, s28, 0x100
	s_addc_u32 s29, s29, 0
	s_cmp_gt_u32 s42, 29
	s_cbranch_scc0 .LBB0_818
	s_and_b64 vcc, exec, s[60:61]
	s_cbranch_vccz .LBB0_821
	s_barrier

; #define PG8_STAGE(bufoff, gbase, voff) do { _Pragma("unroll") for (int _i = 0; _i < 2; ++_i) \
;         __builtin_amdgcn_global_load_lds((const unsigned*)((const char*)(gbase) + (voff)[_i]), (LAS unsigned*)(lds + (bufoff) + ldsw + _i * 8192), 16, 0, 0); } while (0)
; #define PG8_LDA(dst, b, h) do { _Pragma("unroll") for (int m = 0; m < 4; ++m) _Pragma("unroll") for (int k = 0; k < 2; ++k) dst[m][k] = *(const LAS bf16x8*)(lds + PG8_SA(b, h) + aoff + m * 2048 + k * 1024); } while (0)
; #define PG8_LDB(dst, b, h) do { _Pragma("unroll") for (int n = 0; n < 2; ++n) _Pragma("unroll") for (int k = 0; k < 2; ++k) dst[n][k] = *(const LAS bf16x8*)(lds + PG8_SB(b, h) + boff + n * 2048 + k * 1024); } while (0)
; #define PG8_WAIT_V(n) asm volatile("s_waitcnt vmcnt(" #n ")" ::: "memory")
; #define PG8_WAIT_L(n) asm volatile("s_waitcnt lgkmcnt(" #n ")" ::: "memory")
; #define PG8_BAR __builtin_amdgcn_s_barrier()
; #define PG8_SCHED __builtin_amdgcn_sched_barrier(0)
;     ...
;         for (int t = 0; t < nt; t += 2) {
;             const bool last = (t == nt - 2);
;             const char* a1 = cA + (size_t)(t + 1) * kstep;
;             const char* a2 = last ? nA : cA + (size_t)(t + 2) * kstep; const char* b2 = last ? nB : cB + (size_t)(t + 2) * kstep;
;             const char* a3 = a2 + kstep; const char* b3 = b2 + kstep;
;             if constexpr (SP2) {
;             PG8_LDB(B0, 0, 0); PG8_LDB(B1, 0, 1); PG8_SCHED; PG8_LDA(At, 0, 0); PG8_STAGE(PG8_SA(1, 1), a1 + hstepA, voffA);
;             PG8_WAIT_V(8); PG8_WAIT_L(0); PG8_BAR; PG8_MMA(0, 0, At, B0); PG8_MMA(0, 1, At, B1); PG8_BAR; PG8_SCHED;
;             PG8_LDA(At, 0, 1); PG8_STAGE(PG8_SB(0, 0), b2, voffB); PG8_STAGE(PG8_SB(0, 1), b2 + hstepB, voffB); PG8_STAGE(PG8_SA(0, 0), a2, voffA);
;             PG8_WAIT_V(8); PG8_WAIT_L(0); PG8_BAR; PG8_MMA(1, 0, At, B0); PG8_MMA(1, 1, At, B1); PG8_BAR; PG8_SCHED;
.LBB0_912:
	s_add_i32 s59, 0, 0x10000
	v_lshl_add_u64 v[162:163], v[148:149], 0, s[38:39]
	s_cmpk_eq_i32 s38, 0xf00
	v_lshl_add_u64 v[162:163], v[162:163], 0, s[4:5]
	s_cselect_b64 vcc, -1, 0
	v_add_u32_e32 v161, s59, v158
	s_add_i32 s75, 0, 0x14000
	v_lshl_add_u64 v[178:179], v[154:155], 0, s[38:39]
	v_cndmask_b32_e32 v231, v163, v145, vcc
	v_cndmask_b32_e32 v230, v162, v144, vcc
	ds_read_b128 v[162:165], v161
	ds_read_b128 v[166:169], v161 offset:1024
	ds_read_b128 v[170:173], v161 offset:2048
	ds_read_b128 v[174:177], v161 offset:3072
	v_add_u32_e32 v161, s75, v158
	v_cndmask_b32_e32 v233, v179, v147, vcc
	v_cndmask_b32_e32 v232, v178, v146, vcc
	ds_read_b128 v[178:181], v161
	ds_read_b128 v[182:185], v161 offset:1024
	ds_read_b128 v[186:189], v161 offset:2048
	ds_read_b128 v[190:193], v161 offset:3072
	v_lshl_add_u64 v[234:235], v[152:153], 0, s[38:39]
	s_add_i32 m0, s60, 0xc000
	ds_read_b128 v[194:197], v160
	ds_read_b128 v[198:201], v160 offset:1024
	ds_read_b128 v[202:205], v160 offset:2048
	ds_read_b128 v[206:209], v160 offset:3072
	ds_read_b128 v[210:213], v160 offset:4096
	ds_read_b128 v[214:217], v160 offset:5120
	ds_read_b128 v[218:221], v160 offset:6144
	ds_read_b128 v[226:229], v160 offset:7168
	global_load_lds_dwordx4 v[234:235], off
	v_lshl_add_u64 v[234:235], v[150:151], 0, s[38:39]
	s_add_i32 m0, s60, 0xe000
	s_nop 0
	global_load_lds_dwordx4 v[234:235], off
	s_waitcnt vmcnt(8)
	s_waitcnt lgkmcnt(0)
	s_barrier
	s_setprio 1
	v_mfma_i32_16x16x64_i8 v[128:131], v[162:165], v[194:197], v[128:131]
	v_mfma_i32_16x16x64_i8 v[124:127], v[170:173], v[194:197], v[124:127]
	v_mfma_i32_16x16x64_i8 v[120:123], v[162:165], v[202:205], v[120:123]
	v_mfma_i32_16x16x64_i8 v[116:119], v[170:173], v[202:205], v[116:119]
	v_mfma_i32_16x16x64_i8 v[112:115], v[162:165], v[210:213], v[112:115]
	v_mfma_i32_16x16x64_i8 v[108:111], v[170:173], v[210:213], v[108:111]
	v_mfma_i32_16x16x64_i8 v[104:107], v[162:165], v[218:221], v[104:107]
	v_mfma_i32_16x16x64_i8 v[100:103], v[170:173], v[218:221], v[100:103]
	v_mfma_i32_16x16x64_i8 v[128:131], v[166:169], v[198:201], v[128:131]
	v_mfma_i32_16x16x64_i8 v[124:127], v[174:177], v[198:201], v[124:127]
	v_mfma_i32_16x16x64_i8 v[120:123], v[166:169], v[206:209], v[120:123]
	v_mfma_i32_16x16x64_i8 v[116:119], v[174:177], v[206:209], v[116:119]
	v_mfma_i32_16x16x64_i8 v[112:115], v[166:169], v[214:217], v[112:115]
	v_mfma_i32_16x16x64_i8 v[108:111], v[174:177], v[214:217], v[108:111]
	v_mfma_i32_16x16x64_i8 v[104:107], v[166:169], v[226:229], v[104:107]
	v_mfma_i32_16x16x64_i8 v[100:103], v[174:177], v[226:229], v[100:103]
	v_mfma_i32_16x16x64_i8 v[96:99], v[178:181], v[194:197], v[96:99]
	v_mfma_i32_16x16x64_i8 v[92:95], v[186:189], v[194:197], v[92:95]
	v_mfma_i32_16x16x64_i8 v[88:91], v[178:181], v[202:205], v[88:91]
	v_mfma_i32_16x16x64_i8 v[84:87], v[186:189], v[202:205], v[84:87]
	v_mfma_i32_16x16x64_i8 v[80:83], v[178:181], v[210:213], v[80:83]
	v_mfma_i32_16x16x64_i8 v[76:79], v[186:189], v[210:213], v[76:79]
	v_mfma_i32_16x16x64_i8 v[72:75], v[178:181], v[218:221], v[72:75]
	v_mfma_i32_16x16x64_i8 v[68:71], v[186:189], v[218:221], v[68:71]
	v_mfma_i32_16x16x64_i8 v[96:99], v[182:185], v[198:201], v[96:99]
	v_mfma_i32_16x16x64_i8 v[92:95], v[190:193], v[198:201], v[92:95]
	v_mfma_i32_16x16x64_i8 v[88:91], v[182:185], v[206:209], v[88:91]
	v_mfma_i32_16x16x64_i8 v[84:87], v[190:193], v[206:209], v[84:87]
	v_mfma_i32_16x16x64_i8 v[80:83], v[182:185], v[214:217], v[80:83]
	v_mfma_i32_16x16x64_i8 v[76:79], v[190:193], v[214:217], v[76:79]
	v_mfma_i32_16x16x64_i8 v[72:75], v[182:185], v[226:229], v[72:75]
	v_mfma_i32_16x16x64_i8 v[68:71], v[190:193], v[226:229], v[68:71]
	s_setprio 0
	s_barrier
	s_add_i32 s59, s59, s57
	v_lshl_add_u64 v[234:235], v[232:233], 0, v[2:3]
	s_mov_b32 m0, s59
	ds_read_b128 v[194:197], v160 offset:16384
	ds_read_b128 v[198:201], v160 offset:17408
	ds_read_b128 v[202:205], v160 offset:18432
	ds_read_b128 v[206:209], v160 offset:19456
	ds_read_b128 v[210:213], v160 offset:20480
	ds_read_b128 v[214:217], v160 offset:21504
	ds_read_b128 v[218:221], v160 offset:22528
	ds_read_b128 v[226:229], v160 offset:23552
	global_load_lds_dwordx4 v[234:235], off
	v_lshl_add_u64 v[236:237], v[232:233], 0, v[134:135]
	s_add_i32 m0, s59, 0x2000
	v_lshl_add_u64 v[232:233], v[232:233], 0, v[138:139]
	s_add_i32 s59, s75, s57
	global_load_lds_dwordx4 v[236:237], off
	v_lshl_add_u64 v[238:239], v[232:233], 0, v[2:3]
	s_mov_b32 m0, s59
	v_lshl_add_u64 v[232:233], v[232:233], 0, v[134:135]
	global_load_lds_dwordx4 v[238:239], off
	s_add_i32 m0, s59, 0x2000
	v_lshl_add_u64 v[240:241], v[230:231], 0, v[0:1]
	global_load_lds_dwordx4 v[232:233], off
	s_mov_b32 m0, s60
	v_lshl_add_u64 v[242:243], v[230:231], 0, v[132:133]
	global_load_lds_dwordx4 v[240:241], off
	s_mov_b32 m0, s61
	s_nop 0
	global_load_lds_dwordx4 v[242:243], off
	s_waitcnt vmcnt(8)
	s_waitcnt lgkmcnt(0)
	s_barrier
; #define PG8_STAGE(bufoff, gbase, voff) do { _Pragma("unroll") for (int _i = 0; _i < 2; ++_i) \
;         __builtin_amdgcn_global_load_lds((const unsigned*)((const char*)(gbase) + (voff)[_i]), (LAS unsigned*)(lds + (bufoff) + ldsw + _i * 8192), 16, 0, 0); } while (0)
; #define PG8_LDA(dst, b, h) do { _Pragma("unroll") for (int m = 0; m < 4; ++m) _Pragma("unroll") for (int k = 0; k < 2; ++k) dst[m][k] = *(const LAS bf16x8*)(lds + PG8_SA(b, h) + aoff + m * 2048 + k * 1024); } while (0)
; #define PG8_LDB(dst, b, h) do { _Pragma("unroll") for (int n = 0; n < 2; ++n) _Pragma("unroll") for (int k = 0; k < 2; ++k) dst[n][k] = *(const LAS bf16x8*)(lds + PG8_SB(b, h) + boff + n * 2048 + k * 1024); } while (0)
; #define PG8_WAIT_V(n) asm volatile("s_waitcnt vmcnt(" #n ")" ::: "memory")
; #define PG8_WAIT_L(n) asm volatile("s_waitcnt lgkmcnt(" #n ")" ::: "memory")
; #define PG8_BAR __builtin_amdgcn_s_barrier()
; #define PG8_SCHED __builtin_amdgcn_sched_barrier(0)
;     ...
;             PG8_WAIT_V(8); PG8_WAIT_L(0); PG8_BAR; PG8_MMA(1, 0, At, B0); PG8_MMA(1, 1, At, B1); PG8_BAR; PG8_SCHED;
;             PG8_LDB(B0, 1, 0); PG8_LDB(B1, 1, 1); PG8_SCHED; PG8_LDA(At, 1, 0); PG8_STAGE(PG8_SA(0, 1), a2 + hstepA, voffA);
;             PG8_WAIT_V(8); PG8_WAIT_L(0); PG8_BAR; PG8_MMA(0, 0, At, B0); PG8_MMA(0, 1, At, B1); PG8_BAR; PG8_SCHED;
	s_setprio 1
	v_mfma_i32_16x16x64_i8 v[64:67], v[162:165], v[194:197], v[64:67]
	v_mfma_i32_16x16x64_i8 v[60:63], v[170:173], v[194:197], v[60:63]
	v_mfma_i32_16x16x64_i8 v[56:59], v[162:165], v[202:205], v[56:59]
	v_mfma_i32_16x16x64_i8 v[52:55], v[170:173], v[202:205], v[52:55]
	v_mfma_i32_16x16x64_i8 v[48:51], v[162:165], v[210:213], v[48:51]
	v_mfma_i32_16x16x64_i8 v[44:47], v[170:173], v[210:213], v[44:47]
	v_mfma_i32_16x16x64_i8 v[40:43], v[162:165], v[218:221], v[40:43]
	v_mfma_i32_16x16x64_i8 v[36:39], v[170:173], v[218:221], v[36:39]
	v_mfma_i32_16x16x64_i8 v[64:67], v[166:169], v[198:201], v[64:67]
	v_mfma_i32_16x16x64_i8 v[60:63], v[174:177], v[198:201], v[60:63]
	v_mfma_i32_16x16x64_i8 v[56:59], v[166:169], v[206:209], v[56:59]
	v_mfma_i32_16x16x64_i8 v[52:55], v[174:177], v[206:209], v[52:55]
	v_mfma_i32_16x16x64_i8 v[48:51], v[166:169], v[214:217], v[48:51]
	v_mfma_i32_16x16x64_i8 v[44:47], v[174:177], v[214:217], v[44:47]
	v_mfma_i32_16x16x64_i8 v[40:43], v[166:169], v[226:229], v[40:43]
	v_mfma_i32_16x16x64_i8 v[36:39], v[174:177], v[226:229], v[36:39]
	v_mfma_i32_16x16x64_i8 v[32:35], v[178:181], v[194:197], v[32:35]
	v_mfma_i32_16x16x64_i8 v[28:31], v[186:189], v[194:197], v[28:31]
	v_mfma_i32_16x16x64_i8 v[24:27], v[178:181], v[202:205], v[24:27]
	v_mfma_i32_16x16x64_i8 v[20:23], v[186:189], v[202:205], v[20:23]
	v_mfma_i32_16x16x64_i8 v[16:19], v[178:181], v[210:213], v[16:19]
	v_mfma_i32_16x16x64_i8 v[12:15], v[186:189], v[210:213], v[12:15]
	v_mfma_i32_16x16x64_i8 v[8:11], v[178:181], v[218:221], v[8:11]
	v_mfma_i32_16x16x64_i8 v[4:7], v[186:189], v[218:221], v[4:7]
	v_mfma_i32_16x16x64_i8 v[32:35], v[182:185], v[198:201], v[32:35]
	v_mfma_i32_16x16x64_i8 v[28:31], v[190:193], v[198:201], v[28:31]
	v_mfma_i32_16x16x64_i8 v[24:27], v[182:185], v[206:209], v[24:27]
	v_mfma_i32_16x16x64_i8 v[20:23], v[190:193], v[206:209], v[20:23]
	v_mfma_i32_16x16x64_i8 v[16:19], v[182:185], v[214:217], v[16:19]
	v_mfma_i32_16x16x64_i8 v[12:15], v[190:193], v[214:217], v[12:15]
	v_mfma_i32_16x16x64_i8 v[8:11], v[182:185], v[226:229], v[8:11]
	v_mfma_i32_16x16x64_i8 v[4:7], v[190:193], v[226:229], v[4:7]
	s_setprio 0
	s_barrier
	s_add_i32 s59, 0, 0x18000
	v_add_u32_e32 v161, s59, v158
	s_add_i32 s75, 0, 0x1c000
	ds_read_b128 v[162:165], v161
	ds_read_b128 v[166:169], v161 offset:1024
	ds_read_b128 v[170:173], v161 offset:2048
	ds_read_b128 v[174:177], v161 offset:3072
	v_add_u32_e32 v161, s75, v158
	ds_read_b128 v[178:181], v161
	ds_read_b128 v[182:185], v161 offset:1024
	ds_read_b128 v[186:189], v161 offset:2048
	ds_read_b128 v[190:193], v161 offset:3072
	v_lshl_add_u64 v[230:231], v[230:231], 0, v[136:137]
	s_mov_b32 m0, s62
	v_lshl_add_u64 v[244:245], v[230:231], 0, v[0:1]
	ds_read_b128 v[194:197], v160 offset:32768
	ds_read_b128 v[198:201], v160 offset:33792
	ds_read_b128 v[202:205], v160 offset:34816
	ds_read_b128 v[206:209], v160 offset:35840
	ds_read_b128 v[210:213], v160 offset:36864
	ds_read_b128 v[214:217], v160 offset:37888
	ds_read_b128 v[218:221], v160 offset:38912
	ds_read_b128 v[226:229], v160 offset:39936
	global_load_lds_dwordx4 v[244:245], off
	v_lshl_add_u64 v[230:231], v[230:231], 0, v[132:133]
	s_mov_b32 m0, s63
	s_nop 0
	global_load_lds_dwordx4 v[230:231], off
	s_waitcnt vmcnt(8)
	s_waitcnt lgkmcnt(0)
	s_barrier
	s_setprio 1
	v_mfma_i32_16x16x64_i8 v[128:131], v[162:165], v[194:197], v[128:131]
	v_mfma_i32_16x16x64_i8 v[124:127], v[170:173], v[194:197], v[124:127]
	v_mfma_i32_16x16x64_i8 v[120:123], v[162:165], v[202:205], v[120:123]
	v_mfma_i32_16x16x64_i8 v[116:119], v[170:173], v[202:205], v[116:119]
	v_mfma_i32_16x16x64_i8 v[112:115], v[162:165], v[210:213], v[112:115]
	v_mfma_i32_16x16x64_i8 v[108:111], v[170:173], v[210:213], v[108:111]
	v_mfma_i32_16x16x64_i8 v[104:107], v[162:165], v[218:221], v[104:107]
	v_mfma_i32_16x16x64_i8 v[100:103], v[170:173], v[218:221], v[100:103]
	v_mfma_i32_16x16x64_i8 v[128:131], v[166:169], v[198:201], v[128:131]
	v_mfma_i32_16x16x64_i8 v[124:127], v[174:177], v[198:201], v[124:127]
	v_mfma_i32_16x16x64_i8 v[120:123], v[166:169], v[206:209], v[120:123]
	v_mfma_i32_16x16x64_i8 v[116:119], v[174:177], v[206:209], v[116:119]
	v_mfma_i32_16x16x64_i8 v[112:115], v[166:169], v[214:217], v[112:115]
	v_mfma_i32_16x16x64_i8 v[108:111], v[174:177], v[214:217], v[108:111]
	v_mfma_i32_16x16x64_i8 v[104:107], v[166:169], v[226:229], v[104:107]
	v_mfma_i32_16x16x64_i8 v[100:103], v[174:177], v[226:229], v[100:103]
	v_mfma_i32_16x16x64_i8 v[96:99], v[178:181], v[194:197], v[96:99]
	v_mfma_i32_16x16x64_i8 v[92:95], v[186:189], v[194:197], v[92:95]
	v_mfma_i32_16x16x64_i8 v[88:91], v[178:181], v[202:205], v[88:91]
	v_mfma_i32_16x16x64_i8 v[84:87], v[186:189], v[202:205], v[84:87]
	v_mfma_i32_16x16x64_i8 v[80:83], v[178:181], v[210:213], v[80:83]
	v_mfma_i32_16x16x64_i8 v[76:79], v[186:189], v[210:213], v[76:79]
	v_mfma_i32_16x16x64_i8 v[72:75], v[178:181], v[218:221], v[72:75]
	v_mfma_i32_16x16x64_i8 v[68:71], v[186:189], v[218:221], v[68:71]
	v_mfma_i32_16x16x64_i8 v[96:99], v[182:185], v[198:201], v[96:99]
	v_mfma_i32_16x16x64_i8 v[92:95], v[190:193], v[198:201], v[92:95]
	v_mfma_i32_16x16x64_i8 v[88:91], v[182:185], v[206:209], v[88:91]
	v_mfma_i32_16x16x64_i8 v[84:87], v[190:193], v[206:209], v[84:87]
	v_mfma_i32_16x16x64_i8 v[80:83], v[182:185], v[214:217], v[80:83]
	v_mfma_i32_16x16x64_i8 v[76:79], v[190:193], v[214:217], v[76:79]
	v_mfma_i32_16x16x64_i8 v[72:75], v[182:185], v[226:229], v[72:75]
	v_mfma_i32_16x16x64_i8 v[68:71], v[190:193], v[226:229], v[68:71]
	s_setprio 0
	s_barrier
; #define PG8_STAGE(bufoff, gbase, voff) do { _Pragma("unroll") for (int _i = 0; _i < 2; ++_i) \
;         __builtin_amdgcn_global_load_lds((const unsigned*)((const char*)(gbase) + (voff)[_i]), (LAS unsigned*)(lds + (bufoff) + ldsw + _i * 8192), 16, 0, 0); } while (0)
; #define PG8_LDA(dst, b, h) do { _Pragma("unroll") for (int m = 0; m < 4; ++m) _Pragma("unroll") for (int k = 0; k < 2; ++k) dst[m][k] = *(const LAS bf16x8*)(lds + PG8_SA(b, h) + aoff + m * 2048 + k * 1024); } while (0)
; #define PG8_WAIT_V(n) asm volatile("s_waitcnt vmcnt(" #n ")" ::: "memory")
; #define PG8_WAIT_L(n) asm volatile("s_waitcnt lgkmcnt(" #n ")" ::: "memory")
; #define PG8_BAR __builtin_amdgcn_s_barrier()
; #define PG8_SCHED __builtin_amdgcn_sched_barrier(0)
;     ...
;             PG8_LDA(At, 1, 1); PG8_STAGE(PG8_SB(1, 0), b3, voffB); PG8_STAGE(PG8_SB(1, 1), b3 + hstepB, voffB); PG8_STAGE(PG8_SA(1, 0), a3, voffA);
;             PG8_WAIT_V(8); PG8_WAIT_L(0); PG8_BAR; PG8_MMA(1, 0, At, B0); PG8_MMA(1, 1, At, B1); PG8_BAR; PG8_SCHED;
	s_add_i32 s59, s59, s57
	v_lshl_add_u64 v[230:231], v[234:235], 0, s[52:53]
	s_mov_b32 m0, s59
	ds_read_b128 v[194:197], v160 offset:49152
	ds_read_b128 v[198:201], v160 offset:50176
	ds_read_b128 v[202:205], v160 offset:51200
	ds_read_b128 v[206:209], v160 offset:52224
	ds_read_b128 v[210:213], v160 offset:53248
	ds_read_b128 v[214:217], v160 offset:54272
	ds_read_b128 v[218:221], v160 offset:55296
	ds_read_b128 v[226:229], v160 offset:56320
	global_load_lds_dwordx4 v[230:231], off
	v_lshl_add_u64 v[230:231], v[236:237], 0, s[52:53]
	s_add_i32 m0, s59, 0x2000
	s_add_i32 s59, s75, s57
	global_load_lds_dwordx4 v[230:231], off
	v_lshl_add_u64 v[230:231], v[238:239], 0, s[52:53]
	s_mov_b32 m0, s59
	s_nop 0
	global_load_lds_dwordx4 v[230:231], off
	v_lshl_add_u64 v[230:231], v[232:233], 0, s[52:53]
	s_add_i32 m0, s59, 0x2000
	s_nop 0
	global_load_lds_dwordx4 v[230:231], off
	v_lshl_add_u64 v[230:231], v[240:241], 0, s[52:53]
	s_mov_b32 m0, s64
	s_nop 0
	global_load_lds_dwordx4 v[230:231], off
	v_lshl_add_u64 v[230:231], v[242:243], 0, s[52:53]
	s_mov_b32 m0, s65
	s_nop 0
	global_load_lds_dwordx4 v[230:231], off
	s_waitcnt vmcnt(8)
	s_waitcnt lgkmcnt(0)
	s_barrier
	s_setprio 1
	v_mfma_i32_16x16x64_i8 v[64:67], v[162:165], v[194:197], v[64:67]
	v_mfma_i32_16x16x64_i8 v[60:63], v[170:173], v[194:197], v[60:63]
	v_mfma_i32_16x16x64_i8 v[56:59], v[162:165], v[202:205], v[56:59]
	v_mfma_i32_16x16x64_i8 v[52:55], v[170:173], v[202:205], v[52:55]
	v_mfma_i32_16x16x64_i8 v[48:51], v[162:165], v[210:213], v[48:51]
	v_mfma_i32_16x16x64_i8 v[44:47], v[170:173], v[210:213], v[44:47]
	v_mfma_i32_16x16x64_i8 v[40:43], v[162:165], v[218:221], v[40:43]
	v_mfma_i32_16x16x64_i8 v[36:39], v[170:173], v[218:221], v[36:39]
	v_mfma_i32_16x16x64_i8 v[64:67], v[166:169], v[198:201], v[64:67]
	v_mfma_i32_16x16x64_i8 v[60:63], v[174:177], v[198:201], v[60:63]
	v_mfma_i32_16x16x64_i8 v[56:59], v[166:169], v[206:209], v[56:59]
	v_mfma_i32_16x16x64_i8 v[52:55], v[174:177], v[206:209], v[52:55]
	v_mfma_i32_16x16x64_i8 v[48:51], v[166:169], v[214:217], v[48:51]
	v_mfma_i32_16x16x64_i8 v[44:47], v[174:177], v[214:217], v[44:47]
	v_mfma_i32_16x16x64_i8 v[40:43], v[166:169], v[226:229], v[40:43]
	v_mfma_i32_16x16x64_i8 v[36:39], v[174:177], v[226:229], v[36:39]
	v_mfma_i32_16x16x64_i8 v[32:35], v[178:181], v[194:197], v[32:35]
	v_mfma_i32_16x16x64_i8 v[28:31], v[186:189], v[194:197], v[28:31]
	v_mfma_i32_16x16x64_i8 v[24:27], v[178:181], v[202:205], v[24:27]
	v_mfma_i32_16x16x64_i8 v[20:23], v[186:189], v[202:205], v[20:23]
	v_mfma_i32_16x16x64_i8 v[16:19], v[178:181], v[210:213], v[16:19]
	v_mfma_i32_16x16x64_i8 v[12:15], v[186:189], v[210:213], v[12:15]
	v_mfma_i32_16x16x64_i8 v[8:11], v[178:181], v[218:221], v[8:11]
	v_mfma_i32_16x16x64_i8 v[4:7], v[186:189], v[218:221], v[4:7]
	v_mfma_i32_16x16x64_i8 v[32:35], v[182:185], v[198:201], v[32:35]
	v_mfma_i32_16x16x64_i8 v[28:31], v[190:193], v[198:201], v[28:31]
	v_mfma_i32_16x16x64_i8 v[24:27], v[182:185], v[206:209], v[24:27]
	v_mfma_i32_16x16x64_i8 v[20:23], v[190:193], v[206:209], v[20:23]
	v_mfma_i32_16x16x64_i8 v[16:19], v[182:185], v[214:217], v[16:19]
	v_mfma_i32_16x16x64_i8 v[12:15], v[190:193], v[214:217], v[12:15]
	v_mfma_i32_16x16x64_i8 v[8:11], v[182:185], v[226:229], v[8:11]
	v_mfma_i32_16x16x64_i8 v[4:7], v[190:193], v[226:229], v[4:7]
	s_setprio 0
	s_barrier
	s_add_i32 s58, s58, 2
	s_add_u32 s38, s38, 0x100
	s_addc_u32 s39, s39, 0
	s_cmp_gt_u32 s58, 29
	s_cbranch_scc0 .LBB0_912
	s_and_b64 vcc, exec, s[50:51]
	s_cbranch_vccz .LBB0_915
	s_barrier

; #define PG8_STAGE(bufoff, gbase, voff) do { _Pragma("unroll") for (int _i = 0; _i < 2; ++_i) \
;         __builtin_amdgcn_global_load_lds((const unsigned*)((const char*)(gbase) + (voff)[_i]), (LAS unsigned*)(lds + (bufoff) + ldsw + _i * 8192), 16, 0, 0); } while (0)
; #define PG8_LDA(dst, b, h) do { _Pragma("unroll") for (int m = 0; m < 4; ++m) _Pragma("unroll") for (int k = 0; k < 2; ++k) dst[m][k] = *(const LAS bf16x8*)(lds + PG8_SA(b, h) + aoff + m * 2048 + k * 1024); } while (0)
; #define PG8_LDB(dst, b, h) do { _Pragma("unroll") for (int n = 0; n < 2; ++n) _Pragma("unroll") for (int k = 0; k < 2; ++k) dst[n][k] = *(const LAS bf16x8*)(lds + PG8_SB(b, h) + boff + n * 2048 + k * 1024); } while (0)
; #define PG8_WAIT_V(n) asm volatile("s_waitcnt vmcnt(" #n ")" ::: "memory")
; #define PG8_WAIT_L(n) asm volatile("s_waitcnt lgkmcnt(" #n ")" ::: "memory")
; #define PG8_BAR __builtin_amdgcn_s_barrier()
; #define PG8_SCHED __builtin_amdgcn_sched_barrier(0)
;     ...
;         for (int t = 0; t < nt; t += 2) {
;             const bool last = (t == nt - 2);
;             const char* a1 = cA + (size_t)(t + 1) * kstep;
;             const char* a2 = last ? nA : cA + (size_t)(t + 2) * kstep; const char* b2 = last ? nB : cB + (size_t)(t + 2) * kstep;
;             const char* a3 = a2 + kstep; const char* b3 = b2 + kstep;
;             if constexpr (SP2) {
;             PG8_LDB(B0, 0, 0); PG8_LDB(B1, 0, 1); PG8_SCHED; PG8_LDA(At, 0, 0); PG8_STAGE(PG8_SA(1, 1), a1 + hstepA, voffA);
;             PG8_WAIT_V(8); PG8_WAIT_L(0); PG8_BAR; PG8_MMA(0, 0, At, B0); PG8_MMA(0, 1, At, B1); PG8_BAR; PG8_SCHED;
;             PG8_LDA(At, 0, 1); PG8_STAGE(PG8_SB(0, 0), b2, voffB); PG8_STAGE(PG8_SB(0, 1), b2 + hstepB, voffB); PG8_STAGE(PG8_SA(0, 0), a2, voffA);
;             PG8_WAIT_V(8); PG8_WAIT_L(0); PG8_BAR; PG8_MMA(1, 0, At, B0); PG8_MMA(1, 1, At, B1); PG8_BAR; PG8_SCHED;
.LBB0_1046:
	v_lshl_add_u64 v[168:169], v[152:153], 0, s[24:25]
	s_cmpk_eq_i32 s24, 0xf00
	v_lshl_add_u64 v[168:169], v[168:169], 0, s[20:21]
	v_lshl_add_u64 v[184:185], v[158:159], 0, s[24:25]
	s_cselect_b64 vcc, -1, 0
	v_cndmask_b32_e32 v233, v169, v149, vcc
	v_cndmask_b32_e32 v232, v168, v148, vcc
	ds_read_b128 v[168:171], v164
	ds_read_b128 v[172:175], v164 offset:1024
	ds_read_b128 v[176:179], v164 offset:2048
	ds_read_b128 v[180:183], v164 offset:3072
	v_cndmask_b32_e32 v235, v185, v151, vcc
	v_cndmask_b32_e32 v234, v184, v150, vcc
	ds_read_b128 v[184:187], v165
	ds_read_b128 v[188:191], v165 offset:1024
	ds_read_b128 v[192:195], v165 offset:2048
	ds_read_b128 v[196:199], v165 offset:3072
	s_mov_b32 m0, s44
	v_lshl_add_u64 v[236:237], v[156:157], 0, s[24:25]
	ds_read_b128 v[200:203], v166
	ds_read_b128 v[204:207], v166 offset:1024
	ds_read_b128 v[208:211], v166 offset:2048
	ds_read_b128 v[212:215], v166 offset:3072
	ds_read_b128 v[216:219], v166 offset:4096
	ds_read_b128 v[220:223], v166 offset:5120
	ds_read_b128 v[224:227], v166 offset:6144
	ds_read_b128 v[228:231], v166 offset:7168
	global_load_lds_dwordx4 v[236:237], off
	v_lshl_add_u64 v[236:237], v[154:155], 0, s[24:25]
	s_mov_b32 m0, s45
	s_nop 0
	global_load_lds_dwordx4 v[236:237], off
	s_waitcnt vmcnt(8)
	s_waitcnt lgkmcnt(0)
	s_barrier
	s_setprio 1
	v_mfma_i32_16x16x64_i8 v[124:127], v[168:171], v[200:203], v[124:127]
	v_mfma_i32_16x16x64_i8 v[120:123], v[176:179], v[200:203], v[120:123]
	v_mfma_i32_16x16x64_i8 v[116:119], v[168:171], v[208:211], v[116:119]
	v_mfma_i32_16x16x64_i8 v[112:115], v[176:179], v[208:211], v[112:115]
	v_mfma_i32_16x16x64_i8 v[108:111], v[168:171], v[216:219], v[108:111]
	v_mfma_i32_16x16x64_i8 v[104:107], v[176:179], v[216:219], v[104:107]
	v_mfma_i32_16x16x64_i8 v[100:103], v[168:171], v[224:227], v[100:103]
	v_mfma_i32_16x16x64_i8 v[96:99], v[176:179], v[224:227], v[96:99]
	v_mfma_i32_16x16x64_i8 v[124:127], v[172:175], v[204:207], v[124:127]
	v_mfma_i32_16x16x64_i8 v[120:123], v[180:183], v[204:207], v[120:123]
	v_mfma_i32_16x16x64_i8 v[116:119], v[172:175], v[212:215], v[116:119]
	v_mfma_i32_16x16x64_i8 v[112:115], v[180:183], v[212:215], v[112:115]
	v_mfma_i32_16x16x64_i8 v[108:111], v[172:175], v[220:223], v[108:111]
	v_mfma_i32_16x16x64_i8 v[104:107], v[180:183], v[220:223], v[104:107]
	v_mfma_i32_16x16x64_i8 v[100:103], v[172:175], v[228:231], v[100:103]
	v_mfma_i32_16x16x64_i8 v[96:99], v[180:183], v[228:231], v[96:99]
	v_mfma_i32_16x16x64_i8 v[92:95], v[184:187], v[200:203], v[92:95]
	v_mfma_i32_16x16x64_i8 v[88:91], v[192:195], v[200:203], v[88:91]
	v_mfma_i32_16x16x64_i8 v[84:87], v[184:187], v[208:211], v[84:87]
	v_mfma_i32_16x16x64_i8 v[80:83], v[192:195], v[208:211], v[80:83]
	v_mfma_i32_16x16x64_i8 v[76:79], v[184:187], v[216:219], v[76:79]
	v_mfma_i32_16x16x64_i8 v[72:75], v[192:195], v[216:219], v[72:75]
	v_mfma_i32_16x16x64_i8 v[68:71], v[184:187], v[224:227], v[68:71]
	v_mfma_i32_16x16x64_i8 v[64:67], v[192:195], v[224:227], v[64:67]
	v_mfma_i32_16x16x64_i8 v[92:95], v[188:191], v[204:207], v[92:95]
	v_mfma_i32_16x16x64_i8 v[88:91], v[196:199], v[204:207], v[88:91]
	v_mfma_i32_16x16x64_i8 v[84:87], v[188:191], v[212:215], v[84:87]
	v_mfma_i32_16x16x64_i8 v[80:83], v[196:199], v[212:215], v[80:83]
	v_mfma_i32_16x16x64_i8 v[76:79], v[188:191], v[220:223], v[76:79]
	v_mfma_i32_16x16x64_i8 v[72:75], v[196:199], v[220:223], v[72:75]
	v_mfma_i32_16x16x64_i8 v[68:71], v[188:191], v[228:231], v[68:71]
	v_mfma_i32_16x16x64_i8 v[64:67], v[196:199], v[228:231], v[64:67]
	s_setprio 0
	s_barrier
	s_mov_b32 m0, s46
	v_lshl_add_u64 v[236:237], v[234:235], 0, v[136:137]
	ds_read_b128 v[200:203], v166 offset:16384
	ds_read_b128 v[204:207], v166 offset:17408
	ds_read_b128 v[208:211], v166 offset:18432
	ds_read_b128 v[212:215], v166 offset:19456
	ds_read_b128 v[216:219], v166 offset:20480
	ds_read_b128 v[220:223], v166 offset:21504
	ds_read_b128 v[224:227], v166 offset:22528
	ds_read_b128 v[228:231], v166 offset:23552
	global_load_lds_dwordx4 v[236:237], off
	v_lshl_add_u64 v[238:239], v[234:235], 0, v[132:133]
	s_add_i32 m0, s46, 0x2000
	v_lshl_add_u64 v[234:235], v[234:235], 0, v[130:131]
	s_add_i32 s39, s43, s2
	global_load_lds_dwordx4 v[238:239], off
	v_lshl_add_u64 v[240:241], v[234:235], 0, v[136:137]
	s_mov_b32 m0, s39
	v_lshl_add_u64 v[234:235], v[234:235], 0, v[132:133]
	global_load_lds_dwordx4 v[240:241], off
	s_add_i32 m0, s39, 0x2000
	v_lshl_add_u64 v[242:243], v[232:233], 0, v[138:139]
	global_load_lds_dwordx4 v[234:235], off
	s_mov_b32 m0, s26
	v_lshl_add_u64 v[244:245], v[232:233], 0, v[134:135]
	global_load_lds_dwordx4 v[242:243], off
	s_mov_b32 m0, s27
	s_nop 0
	global_load_lds_dwordx4 v[244:245], off
	s_waitcnt vmcnt(8)
	s_waitcnt lgkmcnt(0)
	s_barrier
; #define PG8_STAGE(bufoff, gbase, voff) do { _Pragma("unroll") for (int _i = 0; _i < 2; ++_i) \
;         __builtin_amdgcn_global_load_lds((const unsigned*)((const char*)(gbase) + (voff)[_i]), (LAS unsigned*)(lds + (bufoff) + ldsw + _i * 8192), 16, 0, 0); } while (0)
; #define PG8_LDA(dst, b, h) do { _Pragma("unroll") for (int m = 0; m < 4; ++m) _Pragma("unroll") for (int k = 0; k < 2; ++k) dst[m][k] = *(const LAS bf16x8*)(lds + PG8_SA(b, h) + aoff + m * 2048 + k * 1024); } while (0)
; #define PG8_LDB(dst, b, h) do { _Pragma("unroll") for (int n = 0; n < 2; ++n) _Pragma("unroll") for (int k = 0; k < 2; ++k) dst[n][k] = *(const LAS bf16x8*)(lds + PG8_SB(b, h) + boff + n * 2048 + k * 1024); } while (0)
; #define PG8_WAIT_V(n) asm volatile("s_waitcnt vmcnt(" #n ")" ::: "memory")
; #define PG8_WAIT_L(n) asm volatile("s_waitcnt lgkmcnt(" #n ")" ::: "memory")
; #define PG8_BAR __builtin_amdgcn_s_barrier()
; #define PG8_SCHED __builtin_amdgcn_sched_barrier(0)
;     ...
;             PG8_WAIT_V(8); PG8_WAIT_L(0); PG8_BAR; PG8_MMA(1, 0, At, B0); PG8_MMA(1, 1, At, B1); PG8_BAR; PG8_SCHED;
;             PG8_LDB(B0, 1, 0); PG8_LDB(B1, 1, 1); PG8_SCHED; PG8_LDA(At, 1, 0); PG8_STAGE(PG8_SA(0, 1), a2 + hstepA, voffA);
;             PG8_WAIT_V(8); PG8_WAIT_L(0); PG8_BAR; PG8_MMA(0, 0, At, B0); PG8_MMA(0, 1, At, B1); PG8_BAR; PG8_SCHED;
	s_setprio 1
	v_mfma_i32_16x16x64_i8 v[60:63], v[168:171], v[200:203], v[60:63]
	v_mfma_i32_16x16x64_i8 v[56:59], v[176:179], v[200:203], v[56:59]
	v_mfma_i32_16x16x64_i8 v[52:55], v[168:171], v[208:211], v[52:55]
	v_mfma_i32_16x16x64_i8 v[48:51], v[176:179], v[208:211], v[48:51]
	v_mfma_i32_16x16x64_i8 v[44:47], v[168:171], v[216:219], v[44:47]
	v_mfma_i32_16x16x64_i8 v[40:43], v[176:179], v[216:219], v[40:43]
	v_mfma_i32_16x16x64_i8 v[36:39], v[168:171], v[224:227], v[36:39]
	v_mfma_i32_16x16x64_i8 v[32:35], v[176:179], v[224:227], v[32:35]
	v_mfma_i32_16x16x64_i8 v[60:63], v[172:175], v[204:207], v[60:63]
	v_mfma_i32_16x16x64_i8 v[56:59], v[180:183], v[204:207], v[56:59]
	v_mfma_i32_16x16x64_i8 v[52:55], v[172:175], v[212:215], v[52:55]
	v_mfma_i32_16x16x64_i8 v[48:51], v[180:183], v[212:215], v[48:51]
	v_mfma_i32_16x16x64_i8 v[44:47], v[172:175], v[220:223], v[44:47]
	v_mfma_i32_16x16x64_i8 v[40:43], v[180:183], v[220:223], v[40:43]
	v_mfma_i32_16x16x64_i8 v[36:39], v[172:175], v[228:231], v[36:39]
	v_mfma_i32_16x16x64_i8 v[32:35], v[180:183], v[228:231], v[32:35]
	v_mfma_i32_16x16x64_i8 v[28:31], v[184:187], v[200:203], v[28:31]
	v_mfma_i32_16x16x64_i8 v[24:27], v[192:195], v[200:203], v[24:27]
	v_mfma_i32_16x16x64_i8 v[20:23], v[184:187], v[208:211], v[20:23]
	v_mfma_i32_16x16x64_i8 v[16:19], v[192:195], v[208:211], v[16:19]
	v_mfma_i32_16x16x64_i8 v[12:15], v[184:187], v[216:219], v[12:15]
	v_mfma_i32_16x16x64_i8 v[8:11], v[192:195], v[216:219], v[8:11]
	v_mfma_i32_16x16x64_i8 v[4:7], v[184:187], v[224:227], v[4:7]
	v_mfma_i32_16x16x64_i8 v[0:3], v[192:195], v[224:227], v[0:3]
	v_mfma_i32_16x16x64_i8 v[28:31], v[188:191], v[204:207], v[28:31]
	v_mfma_i32_16x16x64_i8 v[24:27], v[196:199], v[204:207], v[24:27]
	v_mfma_i32_16x16x64_i8 v[20:23], v[188:191], v[212:215], v[20:23]
	v_mfma_i32_16x16x64_i8 v[16:19], v[196:199], v[212:215], v[16:19]
	v_mfma_i32_16x16x64_i8 v[12:15], v[188:191], v[220:223], v[12:15]
	v_mfma_i32_16x16x64_i8 v[8:11], v[196:199], v[220:223], v[8:11]
	v_mfma_i32_16x16x64_i8 v[4:7], v[188:191], v[228:231], v[4:7]
	v_mfma_i32_16x16x64_i8 v[0:3], v[196:199], v[228:231], v[0:3]
	s_setprio 0
	s_barrier
	s_add_i32 s39, 0, 0x18000
	v_add_u32_e32 v167, s39, v162
	s_add_i32 s51, 0, 0x1c000
	ds_read_b128 v[168:171], v167
	ds_read_b128 v[172:175], v167 offset:1024
	ds_read_b128 v[176:179], v167 offset:2048
	ds_read_b128 v[180:183], v167 offset:3072
	v_add_u32_e32 v167, s51, v162
	ds_read_b128 v[184:187], v167
	ds_read_b128 v[188:191], v167 offset:1024
	ds_read_b128 v[192:195], v167 offset:2048
	ds_read_b128 v[196:199], v167 offset:3072
	v_lshl_add_u64 v[232:233], v[232:233], 0, v[128:129]
	s_mov_b32 m0, s28
	v_lshl_add_u64 v[246:247], v[232:233], 0, v[138:139]
	ds_read_b128 v[200:203], v166 offset:32768
	ds_read_b128 v[204:207], v166 offset:33792
	ds_read_b128 v[208:211], v166 offset:34816
	ds_read_b128 v[212:215], v166 offset:35840
	ds_read_b128 v[216:219], v166 offset:36864
	ds_read_b128 v[220:223], v166 offset:37888
	ds_read_b128 v[224:227], v166 offset:38912
	ds_read_b128 v[228:231], v166 offset:39936
	global_load_lds_dwordx4 v[246:247], off
	v_lshl_add_u64 v[232:233], v[232:233], 0, v[134:135]
	s_mov_b32 m0, s29
	s_nop 0
	global_load_lds_dwordx4 v[232:233], off
	s_waitcnt vmcnt(8)
	s_waitcnt lgkmcnt(0)
	s_barrier
	s_setprio 1
	v_mfma_i32_16x16x64_i8 v[124:127], v[168:171], v[200:203], v[124:127]
	v_mfma_i32_16x16x64_i8 v[120:123], v[176:179], v[200:203], v[120:123]
	v_mfma_i32_16x16x64_i8 v[116:119], v[168:171], v[208:211], v[116:119]
	v_mfma_i32_16x16x64_i8 v[112:115], v[176:179], v[208:211], v[112:115]
	v_mfma_i32_16x16x64_i8 v[108:111], v[168:171], v[216:219], v[108:111]
	v_mfma_i32_16x16x64_i8 v[104:107], v[176:179], v[216:219], v[104:107]
	v_mfma_i32_16x16x64_i8 v[100:103], v[168:171], v[224:227], v[100:103]
	v_mfma_i32_16x16x64_i8 v[96:99], v[176:179], v[224:227], v[96:99]
	v_mfma_i32_16x16x64_i8 v[124:127], v[172:175], v[204:207], v[124:127]
	v_mfma_i32_16x16x64_i8 v[120:123], v[180:183], v[204:207], v[120:123]
	v_mfma_i32_16x16x64_i8 v[116:119], v[172:175], v[212:215], v[116:119]
	v_mfma_i32_16x16x64_i8 v[112:115], v[180:183], v[212:215], v[112:115]
	v_mfma_i32_16x16x64_i8 v[108:111], v[172:175], v[220:223], v[108:111]
	v_mfma_i32_16x16x64_i8 v[104:107], v[180:183], v[220:223], v[104:107]
	v_mfma_i32_16x16x64_i8 v[100:103], v[172:175], v[228:231], v[100:103]
	v_mfma_i32_16x16x64_i8 v[96:99], v[180:183], v[228:231], v[96:99]
	v_mfma_i32_16x16x64_i8 v[92:95], v[184:187], v[200:203], v[92:95]
	v_mfma_i32_16x16x64_i8 v[88:91], v[192:195], v[200:203], v[88:91]
	v_mfma_i32_16x16x64_i8 v[84:87], v[184:187], v[208:211], v[84:87]
	v_mfma_i32_16x16x64_i8 v[80:83], v[192:195], v[208:211], v[80:83]
	v_mfma_i32_16x16x64_i8 v[76:79], v[184:187], v[216:219], v[76:79]
	v_mfma_i32_16x16x64_i8 v[72:75], v[192:195], v[216:219], v[72:75]
	v_mfma_i32_16x16x64_i8 v[68:71], v[184:187], v[224:227], v[68:71]
	v_mfma_i32_16x16x64_i8 v[64:67], v[192:195], v[224:227], v[64:67]
	v_mfma_i32_16x16x64_i8 v[92:95], v[188:191], v[204:207], v[92:95]
	v_mfma_i32_16x16x64_i8 v[88:91], v[196:199], v[204:207], v[88:91]
	v_mfma_i32_16x16x64_i8 v[84:87], v[188:191], v[212:215], v[84:87]
	v_mfma_i32_16x16x64_i8 v[80:83], v[196:199], v[212:215], v[80:83]
	v_mfma_i32_16x16x64_i8 v[76:79], v[188:191], v[220:223], v[76:79]
	v_mfma_i32_16x16x64_i8 v[72:75], v[196:199], v[220:223], v[72:75]
	v_mfma_i32_16x16x64_i8 v[68:71], v[188:191], v[228:231], v[68:71]
	v_mfma_i32_16x16x64_i8 v[64:67], v[196:199], v[228:231], v[64:67]
	s_setprio 0
	s_barrier
; #define PG8_STAGE(bufoff, gbase, voff) do { _Pragma("unroll") for (int _i = 0; _i < 2; ++_i) \
;         __builtin_amdgcn_global_load_lds((const unsigned*)((const char*)(gbase) + (voff)[_i]), (LAS unsigned*)(lds + (bufoff) + ldsw + _i * 8192), 16, 0, 0); } while (0)
; #define PG8_LDA(dst, b, h) do { _Pragma("unroll") for (int m = 0; m < 4; ++m) _Pragma("unroll") for (int k = 0; k < 2; ++k) dst[m][k] = *(const LAS bf16x8*)(lds + PG8_SA(b, h) + aoff + m * 2048 + k * 1024); } while (0)
; #define PG8_WAIT_V(n) asm volatile("s_waitcnt vmcnt(" #n ")" ::: "memory")
; #define PG8_WAIT_L(n) asm volatile("s_waitcnt lgkmcnt(" #n ")" ::: "memory")
; #define PG8_BAR __builtin_amdgcn_s_barrier()
; #define PG8_SCHED __builtin_amdgcn_sched_barrier(0)
;     ...
;             PG8_LDA(At, 1, 1); PG8_STAGE(PG8_SB(1, 0), b3, voffB); PG8_STAGE(PG8_SB(1, 1), b3 + hstepB, voffB); PG8_STAGE(PG8_SA(1, 0), a3, voffA);
;             PG8_WAIT_V(8); PG8_WAIT_L(0); PG8_BAR; PG8_MMA(1, 0, At, B0); PG8_MMA(1, 1, At, B1); PG8_BAR; PG8_SCHED;
	s_add_i32 s39, s39, s2
	v_lshl_add_u64 v[232:233], v[236:237], 0, s[16:17]
	s_mov_b32 m0, s39
	ds_read_b128 v[200:203], v166 offset:49152
	ds_read_b128 v[204:207], v166 offset:50176
	ds_read_b128 v[208:211], v166 offset:51200
	ds_read_b128 v[212:215], v166 offset:52224
	ds_read_b128 v[216:219], v166 offset:53248
	ds_read_b128 v[220:223], v166 offset:54272
	ds_read_b128 v[224:227], v166 offset:55296
	ds_read_b128 v[228:231], v166 offset:56320
	global_load_lds_dwordx4 v[232:233], off
	v_lshl_add_u64 v[232:233], v[238:239], 0, s[16:17]
	s_add_i32 m0, s39, 0x2000
	s_add_i32 s39, s51, s2
	global_load_lds_dwordx4 v[232:233], off
	v_lshl_add_u64 v[232:233], v[240:241], 0, s[16:17]
	s_mov_b32 m0, s39
	s_nop 0
	global_load_lds_dwordx4 v[232:233], off
	v_lshl_add_u64 v[232:233], v[234:235], 0, s[16:17]
	s_add_i32 m0, s39, 0x2000
	s_nop 0
	global_load_lds_dwordx4 v[232:233], off
	v_lshl_add_u64 v[232:233], v[242:243], 0, s[16:17]
	s_mov_b32 m0, s40
	s_nop 0
	global_load_lds_dwordx4 v[232:233], off
	v_lshl_add_u64 v[232:233], v[244:245], 0, s[16:17]
	s_mov_b32 m0, s41
	s_nop 0
	global_load_lds_dwordx4 v[232:233], off
	s_waitcnt vmcnt(8)
	s_waitcnt lgkmcnt(0)
	s_barrier
	s_setprio 1
	v_mfma_i32_16x16x64_i8 v[60:63], v[168:171], v[200:203], v[60:63]
	v_mfma_i32_16x16x64_i8 v[56:59], v[176:179], v[200:203], v[56:59]
	v_mfma_i32_16x16x64_i8 v[52:55], v[168:171], v[208:211], v[52:55]
	v_mfma_i32_16x16x64_i8 v[48:51], v[176:179], v[208:211], v[48:51]
	v_mfma_i32_16x16x64_i8 v[44:47], v[168:171], v[216:219], v[44:47]
	v_mfma_i32_16x16x64_i8 v[40:43], v[176:179], v[216:219], v[40:43]
	v_mfma_i32_16x16x64_i8 v[36:39], v[168:171], v[224:227], v[36:39]
	v_mfma_i32_16x16x64_i8 v[32:35], v[176:179], v[224:227], v[32:35]
	v_mfma_i32_16x16x64_i8 v[60:63], v[172:175], v[204:207], v[60:63]
	v_mfma_i32_16x16x64_i8 v[56:59], v[180:183], v[204:207], v[56:59]
	v_mfma_i32_16x16x64_i8 v[52:55], v[172:175], v[212:215], v[52:55]
	v_mfma_i32_16x16x64_i8 v[48:51], v[180:183], v[212:215], v[48:51]
	v_mfma_i32_16x16x64_i8 v[44:47], v[172:175], v[220:223], v[44:47]
	v_mfma_i32_16x16x64_i8 v[40:43], v[180:183], v[220:223], v[40:43]
	v_mfma_i32_16x16x64_i8 v[36:39], v[172:175], v[228:231], v[36:39]
	v_mfma_i32_16x16x64_i8 v[32:35], v[180:183], v[228:231], v[32:35]
	v_mfma_i32_16x16x64_i8 v[28:31], v[184:187], v[200:203], v[28:31]
	v_mfma_i32_16x16x64_i8 v[24:27], v[192:195], v[200:203], v[24:27]
	v_mfma_i32_16x16x64_i8 v[20:23], v[184:187], v[208:211], v[20:23]
	v_mfma_i32_16x16x64_i8 v[16:19], v[192:195], v[208:211], v[16:19]
	v_mfma_i32_16x16x64_i8 v[12:15], v[184:187], v[216:219], v[12:15]
	v_mfma_i32_16x16x64_i8 v[8:11], v[192:195], v[216:219], v[8:11]
	v_mfma_i32_16x16x64_i8 v[4:7], v[184:187], v[224:227], v[4:7]
	v_mfma_i32_16x16x64_i8 v[0:3], v[192:195], v[224:227], v[0:3]
	v_mfma_i32_16x16x64_i8 v[28:31], v[188:191], v[204:207], v[28:31]
	v_mfma_i32_16x16x64_i8 v[24:27], v[196:199], v[204:207], v[24:27]
	v_mfma_i32_16x16x64_i8 v[20:23], v[188:191], v[212:215], v[20:23]
	v_mfma_i32_16x16x64_i8 v[16:19], v[196:199], v[212:215], v[16:19]
	v_mfma_i32_16x16x64_i8 v[12:15], v[188:191], v[220:223], v[12:15]
	v_mfma_i32_16x16x64_i8 v[8:11], v[196:199], v[220:223], v[8:11]
	v_mfma_i32_16x16x64_i8 v[4:7], v[188:191], v[228:231], v[4:7]
	v_mfma_i32_16x16x64_i8 v[0:3], v[196:199], v[228:231], v[0:3]
	s_setprio 0
	s_barrier
	s_add_i32 s38, s38, 2
	s_add_u32 s24, s24, 0x100
	s_addc_u32 s25, s25, 0
	s_cmp_gt_u32 s38, 29
	s_cbranch_scc0 .LBB0_1046
	s_and_b64 vcc, exec, s[18:19]
	s_cbranch_vccz .LBB0_1049
	s_barrier

; #define PG8_STAGE(bufoff, gbase, voff) do { _Pragma("unroll") for (int _i = 0; _i < 2; ++_i) \
;         __builtin_amdgcn_global_load_lds((const unsigned*)((const char*)(gbase) + (voff)[_i]), (LAS unsigned*)(lds + (bufoff) + ldsw + _i * 8192), 16, 0, 0); } while (0)
; #define PG8_LDA(dst, b, h) do { _Pragma("unroll") for (int m = 0; m < 4; ++m) _Pragma("unroll") for (int k = 0; k < 2; ++k) dst[m][k] = *(const LAS bf16x8*)(lds + PG8_SA(b, h) + aoff + m * 2048 + k * 1024); } while (0)
; #define PG8_LDB(dst, b, h) do { _Pragma("unroll") for (int n = 0; n < 2; ++n) _Pragma("unroll") for (int k = 0; k < 2; ++k) dst[n][k] = *(const LAS bf16x8*)(lds + PG8_SB(b, h) + boff + n * 2048 + k * 1024); } while (0)
; #define PG8_WAIT_V(n) asm volatile("s_waitcnt vmcnt(" #n ")" ::: "memory")
; #define PG8_WAIT_L(n) asm volatile("s_waitcnt lgkmcnt(" #n ")" ::: "memory")
; #define PG8_BAR __builtin_amdgcn_s_barrier()
; #define PG8_SCHED __builtin_amdgcn_sched_barrier(0)
;     ...
;         for (int t = 0; t < nt; t += 2) {
;             const bool last = (t == nt - 2);
;             const char* a1 = cA + (size_t)(t + 1) * kstep;
;             const char* a2 = last ? nA : cA + (size_t)(t + 2) * kstep; const char* b2 = last ? nB : cB + (size_t)(t + 2) * kstep;
;             const char* a3 = a2 + kstep; const char* b3 = b2 + kstep;
;             if constexpr (SP2) {
;             PG8_LDB(B0, 0, 0); PG8_LDB(B1, 0, 1); PG8_SCHED; PG8_LDA(At, 0, 0); PG8_STAGE(PG8_SA(1, 1), a1 + hstepA, voffA);
;             PG8_WAIT_V(8); PG8_WAIT_L(0); PG8_BAR; PG8_MMA(0, 0, At, B0); PG8_MMA(0, 1, At, B1); PG8_BAR; PG8_SCHED;
;             PG8_LDA(At, 0, 1); PG8_STAGE(PG8_SB(0, 0), b2, voffB); PG8_STAGE(PG8_SB(0, 1), b2 + hstepB, voffB); PG8_STAGE(PG8_SA(0, 0), a2, voffA);
;             PG8_WAIT_V(8); PG8_WAIT_L(0); PG8_BAR; PG8_MMA(1, 0, At, B0); PG8_MMA(1, 1, At, B1); PG8_BAR; PG8_SCHED;
.LBB0_1066:
	v_lshl_add_u64 v[168:169], v[152:153], 0, s[18:19]
	s_cmpk_eq_i32 s18, 0x1f00
	v_lshl_add_u64 v[168:169], v[168:169], 0, s[16:17]
	v_lshl_add_u64 v[184:185], v[158:159], 0, s[18:19]
	s_cselect_b64 vcc, -1, 0
	v_cndmask_b32_e32 v233, v169, v149, vcc
	v_cndmask_b32_e32 v232, v168, v148, vcc
	ds_read_b128 v[168:171], v164
	ds_read_b128 v[172:175], v164 offset:1024
	ds_read_b128 v[176:179], v164 offset:2048
	ds_read_b128 v[180:183], v164 offset:3072
	v_cndmask_b32_e32 v235, v185, v151, vcc
	v_cndmask_b32_e32 v234, v184, v150, vcc
	ds_read_b128 v[184:187], v165
	ds_read_b128 v[188:191], v165 offset:1024
	ds_read_b128 v[192:195], v165 offset:2048
	ds_read_b128 v[196:199], v165 offset:3072
	s_mov_b32 m0, s35
	v_lshl_add_u64 v[236:237], v[156:157], 0, s[18:19]
	ds_read_b128 v[200:203], v166
	ds_read_b128 v[204:207], v166 offset:1024
	ds_read_b128 v[208:211], v166 offset:2048
	ds_read_b128 v[212:215], v166 offset:3072
	ds_read_b128 v[216:219], v166 offset:4096
	ds_read_b128 v[220:223], v166 offset:5120
	ds_read_b128 v[224:227], v166 offset:6144
	ds_read_b128 v[228:231], v166 offset:7168
	global_load_lds_dwordx4 v[236:237], off
	v_lshl_add_u64 v[236:237], v[154:155], 0, s[18:19]
	s_mov_b32 m0, s40
	s_nop 0
	global_load_lds_dwordx4 v[236:237], off
	s_waitcnt vmcnt(8)
	s_waitcnt lgkmcnt(0)
	s_barrier
	s_setprio 1
	v_mfma_f32_16x16x32_bf16 v[124:127], v[168:171], v[200:203], v[124:127]
	v_mfma_f32_16x16x32_bf16 v[120:123], v[176:179], v[200:203], v[120:123]
	v_mfma_f32_16x16x32_bf16 v[108:111], v[168:171], v[208:211], v[108:111]
	v_mfma_f32_16x16x32_bf16 v[104:107], v[176:179], v[208:211], v[104:107]
	v_mfma_f32_16x16x32_bf16 v[92:95], v[168:171], v[216:219], v[92:95]
	v_mfma_f32_16x16x32_bf16 v[88:91], v[176:179], v[216:219], v[88:91]
	v_mfma_f32_16x16x32_bf16 v[76:79], v[168:171], v[224:227], v[76:79]
	v_mfma_f32_16x16x32_bf16 v[72:75], v[176:179], v[224:227], v[72:75]
	v_mfma_f32_16x16x32_bf16 v[124:127], v[172:175], v[204:207], v[124:127]
	v_mfma_f32_16x16x32_bf16 v[120:123], v[180:183], v[204:207], v[120:123]
	v_mfma_f32_16x16x32_bf16 v[108:111], v[172:175], v[212:215], v[108:111]
	v_mfma_f32_16x16x32_bf16 v[104:107], v[180:183], v[212:215], v[104:107]
	v_mfma_f32_16x16x32_bf16 v[92:95], v[172:175], v[220:223], v[92:95]
	v_mfma_f32_16x16x32_bf16 v[88:91], v[180:183], v[220:223], v[88:91]
	v_mfma_f32_16x16x32_bf16 v[76:79], v[172:175], v[228:231], v[76:79]
	v_mfma_f32_16x16x32_bf16 v[72:75], v[180:183], v[228:231], v[72:75]
	v_mfma_f32_16x16x32_bf16 v[116:119], v[184:187], v[200:203], v[116:119]
	v_mfma_f32_16x16x32_bf16 v[112:115], v[192:195], v[200:203], v[112:115]
	v_mfma_f32_16x16x32_bf16 v[100:103], v[184:187], v[208:211], v[100:103]
	v_mfma_f32_16x16x32_bf16 v[96:99], v[192:195], v[208:211], v[96:99]
	v_mfma_f32_16x16x32_bf16 v[84:87], v[184:187], v[216:219], v[84:87]
	v_mfma_f32_16x16x32_bf16 v[80:83], v[192:195], v[216:219], v[80:83]
	v_mfma_f32_16x16x32_bf16 v[68:71], v[184:187], v[224:227], v[68:71]
	v_mfma_f32_16x16x32_bf16 v[64:67], v[192:195], v[224:227], v[64:67]
	v_mfma_f32_16x16x32_bf16 v[116:119], v[188:191], v[204:207], v[116:119]
	v_mfma_f32_16x16x32_bf16 v[112:115], v[196:199], v[204:207], v[112:115]
	v_mfma_f32_16x16x32_bf16 v[100:103], v[188:191], v[212:215], v[100:103]
	v_mfma_f32_16x16x32_bf16 v[96:99], v[196:199], v[212:215], v[96:99]
	v_mfma_f32_16x16x32_bf16 v[84:87], v[188:191], v[220:223], v[84:87]
	v_mfma_f32_16x16x32_bf16 v[80:83], v[196:199], v[220:223], v[80:83]
	v_mfma_f32_16x16x32_bf16 v[68:71], v[188:191], v[228:231], v[68:71]
	v_mfma_f32_16x16x32_bf16 v[64:67], v[196:199], v[228:231], v[64:67]
	s_setprio 0
	s_barrier
	s_mov_b32 m0, s41
	v_lshl_add_u64 v[236:237], v[234:235], 0, v[136:137]
	ds_read_b128 v[200:203], v166 offset:16384
	ds_read_b128 v[204:207], v166 offset:17408
	ds_read_b128 v[208:211], v166 offset:18432
	ds_read_b128 v[212:215], v166 offset:19456
	ds_read_b128 v[216:219], v166 offset:20480
	ds_read_b128 v[220:223], v166 offset:21504
	ds_read_b128 v[224:227], v166 offset:22528
	ds_read_b128 v[228:231], v166 offset:23552
	global_load_lds_dwordx4 v[236:237], off
	v_lshl_add_u64 v[238:239], v[234:235], 0, v[132:133]
	s_add_i32 m0, s41, 0x2000
	v_lshl_add_u64 v[234:235], v[234:235], 0, v[130:131]
	s_add_i32 s39, s34, s2
	global_load_lds_dwordx4 v[238:239], off
	v_lshl_add_u64 v[240:241], v[234:235], 0, v[136:137]
	s_mov_b32 m0, s39
	v_lshl_add_u64 v[234:235], v[234:235], 0, v[132:133]
	global_load_lds_dwordx4 v[240:241], off
	s_add_i32 m0, s39, 0x2000
	v_lshl_add_u64 v[242:243], v[232:233], 0, v[138:139]
	global_load_lds_dwordx4 v[234:235], off
	s_mov_b32 m0, s21
	v_lshl_add_u64 v[244:245], v[232:233], 0, v[134:135]
	global_load_lds_dwordx4 v[242:243], off
	s_mov_b32 m0, s22
	s_nop 0
	global_load_lds_dwordx4 v[244:245], off
	s_waitcnt vmcnt(8)
	s_waitcnt lgkmcnt(0)
	s_barrier
; #define PG8_STAGE(bufoff, gbase, voff) do { _Pragma("unroll") for (int _i = 0; _i < 2; ++_i) \
;         __builtin_amdgcn_global_load_lds((const unsigned*)((const char*)(gbase) + (voff)[_i]), (LAS unsigned*)(lds + (bufoff) + ldsw + _i * 8192), 16, 0, 0); } while (0)
; #define PG8_LDA(dst, b, h) do { _Pragma("unroll") for (int m = 0; m < 4; ++m) _Pragma("unroll") for (int k = 0; k < 2; ++k) dst[m][k] = *(const LAS bf16x8*)(lds + PG8_SA(b, h) + aoff + m * 2048 + k * 1024); } while (0)
; #define PG8_LDB(dst, b, h) do { _Pragma("unroll") for (int n = 0; n < 2; ++n) _Pragma("unroll") for (int k = 0; k < 2; ++k) dst[n][k] = *(const LAS bf16x8*)(lds + PG8_SB(b, h) + boff + n * 2048 + k * 1024); } while (0)
; #define PG8_WAIT_V(n) asm volatile("s_waitcnt vmcnt(" #n ")" ::: "memory")
; #define PG8_WAIT_L(n) asm volatile("s_waitcnt lgkmcnt(" #n ")" ::: "memory")
; #define PG8_BAR __builtin_amdgcn_s_barrier()
; #define PG8_SCHED __builtin_amdgcn_sched_barrier(0)
;     ...
;             PG8_WAIT_V(8); PG8_WAIT_L(0); PG8_BAR; PG8_MMA(1, 0, At, B0); PG8_MMA(1, 1, At, B1); PG8_BAR; PG8_SCHED;
;             PG8_LDB(B0, 1, 0); PG8_LDB(B1, 1, 1); PG8_SCHED; PG8_LDA(At, 1, 0); PG8_STAGE(PG8_SA(0, 1), a2 + hstepA, voffA);
;             PG8_WAIT_V(8); PG8_WAIT_L(0); PG8_BAR; PG8_MMA(0, 0, At, B0); PG8_MMA(0, 1, At, B1); PG8_BAR; PG8_SCHED;
	s_setprio 1
	v_mfma_f32_16x16x32_bf16 v[60:63], v[168:171], v[200:203], v[60:63]
	v_mfma_f32_16x16x32_bf16 v[56:59], v[176:179], v[200:203], v[56:59]
	v_mfma_f32_16x16x32_bf16 v[44:47], v[168:171], v[208:211], v[44:47]
	v_mfma_f32_16x16x32_bf16 v[40:43], v[176:179], v[208:211], v[40:43]
	v_mfma_f32_16x16x32_bf16 v[28:31], v[168:171], v[216:219], v[28:31]
	v_mfma_f32_16x16x32_bf16 v[24:27], v[176:179], v[216:219], v[24:27]
	v_mfma_f32_16x16x32_bf16 v[12:15], v[168:171], v[224:227], v[12:15]
	v_mfma_f32_16x16x32_bf16 v[8:11], v[176:179], v[224:227], v[8:11]
	v_mfma_f32_16x16x32_bf16 v[60:63], v[172:175], v[204:207], v[60:63]
	v_mfma_f32_16x16x32_bf16 v[56:59], v[180:183], v[204:207], v[56:59]
	v_mfma_f32_16x16x32_bf16 v[44:47], v[172:175], v[212:215], v[44:47]
	v_mfma_f32_16x16x32_bf16 v[40:43], v[180:183], v[212:215], v[40:43]
	v_mfma_f32_16x16x32_bf16 v[28:31], v[172:175], v[220:223], v[28:31]
	v_mfma_f32_16x16x32_bf16 v[24:27], v[180:183], v[220:223], v[24:27]
	v_mfma_f32_16x16x32_bf16 v[12:15], v[172:175], v[228:231], v[12:15]
	v_mfma_f32_16x16x32_bf16 v[8:11], v[180:183], v[228:231], v[8:11]
	v_mfma_f32_16x16x32_bf16 v[52:55], v[184:187], v[200:203], v[52:55]
	v_mfma_f32_16x16x32_bf16 v[48:51], v[192:195], v[200:203], v[48:51]
	v_mfma_f32_16x16x32_bf16 v[36:39], v[184:187], v[208:211], v[36:39]
	v_mfma_f32_16x16x32_bf16 v[32:35], v[192:195], v[208:211], v[32:35]
	v_mfma_f32_16x16x32_bf16 v[20:23], v[184:187], v[216:219], v[20:23]
	v_mfma_f32_16x16x32_bf16 v[16:19], v[192:195], v[216:219], v[16:19]
	v_mfma_f32_16x16x32_bf16 v[4:7], v[184:187], v[224:227], v[4:7]
	v_mfma_f32_16x16x32_bf16 v[0:3], v[192:195], v[224:227], v[0:3]
	v_mfma_f32_16x16x32_bf16 v[52:55], v[188:191], v[204:207], v[52:55]
	v_mfma_f32_16x16x32_bf16 v[48:51], v[196:199], v[204:207], v[48:51]
	v_mfma_f32_16x16x32_bf16 v[36:39], v[188:191], v[212:215], v[36:39]
	v_mfma_f32_16x16x32_bf16 v[32:35], v[196:199], v[212:215], v[32:35]
	v_mfma_f32_16x16x32_bf16 v[20:23], v[188:191], v[220:223], v[20:23]
	v_mfma_f32_16x16x32_bf16 v[16:19], v[196:199], v[220:223], v[16:19]
	v_mfma_f32_16x16x32_bf16 v[4:7], v[188:191], v[228:231], v[4:7]
	v_mfma_f32_16x16x32_bf16 v[0:3], v[196:199], v[228:231], v[0:3]
	s_setprio 0
	s_barrier
	s_add_i32 s39, 0, 0x18000
	v_add_u32_e32 v167, s39, v162
	s_add_i32 s46, 0, 0x1c000
	ds_read_b128 v[168:171], v167
	ds_read_b128 v[172:175], v167 offset:1024
	ds_read_b128 v[176:179], v167 offset:2048
	ds_read_b128 v[180:183], v167 offset:3072
	v_add_u32_e32 v167, s46, v162
	ds_read_b128 v[184:187], v167
	ds_read_b128 v[188:191], v167 offset:1024
	ds_read_b128 v[192:195], v167 offset:2048
	ds_read_b128 v[196:199], v167 offset:3072
	v_lshl_add_u64 v[232:233], v[232:233], 0, v[128:129]
	s_mov_b32 m0, s23
	v_lshl_add_u64 v[246:247], v[232:233], 0, v[138:139]
	ds_read_b128 v[200:203], v166 offset:32768
	ds_read_b128 v[204:207], v166 offset:33792
	ds_read_b128 v[208:211], v166 offset:34816
	ds_read_b128 v[212:215], v166 offset:35840
	ds_read_b128 v[216:219], v166 offset:36864
	ds_read_b128 v[220:223], v166 offset:37888
	ds_read_b128 v[224:227], v166 offset:38912
	ds_read_b128 v[228:231], v166 offset:39936
	global_load_lds_dwordx4 v[246:247], off
	v_lshl_add_u64 v[232:233], v[232:233], 0, v[134:135]
	s_mov_b32 m0, s24
	s_nop 0
	global_load_lds_dwordx4 v[232:233], off
	s_waitcnt vmcnt(8)
	s_waitcnt lgkmcnt(0)
	s_barrier
	s_setprio 1
	v_mfma_f32_16x16x32_bf16 v[124:127], v[168:171], v[200:203], v[124:127]
	v_mfma_f32_16x16x32_bf16 v[120:123], v[176:179], v[200:203], v[120:123]
	v_mfma_f32_16x16x32_bf16 v[108:111], v[168:171], v[208:211], v[108:111]
	v_mfma_f32_16x16x32_bf16 v[104:107], v[176:179], v[208:211], v[104:107]
	v_mfma_f32_16x16x32_bf16 v[92:95], v[168:171], v[216:219], v[92:95]
	v_mfma_f32_16x16x32_bf16 v[88:91], v[176:179], v[216:219], v[88:91]
	v_mfma_f32_16x16x32_bf16 v[76:79], v[168:171], v[224:227], v[76:79]
	v_mfma_f32_16x16x32_bf16 v[72:75], v[176:179], v[224:227], v[72:75]
	v_mfma_f32_16x16x32_bf16 v[124:127], v[172:175], v[204:207], v[124:127]
	v_mfma_f32_16x16x32_bf16 v[120:123], v[180:183], v[204:207], v[120:123]
	v_mfma_f32_16x16x32_bf16 v[108:111], v[172:175], v[212:215], v[108:111]
	v_mfma_f32_16x16x32_bf16 v[104:107], v[180:183], v[212:215], v[104:107]
	v_mfma_f32_16x16x32_bf16 v[92:95], v[172:175], v[220:223], v[92:95]
	v_mfma_f32_16x16x32_bf16 v[88:91], v[180:183], v[220:223], v[88:91]
	v_mfma_f32_16x16x32_bf16 v[76:79], v[172:175], v[228:231], v[76:79]
	v_mfma_f32_16x16x32_bf16 v[72:75], v[180:183], v[228:231], v[72:75]
	v_mfma_f32_16x16x32_bf16 v[116:119], v[184:187], v[200:203], v[116:119]
	v_mfma_f32_16x16x32_bf16 v[112:115], v[192:195], v[200:203], v[112:115]
	v_mfma_f32_16x16x32_bf16 v[100:103], v[184:187], v[208:211], v[100:103]
	v_mfma_f32_16x16x32_bf16 v[96:99], v[192:195], v[208:211], v[96:99]
	v_mfma_f32_16x16x32_bf16 v[84:87], v[184:187], v[216:219], v[84:87]
	v_mfma_f32_16x16x32_bf16 v[80:83], v[192:195], v[216:219], v[80:83]
	v_mfma_f32_16x16x32_bf16 v[68:71], v[184:187], v[224:227], v[68:71]
	v_mfma_f32_16x16x32_bf16 v[64:67], v[192:195], v[224:227], v[64:67]
	v_mfma_f32_16x16x32_bf16 v[116:119], v[188:191], v[204:207], v[116:119]
	v_mfma_f32_16x16x32_bf16 v[112:115], v[196:199], v[204:207], v[112:115]
	v_mfma_f32_16x16x32_bf16 v[100:103], v[188:191], v[212:215], v[100:103]
	v_mfma_f32_16x16x32_bf16 v[96:99], v[196:199], v[212:215], v[96:99]
	v_mfma_f32_16x16x32_bf16 v[84:87], v[188:191], v[220:223], v[84:87]
	v_mfma_f32_16x16x32_bf16 v[80:83], v[196:199], v[220:223], v[80:83]
	v_mfma_f32_16x16x32_bf16 v[68:71], v[188:191], v[228:231], v[68:71]
	v_mfma_f32_16x16x32_bf16 v[64:67], v[196:199], v[228:231], v[64:67]
	s_setprio 0
	s_barrier
; #define PG8_STAGE(bufoff, gbase, voff) do { _Pragma("unroll") for (int _i = 0; _i < 2; ++_i) \
;         __builtin_amdgcn_global_load_lds((const unsigned*)((const char*)(gbase) + (voff)[_i]), (LAS unsigned*)(lds + (bufoff) + ldsw + _i * 8192), 16, 0, 0); } while (0)
; #define PG8_LDA(dst, b, h) do { _Pragma("unroll") for (int m = 0; m < 4; ++m) _Pragma("unroll") for (int k = 0; k < 2; ++k) dst[m][k] = *(const LAS bf16x8*)(lds + PG8_SA(b, h) + aoff + m * 2048 + k * 1024); } while (0)
; #define PG8_WAIT_V(n) asm volatile("s_waitcnt vmcnt(" #n ")" ::: "memory")
; #define PG8_WAIT_L(n) asm volatile("s_waitcnt lgkmcnt(" #n ")" ::: "memory")
; #define PG8_BAR __builtin_amdgcn_s_barrier()
; #define PG8_SCHED __builtin_amdgcn_sched_barrier(0)
;     ...
;             PG8_LDA(At, 1, 1); PG8_STAGE(PG8_SB(1, 0), b3, voffB); PG8_STAGE(PG8_SB(1, 1), b3 + hstepB, voffB); PG8_STAGE(PG8_SA(1, 0), a3, voffA);
;             PG8_WAIT_V(8); PG8_WAIT_L(0); PG8_BAR; PG8_MMA(1, 0, At, B0); PG8_MMA(1, 1, At, B1); PG8_BAR; PG8_SCHED;
	s_add_i32 s39, s39, s2
	v_lshl_add_u64 v[232:233], v[236:237], 0, s[12:13]
	s_mov_b32 m0, s39
	ds_read_b128 v[200:203], v166 offset:49152
	ds_read_b128 v[204:207], v166 offset:50176
	ds_read_b128 v[208:211], v166 offset:51200
	ds_read_b128 v[212:215], v166 offset:52224
	ds_read_b128 v[216:219], v166 offset:53248
	ds_read_b128 v[220:223], v166 offset:54272
	ds_read_b128 v[224:227], v166 offset:55296
	ds_read_b128 v[228:231], v166 offset:56320
	global_load_lds_dwordx4 v[232:233], off
	v_lshl_add_u64 v[232:233], v[238:239], 0, s[12:13]
	s_add_i32 m0, s39, 0x2000
	s_add_i32 s39, s46, s2
	global_load_lds_dwordx4 v[232:233], off
	v_lshl_add_u64 v[232:233], v[240:241], 0, s[12:13]
	s_mov_b32 m0, s39
	s_nop 0
	global_load_lds_dwordx4 v[232:233], off
	v_lshl_add_u64 v[232:233], v[234:235], 0, s[12:13]
	s_add_i32 m0, s39, 0x2000
	s_nop 0
	global_load_lds_dwordx4 v[232:233], off
	v_lshl_add_u64 v[232:233], v[242:243], 0, s[12:13]
	s_mov_b32 m0, s30
	s_nop 0
	global_load_lds_dwordx4 v[232:233], off
	v_lshl_add_u64 v[232:233], v[244:245], 0, s[12:13]
	s_mov_b32 m0, s31
	s_nop 0
	global_load_lds_dwordx4 v[232:233], off
	s_waitcnt vmcnt(8)
	s_waitcnt lgkmcnt(0)
	s_barrier
	s_setprio 1
	v_mfma_f32_16x16x32_bf16 v[60:63], v[168:171], v[200:203], v[60:63]
	v_mfma_f32_16x16x32_bf16 v[56:59], v[176:179], v[200:203], v[56:59]
	v_mfma_f32_16x16x32_bf16 v[44:47], v[168:171], v[208:211], v[44:47]
	v_mfma_f32_16x16x32_bf16 v[40:43], v[176:179], v[208:211], v[40:43]
	v_mfma_f32_16x16x32_bf16 v[28:31], v[168:171], v[216:219], v[28:31]
	v_mfma_f32_16x16x32_bf16 v[24:27], v[176:179], v[216:219], v[24:27]
	v_mfma_f32_16x16x32_bf16 v[12:15], v[168:171], v[224:227], v[12:15]
	v_mfma_f32_16x16x32_bf16 v[8:11], v[176:179], v[224:227], v[8:11]
	v_mfma_f32_16x16x32_bf16 v[60:63], v[172:175], v[204:207], v[60:63]
	v_mfma_f32_16x16x32_bf16 v[56:59], v[180:183], v[204:207], v[56:59]
	v_mfma_f32_16x16x32_bf16 v[44:47], v[172:175], v[212:215], v[44:47]
	v_mfma_f32_16x16x32_bf16 v[40:43], v[180:183], v[212:215], v[40:43]
	v_mfma_f32_16x16x32_bf16 v[28:31], v[172:175], v[220:223], v[28:31]
	v_mfma_f32_16x16x32_bf16 v[24:27], v[180:183], v[220:223], v[24:27]
	v_mfma_f32_16x16x32_bf16 v[12:15], v[172:175], v[228:231], v[12:15]
	v_mfma_f32_16x16x32_bf16 v[8:11], v[180:183], v[228:231], v[8:11]
	v_mfma_f32_16x16x32_bf16 v[52:55], v[184:187], v[200:203], v[52:55]
	v_mfma_f32_16x16x32_bf16 v[48:51], v[192:195], v[200:203], v[48:51]
	v_mfma_f32_16x16x32_bf16 v[36:39], v[184:187], v[208:211], v[36:39]
	v_mfma_f32_16x16x32_bf16 v[32:35], v[192:195], v[208:211], v[32:35]
	v_mfma_f32_16x16x32_bf16 v[20:23], v[184:187], v[216:219], v[20:23]
	v_mfma_f32_16x16x32_bf16 v[16:19], v[192:195], v[216:219], v[16:19]
	v_mfma_f32_16x16x32_bf16 v[4:7], v[184:187], v[224:227], v[4:7]
	v_mfma_f32_16x16x32_bf16 v[0:3], v[192:195], v[224:227], v[0:3]
	v_mfma_f32_16x16x32_bf16 v[52:55], v[188:191], v[204:207], v[52:55]
	v_mfma_f32_16x16x32_bf16 v[48:51], v[196:199], v[204:207], v[48:51]
	v_mfma_f32_16x16x32_bf16 v[36:39], v[188:191], v[212:215], v[36:39]
	v_mfma_f32_16x16x32_bf16 v[32:35], v[196:199], v[212:215], v[32:35]
	v_mfma_f32_16x16x32_bf16 v[20:23], v[188:191], v[220:223], v[20:23]
	v_mfma_f32_16x16x32_bf16 v[16:19], v[196:199], v[220:223], v[16:19]
	v_mfma_f32_16x16x32_bf16 v[4:7], v[188:191], v[228:231], v[4:7]
	v_mfma_f32_16x16x32_bf16 v[0:3], v[196:199], v[228:231], v[0:3]
	s_setprio 0
	s_barrier
	s_add_i32 s38, s38, 2
	s_add_u32 s18, s18, 0x100
	s_addc_u32 s19, s19, 0
	s_cmp_gt_u32 s38, 61
	s_cbranch_scc0 .LBB0_1066
	s_and_b64 vcc, exec, s[14:15]
	s_cbranch_vccz .LBB0_1069
	s_barrier

; #define PG8_STAGE(bufoff, gbase, voff) do { _Pragma("unroll") for (int _i = 0; _i < 2; ++_i) \
;         __builtin_amdgcn_global_load_lds((const unsigned*)((const char*)(gbase) + (voff)[_i]), (LAS unsigned*)(lds + (bufoff) + ldsw + _i * 8192), 16, 0, 0); } while (0)
; #define PG8_LDA(dst, b, h) do { _Pragma("unroll") for (int m = 0; m < 4; ++m) _Pragma("unroll") for (int k = 0; k < 2; ++k) dst[m][k] = *(const LAS bf16x8*)(lds + PG8_SA(b, h) + aoff + m * 2048 + k * 1024); } while (0)
; #define PG8_LDB(dst, b, h) do { _Pragma("unroll") for (int n = 0; n < 2; ++n) _Pragma("unroll") for (int k = 0; k < 2; ++k) dst[n][k] = *(const LAS bf16x8*)(lds + PG8_SB(b, h) + boff + n * 2048 + k * 1024); } while (0)
; #define PG8_WAIT_V(n) asm volatile("s_waitcnt vmcnt(" #n ")" ::: "memory")
; #define PG8_WAIT_L(n) asm volatile("s_waitcnt lgkmcnt(" #n ")" ::: "memory")
; #define PG8_BAR __builtin_amdgcn_s_barrier()
; #define PG8_SCHED __builtin_amdgcn_sched_barrier(0)
;     ...
;         for (int t = 0; t < nt; t += 2) {
;             const bool last = (t == nt - 2);
;             const char* a1 = cA + (size_t)(t + 1) * kstep;
;             const char* a2 = last ? nA : cA + (size_t)(t + 2) * kstep; const char* b2 = last ? nB : cB + (size_t)(t + 2) * kstep;
;             const char* a3 = a2 + kstep; const char* b3 = b2 + kstep;
;             if constexpr (SP2) {
;             PG8_LDB(B0, 0, 0); PG8_LDB(B1, 0, 1); PG8_SCHED; PG8_LDA(At, 0, 0); PG8_STAGE(PG8_SA(1, 1), a1 + hstepA, voffA);
;             PG8_WAIT_V(8); PG8_WAIT_L(0); PG8_BAR; PG8_MMA(0, 0, At, B0); PG8_MMA(0, 1, At, B1); PG8_BAR; PG8_SCHED;
;             PG8_LDA(At, 0, 1); PG8_STAGE(PG8_SB(0, 0), b2, voffB); PG8_STAGE(PG8_SB(0, 1), b2 + hstepB, voffB); PG8_STAGE(PG8_SA(0, 0), a2, voffA);
;             PG8_WAIT_V(8); PG8_WAIT_L(0); PG8_BAR; PG8_MMA(1, 0, At, B0); PG8_MMA(1, 1, At, B1); PG8_BAR; PG8_SCHED;
.LBB0_1148:
	v_lshl_add_u64 v[168:169], v[152:153], 0, s[18:19]
	s_cmpk_eq_i32 s18, 0x7f00
	v_lshl_add_u64 v[168:169], v[168:169], 0, s[16:17]
	v_lshl_add_u64 v[184:185], v[158:159], 0, s[18:19]
	s_cselect_b64 vcc, -1, 0
	v_cndmask_b32_e32 v233, v169, v149, vcc
	v_cndmask_b32_e32 v232, v168, v148, vcc
	ds_read_b128 v[168:171], v164
	ds_read_b128 v[172:175], v164 offset:1024
	ds_read_b128 v[176:179], v164 offset:2048
	ds_read_b128 v[180:183], v164 offset:3072
	v_cndmask_b32_e32 v235, v185, v151, vcc
	v_cndmask_b32_e32 v234, v184, v150, vcc
	ds_read_b128 v[184:187], v165
	ds_read_b128 v[188:191], v165 offset:1024
	ds_read_b128 v[192:195], v165 offset:2048
	ds_read_b128 v[196:199], v165 offset:3072
	v_lshl_add_u64 v[236:237], v[156:157], 0, s[18:19]
	s_add_i32 m0, s3, 0xc000
	ds_read_b128 v[200:203], v166
	ds_read_b128 v[204:207], v166 offset:1024
	ds_read_b128 v[208:211], v166 offset:2048
	ds_read_b128 v[212:215], v166 offset:3072
	ds_read_b128 v[216:219], v166 offset:4096
	ds_read_b128 v[220:223], v166 offset:5120
	ds_read_b128 v[224:227], v166 offset:6144
	ds_read_b128 v[228:231], v166 offset:7168
	global_load_lds_dwordx4 v[236:237], off
	v_lshl_add_u64 v[236:237], v[154:155], 0, s[18:19]
	s_add_i32 m0, s3, 0xe000
	s_nop 0
	global_load_lds_dwordx4 v[236:237], off
	s_waitcnt vmcnt(8)
	s_waitcnt lgkmcnt(0)
	s_barrier
	s_setprio 1
	v_mfma_f32_16x16x32_bf16 v[124:127], v[168:171], v[200:203], v[124:127]
	v_mfma_f32_16x16x32_bf16 v[120:123], v[176:179], v[200:203], v[120:123]
	v_mfma_f32_16x16x32_bf16 v[108:111], v[168:171], v[208:211], v[108:111]
	v_mfma_f32_16x16x32_bf16 v[104:107], v[176:179], v[208:211], v[104:107]
	v_mfma_f32_16x16x32_bf16 v[92:95], v[168:171], v[216:219], v[92:95]
	v_mfma_f32_16x16x32_bf16 v[88:91], v[176:179], v[216:219], v[88:91]
	v_mfma_f32_16x16x32_bf16 v[76:79], v[168:171], v[224:227], v[76:79]
	v_mfma_f32_16x16x32_bf16 v[72:75], v[176:179], v[224:227], v[72:75]
	v_mfma_f32_16x16x32_bf16 v[124:127], v[172:175], v[204:207], v[124:127]
	v_mfma_f32_16x16x32_bf16 v[120:123], v[180:183], v[204:207], v[120:123]
	v_mfma_f32_16x16x32_bf16 v[108:111], v[172:175], v[212:215], v[108:111]
	v_mfma_f32_16x16x32_bf16 v[104:107], v[180:183], v[212:215], v[104:107]
	v_mfma_f32_16x16x32_bf16 v[92:95], v[172:175], v[220:223], v[92:95]
	v_mfma_f32_16x16x32_bf16 v[88:91], v[180:183], v[220:223], v[88:91]
	v_mfma_f32_16x16x32_bf16 v[76:79], v[172:175], v[228:231], v[76:79]
	v_mfma_f32_16x16x32_bf16 v[72:75], v[180:183], v[228:231], v[72:75]
	v_mfma_f32_16x16x32_bf16 v[116:119], v[184:187], v[200:203], v[116:119]
	v_mfma_f32_16x16x32_bf16 v[112:115], v[192:195], v[200:203], v[112:115]
	v_mfma_f32_16x16x32_bf16 v[100:103], v[184:187], v[208:211], v[100:103]
	v_mfma_f32_16x16x32_bf16 v[96:99], v[192:195], v[208:211], v[96:99]
	v_mfma_f32_16x16x32_bf16 v[84:87], v[184:187], v[216:219], v[84:87]
	v_mfma_f32_16x16x32_bf16 v[80:83], v[192:195], v[216:219], v[80:83]
	v_mfma_f32_16x16x32_bf16 v[68:71], v[184:187], v[224:227], v[68:71]
	v_mfma_f32_16x16x32_bf16 v[64:67], v[192:195], v[224:227], v[64:67]
	v_mfma_f32_16x16x32_bf16 v[116:119], v[188:191], v[204:207], v[116:119]
	v_mfma_f32_16x16x32_bf16 v[112:115], v[196:199], v[204:207], v[112:115]
	v_mfma_f32_16x16x32_bf16 v[100:103], v[188:191], v[212:215], v[100:103]
	v_mfma_f32_16x16x32_bf16 v[96:99], v[196:199], v[212:215], v[96:99]
	v_mfma_f32_16x16x32_bf16 v[84:87], v[188:191], v[220:223], v[84:87]
	v_mfma_f32_16x16x32_bf16 v[80:83], v[196:199], v[220:223], v[80:83]
	v_mfma_f32_16x16x32_bf16 v[68:71], v[188:191], v[228:231], v[68:71]
	v_mfma_f32_16x16x32_bf16 v[64:67], v[196:199], v[228:231], v[64:67]
	s_setprio 0
	s_barrier
	s_add_i32 s21, s43, s2
	v_lshl_add_u64 v[236:237], v[234:235], 0, v[130:131]
	s_mov_b32 m0, s21
	ds_read_b128 v[200:203], v166 offset:16384
	ds_read_b128 v[204:207], v166 offset:17408
	ds_read_b128 v[208:211], v166 offset:18432
	ds_read_b128 v[212:215], v166 offset:19456
	ds_read_b128 v[216:219], v166 offset:20480
	ds_read_b128 v[220:223], v166 offset:21504
	ds_read_b128 v[224:227], v166 offset:22528
	ds_read_b128 v[228:231], v166 offset:23552
	global_load_lds_dwordx4 v[236:237], off
	v_lshl_add_u64 v[238:239], v[234:235], 0, v[134:135]
	s_add_i32 m0, s21, 0x2000
	v_lshl_add_u64 v[234:235], v[234:235], 0, v[138:139]
	s_add_i32 s21, s46, s2
	global_load_lds_dwordx4 v[238:239], off
	v_lshl_add_u64 v[240:241], v[234:235], 0, v[130:131]
	s_mov_b32 m0, s21
	v_lshl_add_u64 v[234:235], v[234:235], 0, v[134:135]
	global_load_lds_dwordx4 v[240:241], off
	s_add_i32 m0, s21, 0x2000
	v_lshl_add_u64 v[242:243], v[232:233], 0, v[128:129]
	global_load_lds_dwordx4 v[234:235], off
	s_mov_b32 m0, s3
	v_lshl_add_u64 v[244:245], v[232:233], 0, v[132:133]
	global_load_lds_dwordx4 v[242:243], off
	s_mov_b32 m0, s22
	s_nop 0
	global_load_lds_dwordx4 v[244:245], off
	s_waitcnt vmcnt(8)
	s_waitcnt lgkmcnt(0)
	s_barrier
; #define PG8_STAGE(bufoff, gbase, voff) do { _Pragma("unroll") for (int _i = 0; _i < 2; ++_i) \
;         __builtin_amdgcn_global_load_lds((const unsigned*)((const char*)(gbase) + (voff)[_i]), (LAS unsigned*)(lds + (bufoff) + ldsw + _i * 8192), 16, 0, 0); } while (0)
; #define PG8_LDA(dst, b, h) do { _Pragma("unroll") for (int m = 0; m < 4; ++m) _Pragma("unroll") for (int k = 0; k < 2; ++k) dst[m][k] = *(const LAS bf16x8*)(lds + PG8_SA(b, h) + aoff + m * 2048 + k * 1024); } while (0)
; #define PG8_LDB(dst, b, h) do { _Pragma("unroll") for (int n = 0; n < 2; ++n) _Pragma("unroll") for (int k = 0; k < 2; ++k) dst[n][k] = *(const LAS bf16x8*)(lds + PG8_SB(b, h) + boff + n * 2048 + k * 1024); } while (0)
; #define PG8_WAIT_V(n) asm volatile("s_waitcnt vmcnt(" #n ")" ::: "memory")
; #define PG8_WAIT_L(n) asm volatile("s_waitcnt lgkmcnt(" #n ")" ::: "memory")
; #define PG8_BAR __builtin_amdgcn_s_barrier()
; #define PG8_SCHED __builtin_amdgcn_sched_barrier(0)
;     ...
;             PG8_WAIT_V(8); PG8_WAIT_L(0); PG8_BAR; PG8_MMA(1, 0, At, B0); PG8_MMA(1, 1, At, B1); PG8_BAR; PG8_SCHED;
;             PG8_LDB(B0, 1, 0); PG8_LDB(B1, 1, 1); PG8_SCHED; PG8_LDA(At, 1, 0); PG8_STAGE(PG8_SA(0, 1), a2 + hstepA, voffA);
;             PG8_WAIT_V(8); PG8_WAIT_L(0); PG8_BAR; PG8_MMA(0, 0, At, B0); PG8_MMA(0, 1, At, B1); PG8_BAR; PG8_SCHED;
	s_setprio 1
	v_mfma_f32_16x16x32_bf16 v[60:63], v[168:171], v[200:203], v[60:63]
	v_mfma_f32_16x16x32_bf16 v[56:59], v[176:179], v[200:203], v[56:59]
	v_mfma_f32_16x16x32_bf16 v[44:47], v[168:171], v[208:211], v[44:47]
	v_mfma_f32_16x16x32_bf16 v[40:43], v[176:179], v[208:211], v[40:43]
	v_mfma_f32_16x16x32_bf16 v[28:31], v[168:171], v[216:219], v[28:31]
	v_mfma_f32_16x16x32_bf16 v[24:27], v[176:179], v[216:219], v[24:27]
	v_mfma_f32_16x16x32_bf16 v[12:15], v[168:171], v[224:227], v[12:15]
	v_mfma_f32_16x16x32_bf16 v[8:11], v[176:179], v[224:227], v[8:11]
	v_mfma_f32_16x16x32_bf16 v[60:63], v[172:175], v[204:207], v[60:63]
	v_mfma_f32_16x16x32_bf16 v[56:59], v[180:183], v[204:207], v[56:59]
	v_mfma_f32_16x16x32_bf16 v[44:47], v[172:175], v[212:215], v[44:47]
	v_mfma_f32_16x16x32_bf16 v[40:43], v[180:183], v[212:215], v[40:43]
	v_mfma_f32_16x16x32_bf16 v[28:31], v[172:175], v[220:223], v[28:31]
	v_mfma_f32_16x16x32_bf16 v[24:27], v[180:183], v[220:223], v[24:27]
	v_mfma_f32_16x16x32_bf16 v[12:15], v[172:175], v[228:231], v[12:15]
	v_mfma_f32_16x16x32_bf16 v[8:11], v[180:183], v[228:231], v[8:11]
	v_mfma_f32_16x16x32_bf16 v[52:55], v[184:187], v[200:203], v[52:55]
	v_mfma_f32_16x16x32_bf16 v[48:51], v[192:195], v[200:203], v[48:51]
	v_mfma_f32_16x16x32_bf16 v[36:39], v[184:187], v[208:211], v[36:39]
	v_mfma_f32_16x16x32_bf16 v[32:35], v[192:195], v[208:211], v[32:35]
	v_mfma_f32_16x16x32_bf16 v[20:23], v[184:187], v[216:219], v[20:23]
	v_mfma_f32_16x16x32_bf16 v[16:19], v[192:195], v[216:219], v[16:19]
	v_mfma_f32_16x16x32_bf16 v[4:7], v[184:187], v[224:227], v[4:7]
	v_mfma_f32_16x16x32_bf16 v[0:3], v[192:195], v[224:227], v[0:3]
	v_mfma_f32_16x16x32_bf16 v[52:55], v[188:191], v[204:207], v[52:55]
	v_mfma_f32_16x16x32_bf16 v[48:51], v[196:199], v[204:207], v[48:51]
	v_mfma_f32_16x16x32_bf16 v[36:39], v[188:191], v[212:215], v[36:39]
	v_mfma_f32_16x16x32_bf16 v[32:35], v[196:199], v[212:215], v[32:35]
	v_mfma_f32_16x16x32_bf16 v[20:23], v[188:191], v[220:223], v[20:23]
	v_mfma_f32_16x16x32_bf16 v[16:19], v[196:199], v[220:223], v[16:19]
	v_mfma_f32_16x16x32_bf16 v[4:7], v[188:191], v[228:231], v[4:7]
	v_mfma_f32_16x16x32_bf16 v[0:3], v[196:199], v[228:231], v[0:3]
	s_setprio 0
	s_barrier
	s_add_i32 s21, 0, 0x18000
	v_add_u32_e32 v167, s21, v162
	s_add_i32 s40, 0, 0x1c000
	ds_read_b128 v[168:171], v167
	ds_read_b128 v[172:175], v167 offset:1024
	ds_read_b128 v[176:179], v167 offset:2048
	ds_read_b128 v[180:183], v167 offset:3072
	v_add_u32_e32 v167, s40, v162
	ds_read_b128 v[184:187], v167
	ds_read_b128 v[188:191], v167 offset:1024
	ds_read_b128 v[192:195], v167 offset:2048
	ds_read_b128 v[196:199], v167 offset:3072
	v_lshl_add_u64 v[232:233], v[232:233], 0, v[136:137]
	s_mov_b32 m0, s23
	v_lshl_add_u64 v[246:247], v[232:233], 0, v[128:129]
	ds_read_b128 v[200:203], v166 offset:32768
	ds_read_b128 v[204:207], v166 offset:33792
	ds_read_b128 v[208:211], v166 offset:34816
	ds_read_b128 v[212:215], v166 offset:35840
	ds_read_b128 v[216:219], v166 offset:36864
	ds_read_b128 v[220:223], v166 offset:37888
	ds_read_b128 v[224:227], v166 offset:38912
	ds_read_b128 v[228:231], v166 offset:39936
	global_load_lds_dwordx4 v[246:247], off
	v_lshl_add_u64 v[232:233], v[232:233], 0, v[132:133]
	s_mov_b32 m0, s24
	s_nop 0
	global_load_lds_dwordx4 v[232:233], off
	s_waitcnt vmcnt(8)
	s_waitcnt lgkmcnt(0)
	s_barrier
	s_setprio 1
	v_mfma_f32_16x16x32_bf16 v[124:127], v[168:171], v[200:203], v[124:127]
	v_mfma_f32_16x16x32_bf16 v[120:123], v[176:179], v[200:203], v[120:123]
	v_mfma_f32_16x16x32_bf16 v[108:111], v[168:171], v[208:211], v[108:111]
	v_mfma_f32_16x16x32_bf16 v[104:107], v[176:179], v[208:211], v[104:107]
	v_mfma_f32_16x16x32_bf16 v[92:95], v[168:171], v[216:219], v[92:95]
	v_mfma_f32_16x16x32_bf16 v[88:91], v[176:179], v[216:219], v[88:91]
	v_mfma_f32_16x16x32_bf16 v[76:79], v[168:171], v[224:227], v[76:79]
	v_mfma_f32_16x16x32_bf16 v[72:75], v[176:179], v[224:227], v[72:75]
	v_mfma_f32_16x16x32_bf16 v[124:127], v[172:175], v[204:207], v[124:127]
	v_mfma_f32_16x16x32_bf16 v[120:123], v[180:183], v[204:207], v[120:123]
	v_mfma_f32_16x16x32_bf16 v[108:111], v[172:175], v[212:215], v[108:111]
	v_mfma_f32_16x16x32_bf16 v[104:107], v[180:183], v[212:215], v[104:107]
	v_mfma_f32_16x16x32_bf16 v[92:95], v[172:175], v[220:223], v[92:95]
	v_mfma_f32_16x16x32_bf16 v[88:91], v[180:183], v[220:223], v[88:91]
	v_mfma_f32_16x16x32_bf16 v[76:79], v[172:175], v[228:231], v[76:79]
	v_mfma_f32_16x16x32_bf16 v[72:75], v[180:183], v[228:231], v[72:75]
	v_mfma_f32_16x16x32_bf16 v[116:119], v[184:187], v[200:203], v[116:119]
	v_mfma_f32_16x16x32_bf16 v[112:115], v[192:195], v[200:203], v[112:115]
	v_mfma_f32_16x16x32_bf16 v[100:103], v[184:187], v[208:211], v[100:103]
	v_mfma_f32_16x16x32_bf16 v[96:99], v[192:195], v[208:211], v[96:99]
	v_mfma_f32_16x16x32_bf16 v[84:87], v[184:187], v[216:219], v[84:87]
	v_mfma_f32_16x16x32_bf16 v[80:83], v[192:195], v[216:219], v[80:83]
	v_mfma_f32_16x16x32_bf16 v[68:71], v[184:187], v[224:227], v[68:71]
	v_mfma_f32_16x16x32_bf16 v[64:67], v[192:195], v[224:227], v[64:67]
	v_mfma_f32_16x16x32_bf16 v[116:119], v[188:191], v[204:207], v[116:119]
	v_mfma_f32_16x16x32_bf16 v[112:115], v[196:199], v[204:207], v[112:115]
	v_mfma_f32_16x16x32_bf16 v[100:103], v[188:191], v[212:215], v[100:103]
	v_mfma_f32_16x16x32_bf16 v[96:99], v[196:199], v[212:215], v[96:99]
	v_mfma_f32_16x16x32_bf16 v[84:87], v[188:191], v[220:223], v[84:87]
	v_mfma_f32_16x16x32_bf16 v[80:83], v[196:199], v[220:223], v[80:83]
	v_mfma_f32_16x16x32_bf16 v[68:71], v[188:191], v[228:231], v[68:71]
	v_mfma_f32_16x16x32_bf16 v[64:67], v[196:199], v[228:231], v[64:67]
	s_setprio 0
	s_barrier
; #define PG8_STAGE(bufoff, gbase, voff) do { _Pragma("unroll") for (int _i = 0; _i < 2; ++_i) \
;         __builtin_amdgcn_global_load_lds((const unsigned*)((const char*)(gbase) + (voff)[_i]), (LAS unsigned*)(lds + (bufoff) + ldsw + _i * 8192), 16, 0, 0); } while (0)
; #define PG8_LDA(dst, b, h) do { _Pragma("unroll") for (int m = 0; m < 4; ++m) _Pragma("unroll") for (int k = 0; k < 2; ++k) dst[m][k] = *(const LAS bf16x8*)(lds + PG8_SA(b, h) + aoff + m * 2048 + k * 1024); } while (0)
; #define PG8_WAIT_V(n) asm volatile("s_waitcnt vmcnt(" #n ")" ::: "memory")
; #define PG8_WAIT_L(n) asm volatile("s_waitcnt lgkmcnt(" #n ")" ::: "memory")
; #define PG8_BAR __builtin_amdgcn_s_barrier()
; #define PG8_SCHED __builtin_amdgcn_sched_barrier(0)
;     ...
;             PG8_LDA(At, 1, 1); PG8_STAGE(PG8_SB(1, 0), b3, voffB); PG8_STAGE(PG8_SB(1, 1), b3 + hstepB, voffB); PG8_STAGE(PG8_SA(1, 0), a3, voffA);
;             PG8_WAIT_V(8); PG8_WAIT_L(0); PG8_BAR; PG8_MMA(1, 0, At, B0); PG8_MMA(1, 1, At, B1); PG8_BAR; PG8_SCHED;
	s_add_i32 s21, s21, s2
	v_lshl_add_u64 v[232:233], v[236:237], 0, s[12:13]
	s_mov_b32 m0, s21
	ds_read_b128 v[200:203], v166 offset:49152
	ds_read_b128 v[204:207], v166 offset:50176
	ds_read_b128 v[208:211], v166 offset:51200
	ds_read_b128 v[212:215], v166 offset:52224
	ds_read_b128 v[216:219], v166 offset:53248
	ds_read_b128 v[220:223], v166 offset:54272
	ds_read_b128 v[224:227], v166 offset:55296
	ds_read_b128 v[228:231], v166 offset:56320
	global_load_lds_dwordx4 v[232:233], off
	v_lshl_add_u64 v[232:233], v[238:239], 0, s[12:13]
	s_add_i32 m0, s21, 0x2000
	s_add_i32 s21, s40, s2
	global_load_lds_dwordx4 v[232:233], off
	v_lshl_add_u64 v[232:233], v[240:241], 0, s[12:13]
	s_mov_b32 m0, s21
	s_nop 0
	global_load_lds_dwordx4 v[232:233], off
	v_lshl_add_u64 v[232:233], v[234:235], 0, s[12:13]
	s_add_i32 m0, s21, 0x2000
	s_nop 0
	global_load_lds_dwordx4 v[232:233], off
	v_lshl_add_u64 v[232:233], v[242:243], 0, s[12:13]
	s_mov_b32 m0, s30
	s_nop 0
	global_load_lds_dwordx4 v[232:233], off
	v_lshl_add_u64 v[232:233], v[244:245], 0, s[12:13]
	s_mov_b32 m0, s31
	s_nop 0
	global_load_lds_dwordx4 v[232:233], off
	s_waitcnt vmcnt(8)
	s_waitcnt lgkmcnt(0)
	s_barrier
	s_setprio 1
	v_mfma_f32_16x16x32_bf16 v[60:63], v[168:171], v[200:203], v[60:63]
	v_mfma_f32_16x16x32_bf16 v[56:59], v[176:179], v[200:203], v[56:59]
	v_mfma_f32_16x16x32_bf16 v[44:47], v[168:171], v[208:211], v[44:47]
	v_mfma_f32_16x16x32_bf16 v[40:43], v[176:179], v[208:211], v[40:43]
	v_mfma_f32_16x16x32_bf16 v[28:31], v[168:171], v[216:219], v[28:31]
	v_mfma_f32_16x16x32_bf16 v[24:27], v[176:179], v[216:219], v[24:27]
	v_mfma_f32_16x16x32_bf16 v[12:15], v[168:171], v[224:227], v[12:15]
	v_mfma_f32_16x16x32_bf16 v[8:11], v[176:179], v[224:227], v[8:11]
	v_mfma_f32_16x16x32_bf16 v[60:63], v[172:175], v[204:207], v[60:63]
	v_mfma_f32_16x16x32_bf16 v[56:59], v[180:183], v[204:207], v[56:59]
	v_mfma_f32_16x16x32_bf16 v[44:47], v[172:175], v[212:215], v[44:47]
	v_mfma_f32_16x16x32_bf16 v[40:43], v[180:183], v[212:215], v[40:43]
	v_mfma_f32_16x16x32_bf16 v[28:31], v[172:175], v[220:223], v[28:31]
	v_mfma_f32_16x16x32_bf16 v[24:27], v[180:183], v[220:223], v[24:27]
	v_mfma_f32_16x16x32_bf16 v[12:15], v[172:175], v[228:231], v[12:15]
	v_mfma_f32_16x16x32_bf16 v[8:11], v[180:183], v[228:231], v[8:11]
	v_mfma_f32_16x16x32_bf16 v[52:55], v[184:187], v[200:203], v[52:55]
	v_mfma_f32_16x16x32_bf16 v[48:51], v[192:195], v[200:203], v[48:51]
	v_mfma_f32_16x16x32_bf16 v[36:39], v[184:187], v[208:211], v[36:39]
	v_mfma_f32_16x16x32_bf16 v[32:35], v[192:195], v[208:211], v[32:35]
	v_mfma_f32_16x16x32_bf16 v[20:23], v[184:187], v[216:219], v[20:23]
	v_mfma_f32_16x16x32_bf16 v[16:19], v[192:195], v[216:219], v[16:19]
	v_mfma_f32_16x16x32_bf16 v[4:7], v[184:187], v[224:227], v[4:7]
	v_mfma_f32_16x16x32_bf16 v[0:3], v[192:195], v[224:227], v[0:3]
	v_mfma_f32_16x16x32_bf16 v[52:55], v[188:191], v[204:207], v[52:55]
	v_mfma_f32_16x16x32_bf16 v[48:51], v[196:199], v[204:207], v[48:51]
	v_mfma_f32_16x16x32_bf16 v[36:39], v[188:191], v[212:215], v[36:39]
	v_mfma_f32_16x16x32_bf16 v[32:35], v[196:199], v[212:215], v[32:35]
	v_mfma_f32_16x16x32_bf16 v[20:23], v[188:191], v[220:223], v[20:23]
	v_mfma_f32_16x16x32_bf16 v[16:19], v[196:199], v[220:223], v[16:19]
	v_mfma_f32_16x16x32_bf16 v[4:7], v[188:191], v[228:231], v[4:7]
	v_mfma_f32_16x16x32_bf16 v[0:3], v[196:199], v[228:231], v[0:3]
	s_setprio 0
	s_barrier
	s_add_i32 s20, s20, 2
	s_add_u32 s18, s18, 0x100
	s_addc_u32 s19, s19, 0
	s_cmpk_gt_u32 s20, 0xfd
	s_cbranch_scc0 .LBB0_1148
	s_and_b64 vcc, exec, s[14:15]
	s_cbranch_vccz .LBB0_1151
	s_barrier
